# v2 + removed redundant mid-segment s_setprio 0/1 pairs between the two MFMA blocks of each GEMM compute segment
# baseline (speedup 1.0000x reference)
.LBB0_102:
	ds_read_b128 v[104:107], v165
	ds_read_b128 v[108:111], v165 offset:1024
	ds_read_b128 v[136:139], v165 offset:2048
	ds_read_b128 v[158:161], v165 offset:3072
	ds_read_b128 v[168:171], v166
	ds_read_b128 v[172:175], v166 offset:1024
	ds_read_b128 v[176:179], v166 offset:2048
	ds_read_b128 v[180:183], v166 offset:3072
	s_add_u32 s2, s36, 0xfff80080
	s_addc_u32 s3, s37, -1
	s_cmp_eq_u32 s56, 28
	s_cselect_b32 s39, s7, s3
	s_cselect_b32 s38, s27, s2
	s_cselect_b32 s3, s23, s55
	s_cselect_b32 s2, s35, s54
	v_lshl_add_u64 v[218:219], s[36:37], 0, v[150:151]
	s_add_i32 m0, s25, 0xc000
	ds_read_b128 v[186:189], v167
	ds_read_b128 v[190:193], v167 offset:1024
	ds_read_b128 v[194:197], v167 offset:2048
	ds_read_b128 v[198:201], v167 offset:3072
	ds_read_b128 v[202:205], v167 offset:4096
	ds_read_b128 v[206:209], v167 offset:5120
	ds_read_b128 v[210:213], v167 offset:6144
	ds_read_b128 v[214:217], v167 offset:7168
	global_load_lds_dwordx4 v[218:219], off
	v_lshl_add_u64 v[218:219], s[36:37], 0, v[152:153]
	s_add_i32 m0, s25, 0xe000
	s_nop 0
	global_load_lds_dwordx4 v[218:219], off
	s_waitcnt vmcnt(8)
	s_waitcnt lgkmcnt(0)
	s_barrier
	s_setprio 1
	s_waitcnt lgkmcnt(0)
	v_mfma_f32_16x16x32_bf16 v[132:135], v[104:107], v[186:189], v[132:135]
	v_mfma_f32_16x16x32_bf16 v[128:131], v[136:139], v[186:189], v[128:131]
	v_mfma_f32_16x16x32_bf16 v[124:127], v[104:107], v[194:197], v[124:127]
	v_mfma_f32_16x16x32_bf16 v[120:123], v[136:139], v[194:197], v[120:123]
	v_mfma_f32_16x16x32_bf16 v[116:119], v[104:107], v[202:205], v[116:119]
	v_mfma_f32_16x16x32_bf16 v[112:115], v[136:139], v[202:205], v[112:115]
	v_mfma_f32_16x16x32_bf16 v[100:103], v[104:107], v[210:213], v[100:103]
	v_mfma_f32_16x16x32_bf16 v[96:99], v[136:139], v[210:213], v[96:99]
	v_mfma_f32_16x16x32_bf16 v[132:135], v[108:111], v[190:193], v[132:135]
	v_mfma_f32_16x16x32_bf16 v[128:131], v[158:161], v[190:193], v[128:131]
	v_mfma_f32_16x16x32_bf16 v[124:127], v[108:111], v[198:201], v[124:127]
	v_mfma_f32_16x16x32_bf16 v[120:123], v[158:161], v[198:201], v[120:123]
	v_mfma_f32_16x16x32_bf16 v[116:119], v[108:111], v[206:209], v[116:119]
	v_mfma_f32_16x16x32_bf16 v[112:115], v[158:161], v[206:209], v[112:115]
	v_mfma_f32_16x16x32_bf16 v[100:103], v[108:111], v[214:217], v[100:103]
	v_mfma_f32_16x16x32_bf16 v[96:99], v[158:161], v[214:217], v[96:99]
	v_mfma_f32_16x16x32_bf16 v[60:63], v[168:171], v[186:189], v[60:63]
	v_mfma_f32_16x16x32_bf16 v[56:59], v[176:179], v[186:189], v[56:59]
	v_mfma_f32_16x16x32_bf16 v[52:55], v[168:171], v[194:197], v[52:55]
	v_mfma_f32_16x16x32_bf16 v[48:51], v[176:179], v[194:197], v[48:51]
	v_mfma_f32_16x16x32_bf16 v[44:47], v[168:171], v[202:205], v[44:47]
	v_mfma_f32_16x16x32_bf16 v[40:43], v[176:179], v[202:205], v[40:43]
	v_mfma_f32_16x16x32_bf16 v[36:39], v[168:171], v[210:213], v[36:39]
	v_mfma_f32_16x16x32_bf16 v[32:35], v[176:179], v[210:213], v[32:35]
	v_mfma_f32_16x16x32_bf16 v[60:63], v[172:175], v[190:193], v[60:63]
	v_mfma_f32_16x16x32_bf16 v[56:59], v[180:183], v[190:193], v[56:59]
	v_mfma_f32_16x16x32_bf16 v[52:55], v[172:175], v[198:201], v[52:55]
	v_mfma_f32_16x16x32_bf16 v[48:51], v[180:183], v[198:201], v[48:51]
	v_mfma_f32_16x16x32_bf16 v[44:47], v[172:175], v[206:209], v[44:47]
	v_mfma_f32_16x16x32_bf16 v[40:43], v[180:183], v[206:209], v[40:43]
	v_mfma_f32_16x16x32_bf16 v[36:39], v[172:175], v[214:217], v[36:39]
	v_mfma_f32_16x16x32_bf16 v[32:35], v[180:183], v[214:217], v[32:35]
	s_setprio 0
	s_barrier
	s_add_i32 s57, s51, s19
	v_lshl_add_u64 v[218:219], s[2:3], 0, v[142:143]
	s_mov_b32 m0, s57
	ds_read_b128 v[186:189], v167 offset:16384
	ds_read_b128 v[190:193], v167 offset:17408
	ds_read_b128 v[194:197], v167 offset:18432
	ds_read_b128 v[198:201], v167 offset:19456
	ds_read_b128 v[202:205], v167 offset:20480
	ds_read_b128 v[206:209], v167 offset:21504
	ds_read_b128 v[210:213], v167 offset:22528
	ds_read_b128 v[214:217], v167 offset:23552
	global_load_lds_dwordx4 v[218:219], off
	s_add_i32 m0, s57, 0x2000
	s_add_u32 s62, s2, 0x80000
	v_lshl_add_u64 v[220:221], s[2:3], 0, v[146:147]
	s_addc_u32 s63, s3, 0
	s_add_i32 s57, s52, s19
	global_load_lds_dwordx4 v[220:221], off
	v_lshl_add_u64 v[222:223], s[62:63], 0, v[142:143]
	s_mov_b32 m0, s57
	v_lshl_add_u64 v[224:225], s[38:39], 0, v[144:145]
	global_load_lds_dwordx4 v[222:223], off
	v_lshl_add_u64 v[222:223], s[62:63], 0, v[146:147]
	s_add_i32 m0, s57, 0x2000
	s_nop 0
	global_load_lds_dwordx4 v[222:223], off
	v_lshl_add_u64 v[222:223], s[38:39], 0, v[140:141]
	s_mov_b32 m0, s25
	s_nop 0
	global_load_lds_dwordx4 v[222:223], off
	s_mov_b32 m0, s40
	s_nop 0
	global_load_lds_dwordx4 v[224:225], off
	s_waitcnt vmcnt(8)
	s_waitcnt lgkmcnt(0)
	s_barrier
	s_setprio 1
	s_waitcnt lgkmcnt(0)
	v_mfma_f32_16x16x32_bf16 v[92:95], v[104:107], v[186:189], v[92:95]
	v_mfma_f32_16x16x32_bf16 v[88:91], v[136:139], v[186:189], v[88:91]
	v_mfma_f32_16x16x32_bf16 v[84:87], v[104:107], v[194:197], v[84:87]
	v_mfma_f32_16x16x32_bf16 v[80:83], v[136:139], v[194:197], v[80:83]
	v_mfma_f32_16x16x32_bf16 v[76:79], v[104:107], v[202:205], v[76:79]
	v_mfma_f32_16x16x32_bf16 v[72:75], v[136:139], v[202:205], v[72:75]
	v_mfma_f32_16x16x32_bf16 v[68:71], v[104:107], v[210:213], v[68:71]
	v_mfma_f32_16x16x32_bf16 v[64:67], v[136:139], v[210:213], v[64:67]
	v_mfma_f32_16x16x32_bf16 v[92:95], v[108:111], v[190:193], v[92:95]
	v_mfma_f32_16x16x32_bf16 v[88:91], v[158:161], v[190:193], v[88:91]
	v_mfma_f32_16x16x32_bf16 v[84:87], v[108:111], v[198:201], v[84:87]
	v_mfma_f32_16x16x32_bf16 v[80:83], v[158:161], v[198:201], v[80:83]
	v_mfma_f32_16x16x32_bf16 v[76:79], v[108:111], v[206:209], v[76:79]
	v_mfma_f32_16x16x32_bf16 v[72:75], v[158:161], v[206:209], v[72:75]
	v_mfma_f32_16x16x32_bf16 v[68:71], v[108:111], v[214:217], v[68:71]
	v_mfma_f32_16x16x32_bf16 v[64:67], v[158:161], v[214:217], v[64:67]
	v_mfma_f32_16x16x32_bf16 v[28:31], v[168:171], v[186:189], v[28:31]
	v_mfma_f32_16x16x32_bf16 v[24:27], v[176:179], v[186:189], v[24:27]
	v_mfma_f32_16x16x32_bf16 v[20:23], v[168:171], v[194:197], v[20:23]
	v_mfma_f32_16x16x32_bf16 v[16:19], v[176:179], v[194:197], v[16:19]
	v_mfma_f32_16x16x32_bf16 v[12:15], v[168:171], v[202:205], v[12:15]
	v_mfma_f32_16x16x32_bf16 v[8:11], v[176:179], v[202:205], v[8:11]
	v_mfma_f32_16x16x32_bf16 v[4:7], v[168:171], v[210:213], v[4:7]
	v_mfma_f32_16x16x32_bf16 v[0:3], v[176:179], v[210:213], v[0:3]
	v_mfma_f32_16x16x32_bf16 v[28:31], v[172:175], v[190:193], v[28:31]
	v_mfma_f32_16x16x32_bf16 v[24:27], v[180:183], v[190:193], v[24:27]
	v_mfma_f32_16x16x32_bf16 v[20:23], v[172:175], v[198:201], v[20:23]
	v_mfma_f32_16x16x32_bf16 v[16:19], v[180:183], v[198:201], v[16:19]
	v_mfma_f32_16x16x32_bf16 v[12:15], v[172:175], v[206:209], v[12:15]
	v_mfma_f32_16x16x32_bf16 v[8:11], v[180:183], v[206:209], v[8:11]
	v_mfma_f32_16x16x32_bf16 v[4:7], v[172:175], v[214:217], v[4:7]
	v_mfma_f32_16x16x32_bf16 v[0:3], v[180:183], v[214:217], v[0:3]
	s_setprio 0
	s_barrier
	s_add_i32 s57, 0, 0x18000
	v_add_u32_e32 v148, s57, v164
	s_add_i32 s61, 0, 0x1c000
	ds_read_b128 v[104:107], v148
	ds_read_b128 v[108:111], v148 offset:1024
	ds_read_b128 v[136:139], v148 offset:2048
	ds_read_b128 v[158:161], v148 offset:3072
	v_add_u32_e32 v148, s61, v164
	ds_read_b128 v[168:171], v148
	ds_read_b128 v[172:175], v148 offset:1024
	ds_read_b128 v[176:179], v148 offset:2048
	ds_read_b128 v[180:183], v148 offset:3072
	s_add_u32 s38, s38, 0x80000
	s_addc_u32 s39, s39, 0
	s_mov_b32 m0, s41
	v_lshl_add_u64 v[226:227], s[38:39], 0, v[140:141]
	ds_read_b128 v[186:189], v167 offset:32768
	ds_read_b128 v[190:193], v167 offset:33792
	ds_read_b128 v[194:197], v167 offset:34816
	ds_read_b128 v[198:201], v167 offset:35840
	ds_read_b128 v[202:205], v167 offset:36864
	ds_read_b128 v[206:209], v167 offset:37888
	ds_read_b128 v[210:213], v167 offset:38912
	ds_read_b128 v[214:217], v167 offset:39936
	global_load_lds_dwordx4 v[226:227], off
	v_lshl_add_u64 v[226:227], s[38:39], 0, v[144:145]
	s_mov_b32 m0, s42
	s_nop 0
	global_load_lds_dwordx4 v[226:227], off
	s_waitcnt vmcnt(8)
	s_waitcnt lgkmcnt(0)
	s_barrier
	s_setprio 1
	s_waitcnt lgkmcnt(0)
	v_mfma_f32_16x16x32_bf16 v[132:135], v[104:107], v[186:189], v[132:135]
	v_mfma_f32_16x16x32_bf16 v[128:131], v[136:139], v[186:189], v[128:131]
	v_mfma_f32_16x16x32_bf16 v[124:127], v[104:107], v[194:197], v[124:127]
	v_mfma_f32_16x16x32_bf16 v[120:123], v[136:139], v[194:197], v[120:123]
	v_mfma_f32_16x16x32_bf16 v[116:119], v[104:107], v[202:205], v[116:119]
	v_mfma_f32_16x16x32_bf16 v[112:115], v[136:139], v[202:205], v[112:115]
	v_mfma_f32_16x16x32_bf16 v[100:103], v[104:107], v[210:213], v[100:103]
	v_mfma_f32_16x16x32_bf16 v[96:99], v[136:139], v[210:213], v[96:99]
	v_mfma_f32_16x16x32_bf16 v[132:135], v[108:111], v[190:193], v[132:135]
	v_mfma_f32_16x16x32_bf16 v[128:131], v[158:161], v[190:193], v[128:131]
	v_mfma_f32_16x16x32_bf16 v[124:127], v[108:111], v[198:201], v[124:127]
	v_mfma_f32_16x16x32_bf16 v[120:123], v[158:161], v[198:201], v[120:123]
	v_mfma_f32_16x16x32_bf16 v[116:119], v[108:111], v[206:209], v[116:119]
	v_mfma_f32_16x16x32_bf16 v[112:115], v[158:161], v[206:209], v[112:115]
	v_mfma_f32_16x16x32_bf16 v[100:103], v[108:111], v[214:217], v[100:103]
	v_mfma_f32_16x16x32_bf16 v[96:99], v[158:161], v[214:217], v[96:99]
	v_mfma_f32_16x16x32_bf16 v[60:63], v[168:171], v[186:189], v[60:63]
	v_mfma_f32_16x16x32_bf16 v[56:59], v[176:179], v[186:189], v[56:59]
	v_mfma_f32_16x16x32_bf16 v[52:55], v[168:171], v[194:197], v[52:55]
	v_mfma_f32_16x16x32_bf16 v[48:51], v[176:179], v[194:197], v[48:51]
	v_mfma_f32_16x16x32_bf16 v[44:47], v[168:171], v[202:205], v[44:47]
	v_mfma_f32_16x16x32_bf16 v[40:43], v[176:179], v[202:205], v[40:43]
	v_mfma_f32_16x16x32_bf16 v[36:39], v[168:171], v[210:213], v[36:39]
	v_mfma_f32_16x16x32_bf16 v[32:35], v[176:179], v[210:213], v[32:35]
	v_mfma_f32_16x16x32_bf16 v[60:63], v[172:175], v[190:193], v[60:63]
	v_mfma_f32_16x16x32_bf16 v[56:59], v[180:183], v[190:193], v[56:59]
	v_mfma_f32_16x16x32_bf16 v[52:55], v[172:175], v[198:201], v[52:55]
	v_mfma_f32_16x16x32_bf16 v[48:51], v[180:183], v[198:201], v[48:51]
	v_mfma_f32_16x16x32_bf16 v[44:47], v[172:175], v[206:209], v[44:47]
	v_mfma_f32_16x16x32_bf16 v[40:43], v[180:183], v[206:209], v[40:43]
	v_mfma_f32_16x16x32_bf16 v[36:39], v[172:175], v[214:217], v[36:39]
	v_mfma_f32_16x16x32_bf16 v[32:35], v[180:183], v[214:217], v[32:35]
	s_setprio 0
	s_barrier
	s_add_i32 s38, s57, s19
	v_lshl_add_u64 v[218:219], v[218:219], 0, s[12:13]
	s_mov_b32 m0, s38
	ds_read_b128 v[186:189], v167 offset:49152
	ds_read_b128 v[190:193], v167 offset:50176
	ds_read_b128 v[194:197], v167 offset:51200
	ds_read_b128 v[198:201], v167 offset:52224
	ds_read_b128 v[202:205], v167 offset:53248
	ds_read_b128 v[206:209], v167 offset:54272
	ds_read_b128 v[210:213], v167 offset:55296
	ds_read_b128 v[214:217], v167 offset:56320
	global_load_lds_dwordx4 v[218:219], off
	s_add_i32 m0, s38, 0x2000
	s_add_u32 s2, s2, 0x80080
	v_lshl_add_u64 v[218:219], v[220:221], 0, s[12:13]
	s_addc_u32 s3, s3, 0
	s_add_i32 s38, s61, s19
	global_load_lds_dwordx4 v[218:219], off
	v_lshl_add_u64 v[218:219], s[2:3], 0, v[142:143]
	s_mov_b32 m0, s38
	s_nop 0
	global_load_lds_dwordx4 v[218:219], off
	v_lshl_add_u64 v[218:219], s[2:3], 0, v[146:147]
	s_add_i32 m0, s38, 0x2000
	s_nop 0
	global_load_lds_dwordx4 v[218:219], off
	v_lshl_add_u64 v[218:219], v[222:223], 0, s[12:13]
	s_mov_b32 m0, s46
	s_nop 0
	global_load_lds_dwordx4 v[218:219], off
	v_lshl_add_u64 v[218:219], v[224:225], 0, s[12:13]
	s_mov_b32 m0, s47
	s_nop 0
	global_load_lds_dwordx4 v[218:219], off
	s_waitcnt vmcnt(8)
	s_waitcnt lgkmcnt(0)
	s_barrier
	s_setprio 1
	s_waitcnt lgkmcnt(0)
	v_mfma_f32_16x16x32_bf16 v[92:95], v[104:107], v[186:189], v[92:95]
	v_mfma_f32_16x16x32_bf16 v[88:91], v[136:139], v[186:189], v[88:91]
	v_mfma_f32_16x16x32_bf16 v[84:87], v[104:107], v[194:197], v[84:87]
	v_mfma_f32_16x16x32_bf16 v[80:83], v[136:139], v[194:197], v[80:83]
	v_mfma_f32_16x16x32_bf16 v[76:79], v[104:107], v[202:205], v[76:79]
	v_mfma_f32_16x16x32_bf16 v[72:75], v[136:139], v[202:205], v[72:75]
	v_mfma_f32_16x16x32_bf16 v[68:71], v[104:107], v[210:213], v[68:71]
	v_mfma_f32_16x16x32_bf16 v[64:67], v[136:139], v[210:213], v[64:67]
	v_mfma_f32_16x16x32_bf16 v[92:95], v[108:111], v[190:193], v[92:95]
	v_mfma_f32_16x16x32_bf16 v[88:91], v[158:161], v[190:193], v[88:91]
	v_mfma_f32_16x16x32_bf16 v[84:87], v[108:111], v[198:201], v[84:87]
	v_mfma_f32_16x16x32_bf16 v[80:83], v[158:161], v[198:201], v[80:83]
	v_mfma_f32_16x16x32_bf16 v[76:79], v[108:111], v[206:209], v[76:79]
	v_mfma_f32_16x16x32_bf16 v[72:75], v[158:161], v[206:209], v[72:75]
	v_mfma_f32_16x16x32_bf16 v[68:71], v[108:111], v[214:217], v[68:71]
	v_mfma_f32_16x16x32_bf16 v[64:67], v[158:161], v[214:217], v[64:67]
	v_mfma_f32_16x16x32_bf16 v[28:31], v[168:171], v[186:189], v[28:31]
	v_mfma_f32_16x16x32_bf16 v[24:27], v[176:179], v[186:189], v[24:27]
	v_mfma_f32_16x16x32_bf16 v[20:23], v[168:171], v[194:197], v[20:23]
	v_mfma_f32_16x16x32_bf16 v[16:19], v[176:179], v[194:197], v[16:19]
	v_mfma_f32_16x16x32_bf16 v[12:15], v[168:171], v[202:205], v[12:15]
	v_mfma_f32_16x16x32_bf16 v[8:11], v[176:179], v[202:205], v[8:11]
	v_mfma_f32_16x16x32_bf16 v[4:7], v[168:171], v[210:213], v[4:7]
	v_mfma_f32_16x16x32_bf16 v[0:3], v[176:179], v[210:213], v[0:3]
	v_mfma_f32_16x16x32_bf16 v[28:31], v[172:175], v[190:193], v[28:31]
	v_mfma_f32_16x16x32_bf16 v[24:27], v[180:183], v[190:193], v[24:27]
	v_mfma_f32_16x16x32_bf16 v[20:23], v[172:175], v[198:201], v[20:23]
	v_mfma_f32_16x16x32_bf16 v[16:19], v[180:183], v[198:201], v[16:19]
	v_mfma_f32_16x16x32_bf16 v[12:15], v[172:175], v[206:209], v[12:15]
	v_mfma_f32_16x16x32_bf16 v[8:11], v[180:183], v[206:209], v[8:11]
	v_mfma_f32_16x16x32_bf16 v[4:7], v[172:175], v[214:217], v[4:7]
	v_mfma_f32_16x16x32_bf16 v[0:3], v[180:183], v[214:217], v[0:3]
	s_setprio 0
	s_barrier
	s_add_i32 s56, s56, 2
	s_add_u32 s36, s36, 0x100
	s_addc_u32 s37, s37, 0
	s_add_u32 s54, s54, 0x100
	s_addc_u32 s55, s55, 0
	s_cmp_gt_u32 s56, 29
	s_cbranch_scc0 .LBB0_102
	s_and_b64 vcc, exec, s[20:21]
	s_cbranch_vccz .LBB0_105
	s_barrier

.LBB0_315:
	s_add_u32 s50, s40, s44
	s_addc_u32 s51, s41, s45
	s_add_u32 s48, s50, 0x100
	s_addc_u32 s49, s51, 0
	s_and_b64 s[46:47], s[42:43], exec
	s_cselect_b32 s47, s31, s49
	s_cselect_b32 s46, s30, s48
	s_add_u32 s44, s38, s44
	s_addc_u32 s45, s39, s45
	s_add_u32 s44, s44, 0x100
	s_addc_u32 s45, s45, 0
	s_and_b64 s[42:43], s[42:43], exec
	s_cselect_b32 s49, s27, s45
	s_cselect_b32 s48, s29, s44
	s_add_u32 s52, s50, 0x80080
	ds_read_b128 v[104:107], v193
	ds_read_b128 v[108:111], v193 offset:1024
	ds_read_b128 v[112:115], v193 offset:2048
	ds_read_b128 v[154:157], v193 offset:3072
	ds_read_b128 v[158:161], v194
	ds_read_b128 v[162:165], v194 offset:1024
	ds_read_b128 v[166:169], v194 offset:2048
	ds_read_b128 v[170:173], v194 offset:3072
	s_addc_u32 s53, s51, 0
	s_add_i32 s79, s64, s3
	s_add_i32 m0, s23, 0xc000
	s_add_i32 s80, s23, 0xe000
	s_add_i32 s76, s79, 0x2000
	s_add_u32 s50, s48, 0x10000
	s_addc_u32 s51, s49, 0
	s_add_i32 s78, s65, s3
	s_add_i32 s77, s78, 0x2000
	s_add_i32 s73, 0, 0x18000
	s_add_i32 s72, 0, 0x1c000
	s_add_u32 s44, s46, 0x80000
	s_addc_u32 s45, s47, 0
	s_add_i32 s71, s73, s3
	s_add_i32 s69, s71, 0x2000
	s_add_u32 s42, s48, 0x10080
	s_addc_u32 s43, s49, 0
	s_add_i32 s70, s72, s3
	s_add_i32 s68, s70, 0x2000
	v_lshl_add_u64 v[182:183], s[52:53], 0, v[140:141]
	ds_read_b128 v[174:177], v195
	ds_read_b128 v[178:181], v195 offset:1024
	ds_read_b128 v[186:189], v195 offset:2048
	ds_read_b128 v[196:199], v195 offset:3072
	ds_read_b128 v[200:203], v195 offset:4096
	ds_read_b128 v[204:207], v195 offset:5120
	ds_read_b128 v[208:211], v195 offset:6144
	ds_read_b128 v[212:215], v195 offset:7168
	global_load_lds_dwordx4 v[182:183], off
	v_lshl_add_u64 v[182:183], s[52:53], 0, v[144:145]
	s_mov_b32 m0, s80
	s_nop 0
	global_load_lds_dwordx4 v[182:183], off
	s_waitcnt vmcnt(8)
	s_waitcnt lgkmcnt(0)
	s_barrier
	s_setprio 1
	s_waitcnt lgkmcnt(0)
	v_mfma_f32_16x16x32_bf16 v[136:139], v[104:107], v[174:177], v[136:139]
	v_mfma_f32_16x16x32_bf16 v[60:63], v[112:115], v[174:177], v[60:63]
	v_mfma_f32_16x16x32_bf16 v[128:131], v[104:107], v[186:189], v[128:131]
	v_mfma_f32_16x16x32_bf16 v[52:55], v[112:115], v[186:189], v[52:55]
	v_mfma_f32_16x16x32_bf16 v[120:123], v[104:107], v[200:203], v[120:123]
	v_mfma_f32_16x16x32_bf16 v[44:47], v[112:115], v[200:203], v[44:47]
	v_mfma_f32_16x16x32_bf16 v[100:103], v[104:107], v[208:211], v[100:103]
	v_mfma_f32_16x16x32_bf16 v[36:39], v[112:115], v[208:211], v[36:39]
	v_mfma_f32_16x16x32_bf16 v[136:139], v[108:111], v[178:181], v[136:139]
	v_mfma_f32_16x16x32_bf16 v[60:63], v[154:157], v[178:181], v[60:63]
	v_mfma_f32_16x16x32_bf16 v[128:131], v[108:111], v[196:199], v[128:131]
	v_mfma_f32_16x16x32_bf16 v[52:55], v[154:157], v[196:199], v[52:55]
	v_mfma_f32_16x16x32_bf16 v[120:123], v[108:111], v[204:207], v[120:123]
	v_mfma_f32_16x16x32_bf16 v[44:47], v[154:157], v[204:207], v[44:47]
	v_mfma_f32_16x16x32_bf16 v[100:103], v[108:111], v[212:215], v[100:103]
	v_mfma_f32_16x16x32_bf16 v[36:39], v[154:157], v[212:215], v[36:39]
	v_mfma_f32_16x16x32_bf16 v[132:135], v[158:161], v[174:177], v[132:135]
	v_mfma_f32_16x16x32_bf16 v[56:59], v[166:169], v[174:177], v[56:59]
	v_mfma_f32_16x16x32_bf16 v[124:127], v[158:161], v[186:189], v[124:127]
	v_mfma_f32_16x16x32_bf16 v[48:51], v[166:169], v[186:189], v[48:51]
	v_mfma_f32_16x16x32_bf16 v[116:119], v[158:161], v[200:203], v[116:119]
	v_mfma_f32_16x16x32_bf16 v[40:43], v[166:169], v[200:203], v[40:43]
	v_mfma_f32_16x16x32_bf16 v[96:99], v[158:161], v[208:211], v[96:99]
	v_mfma_f32_16x16x32_bf16 v[32:35], v[166:169], v[208:211], v[32:35]
	v_mfma_f32_16x16x32_bf16 v[132:135], v[162:165], v[178:181], v[132:135]
	v_mfma_f32_16x16x32_bf16 v[56:59], v[170:173], v[178:181], v[56:59]
	v_mfma_f32_16x16x32_bf16 v[124:127], v[162:165], v[196:199], v[124:127]
	v_mfma_f32_16x16x32_bf16 v[48:51], v[170:173], v[196:199], v[48:51]
	v_mfma_f32_16x16x32_bf16 v[116:119], v[162:165], v[204:207], v[116:119]
	v_mfma_f32_16x16x32_bf16 v[40:43], v[170:173], v[204:207], v[40:43]
	v_mfma_f32_16x16x32_bf16 v[96:99], v[162:165], v[212:215], v[96:99]
	v_mfma_f32_16x16x32_bf16 v[32:35], v[170:173], v[212:215], v[32:35]
	s_setprio 0
	s_barrier
	s_mov_b32 m0, s79
	v_lshl_add_u64 v[182:183], s[48:49], 0, v[142:143]
	ds_read_b128 v[174:177], v195 offset:16384
	ds_read_b128 v[178:181], v195 offset:17408
	ds_read_b128 v[186:189], v195 offset:18432
	ds_read_b128 v[196:199], v195 offset:19456
	ds_read_b128 v[200:203], v195 offset:20480
	ds_read_b128 v[204:207], v195 offset:21504
	ds_read_b128 v[208:211], v195 offset:22528
	ds_read_b128 v[212:215], v195 offset:23552
	global_load_lds_dwordx4 v[182:183], off
	v_lshl_add_u64 v[216:217], s[48:49], 0, v[146:147]
	s_mov_b32 m0, s76
	v_lshl_add_u64 v[218:219], s[50:51], 0, v[142:143]
	global_load_lds_dwordx4 v[216:217], off
	s_mov_b32 m0, s78
	v_lshl_add_u64 v[220:221], s[46:47], 0, v[144:145]
	global_load_lds_dwordx4 v[218:219], off
	v_lshl_add_u64 v[218:219], s[50:51], 0, v[146:147]
	s_mov_b32 m0, s77
	s_nop 0
	global_load_lds_dwordx4 v[218:219], off
	v_lshl_add_u64 v[218:219], s[46:47], 0, v[140:141]
	s_mov_b32 m0, s23
	s_nop 0
	global_load_lds_dwordx4 v[218:219], off
	s_mov_b32 m0, s25
	s_nop 0
	global_load_lds_dwordx4 v[220:221], off
	s_waitcnt vmcnt(8)
	s_waitcnt lgkmcnt(0)
	s_barrier
	s_setprio 1
	s_waitcnt lgkmcnt(0)
	v_mfma_f32_16x16x32_bf16 v[92:95], v[104:107], v[174:177], v[92:95]
	v_mfma_f32_16x16x32_bf16 v[28:31], v[112:115], v[174:177], v[28:31]
	v_mfma_f32_16x16x32_bf16 v[84:87], v[104:107], v[186:189], v[84:87]
	v_mfma_f32_16x16x32_bf16 v[20:23], v[112:115], v[186:189], v[20:23]
	v_mfma_f32_16x16x32_bf16 v[76:79], v[104:107], v[200:203], v[76:79]
	v_mfma_f32_16x16x32_bf16 v[12:15], v[112:115], v[200:203], v[12:15]
	v_mfma_f32_16x16x32_bf16 v[68:71], v[104:107], v[208:211], v[68:71]
	v_mfma_f32_16x16x32_bf16 v[4:7], v[112:115], v[208:211], v[4:7]
	v_mfma_f32_16x16x32_bf16 v[92:95], v[108:111], v[178:181], v[92:95]
	v_mfma_f32_16x16x32_bf16 v[28:31], v[154:157], v[178:181], v[28:31]
	v_mfma_f32_16x16x32_bf16 v[84:87], v[108:111], v[196:199], v[84:87]
	v_mfma_f32_16x16x32_bf16 v[20:23], v[154:157], v[196:199], v[20:23]
	v_mfma_f32_16x16x32_bf16 v[76:79], v[108:111], v[204:207], v[76:79]
	v_mfma_f32_16x16x32_bf16 v[12:15], v[154:157], v[204:207], v[12:15]
	v_mfma_f32_16x16x32_bf16 v[68:71], v[108:111], v[212:215], v[68:71]
	v_mfma_f32_16x16x32_bf16 v[4:7], v[154:157], v[212:215], v[4:7]
	v_mfma_f32_16x16x32_bf16 v[88:91], v[158:161], v[174:177], v[88:91]
	v_mfma_f32_16x16x32_bf16 v[24:27], v[166:169], v[174:177], v[24:27]
	v_mfma_f32_16x16x32_bf16 v[80:83], v[158:161], v[186:189], v[80:83]
	v_mfma_f32_16x16x32_bf16 v[16:19], v[166:169], v[186:189], v[16:19]
	v_mfma_f32_16x16x32_bf16 v[72:75], v[158:161], v[200:203], v[72:75]
	v_mfma_f32_16x16x32_bf16 v[8:11], v[166:169], v[200:203], v[8:11]
	v_mfma_f32_16x16x32_bf16 v[64:67], v[158:161], v[208:211], v[64:67]
	v_mfma_f32_16x16x32_bf16 v[0:3], v[166:169], v[208:211], v[0:3]
	v_mfma_f32_16x16x32_bf16 v[88:91], v[162:165], v[178:181], v[88:91]
	v_mfma_f32_16x16x32_bf16 v[24:27], v[170:173], v[178:181], v[24:27]
	v_mfma_f32_16x16x32_bf16 v[80:83], v[162:165], v[196:199], v[80:83]
	v_mfma_f32_16x16x32_bf16 v[16:19], v[170:173], v[196:199], v[16:19]
	v_mfma_f32_16x16x32_bf16 v[72:75], v[162:165], v[204:207], v[72:75]
	v_mfma_f32_16x16x32_bf16 v[8:11], v[170:173], v[204:207], v[8:11]
	v_mfma_f32_16x16x32_bf16 v[64:67], v[162:165], v[212:215], v[64:67]
	v_mfma_f32_16x16x32_bf16 v[0:3], v[170:173], v[212:215], v[0:3]
	s_setprio 0
	s_barrier
	v_add_u32_e32 v148, s73, v192
	ds_read_b128 v[104:107], v148
	ds_read_b128 v[108:111], v148 offset:1024
	ds_read_b128 v[112:115], v148 offset:2048
	ds_read_b128 v[154:157], v148 offset:3072
	v_add_u32_e32 v148, s72, v192
	ds_read_b128 v[158:161], v148
	ds_read_b128 v[162:165], v148 offset:1024
	ds_read_b128 v[166:169], v148 offset:2048
	ds_read_b128 v[170:173], v148 offset:3072
	s_mov_b32 m0, s33
	v_lshl_add_u64 v[222:223], s[44:45], 0, v[140:141]
	ds_read_b128 v[174:177], v195 offset:32768
	ds_read_b128 v[178:181], v195 offset:33792
	ds_read_b128 v[186:189], v195 offset:34816
	ds_read_b128 v[196:199], v195 offset:35840
	ds_read_b128 v[200:203], v195 offset:36864
	ds_read_b128 v[204:207], v195 offset:37888
	ds_read_b128 v[208:211], v195 offset:38912
	ds_read_b128 v[212:215], v195 offset:39936
	global_load_lds_dwordx4 v[222:223], off
	v_lshl_add_u64 v[222:223], s[44:45], 0, v[144:145]
	s_mov_b32 m0, s37
	s_nop 0
	global_load_lds_dwordx4 v[222:223], off
	s_waitcnt vmcnt(8)
	s_waitcnt lgkmcnt(0)
	s_barrier
	s_setprio 1
	s_waitcnt lgkmcnt(0)
	v_mfma_f32_16x16x32_bf16 v[136:139], v[104:107], v[174:177], v[136:139]
	v_mfma_f32_16x16x32_bf16 v[60:63], v[112:115], v[174:177], v[60:63]
	v_mfma_f32_16x16x32_bf16 v[128:131], v[104:107], v[186:189], v[128:131]
	v_mfma_f32_16x16x32_bf16 v[52:55], v[112:115], v[186:189], v[52:55]
	v_mfma_f32_16x16x32_bf16 v[120:123], v[104:107], v[200:203], v[120:123]
	v_mfma_f32_16x16x32_bf16 v[44:47], v[112:115], v[200:203], v[44:47]
	v_mfma_f32_16x16x32_bf16 v[100:103], v[104:107], v[208:211], v[100:103]
	v_mfma_f32_16x16x32_bf16 v[36:39], v[112:115], v[208:211], v[36:39]
	v_mfma_f32_16x16x32_bf16 v[136:139], v[108:111], v[178:181], v[136:139]
	v_mfma_f32_16x16x32_bf16 v[60:63], v[154:157], v[178:181], v[60:63]
	v_mfma_f32_16x16x32_bf16 v[128:131], v[108:111], v[196:199], v[128:131]
	v_mfma_f32_16x16x32_bf16 v[52:55], v[154:157], v[196:199], v[52:55]
	v_mfma_f32_16x16x32_bf16 v[120:123], v[108:111], v[204:207], v[120:123]
	v_mfma_f32_16x16x32_bf16 v[44:47], v[154:157], v[204:207], v[44:47]
	v_mfma_f32_16x16x32_bf16 v[100:103], v[108:111], v[212:215], v[100:103]
	v_mfma_f32_16x16x32_bf16 v[36:39], v[154:157], v[212:215], v[36:39]
	v_mfma_f32_16x16x32_bf16 v[132:135], v[158:161], v[174:177], v[132:135]
	v_mfma_f32_16x16x32_bf16 v[56:59], v[166:169], v[174:177], v[56:59]
	v_mfma_f32_16x16x32_bf16 v[124:127], v[158:161], v[186:189], v[124:127]
	v_mfma_f32_16x16x32_bf16 v[48:51], v[166:169], v[186:189], v[48:51]
	v_mfma_f32_16x16x32_bf16 v[116:119], v[158:161], v[200:203], v[116:119]
	v_mfma_f32_16x16x32_bf16 v[40:43], v[166:169], v[200:203], v[40:43]
	v_mfma_f32_16x16x32_bf16 v[96:99], v[158:161], v[208:211], v[96:99]
	v_mfma_f32_16x16x32_bf16 v[32:35], v[166:169], v[208:211], v[32:35]
	v_mfma_f32_16x16x32_bf16 v[132:135], v[162:165], v[178:181], v[132:135]
	v_mfma_f32_16x16x32_bf16 v[56:59], v[170:173], v[178:181], v[56:59]
	v_mfma_f32_16x16x32_bf16 v[124:127], v[162:165], v[196:199], v[124:127]
	v_mfma_f32_16x16x32_bf16 v[48:51], v[170:173], v[196:199], v[48:51]
	v_mfma_f32_16x16x32_bf16 v[116:119], v[162:165], v[204:207], v[116:119]
	v_mfma_f32_16x16x32_bf16 v[40:43], v[170:173], v[204:207], v[40:43]
	v_mfma_f32_16x16x32_bf16 v[96:99], v[162:165], v[212:215], v[96:99]
	v_mfma_f32_16x16x32_bf16 v[32:35], v[170:173], v[212:215], v[32:35]
	s_setprio 0
	s_barrier
	s_mov_b32 m0, s71
	v_lshl_add_u64 v[182:183], v[182:183], 0, s[18:19]
	ds_read_b128 v[174:177], v195 offset:49152
	ds_read_b128 v[178:181], v195 offset:50176
	ds_read_b128 v[186:189], v195 offset:51200
	ds_read_b128 v[196:199], v195 offset:52224
	ds_read_b128 v[200:203], v195 offset:53248
	ds_read_b128 v[204:207], v195 offset:54272
	ds_read_b128 v[208:211], v195 offset:55296
	ds_read_b128 v[212:215], v195 offset:56320
	global_load_lds_dwordx4 v[182:183], off
	v_lshl_add_u64 v[182:183], v[216:217], 0, s[18:19]
	s_mov_b32 m0, s69
	s_nop 0
	global_load_lds_dwordx4 v[182:183], off
	v_lshl_add_u64 v[182:183], s[42:43], 0, v[142:143]
	s_mov_b32 m0, s70
	s_nop 0
	global_load_lds_dwordx4 v[182:183], off
	v_lshl_add_u64 v[182:183], s[42:43], 0, v[146:147]
	s_mov_b32 m0, s68
	s_nop 0
	global_load_lds_dwordx4 v[182:183], off
	v_lshl_add_u64 v[182:183], v[218:219], 0, s[18:19]
	s_mov_b32 m0, s57
	s_nop 0
	global_load_lds_dwordx4 v[182:183], off
	v_lshl_add_u64 v[182:183], v[220:221], 0, s[18:19]
	s_mov_b32 m0, s61
	s_nop 0
	global_load_lds_dwordx4 v[182:183], off
	s_waitcnt vmcnt(8)
	s_waitcnt lgkmcnt(0)
	s_barrier
	s_setprio 1
	s_waitcnt lgkmcnt(0)
	v_mfma_f32_16x16x32_bf16 v[92:95], v[104:107], v[174:177], v[92:95]
	v_mfma_f32_16x16x32_bf16 v[28:31], v[112:115], v[174:177], v[28:31]
	v_mfma_f32_16x16x32_bf16 v[84:87], v[104:107], v[186:189], v[84:87]
	v_mfma_f32_16x16x32_bf16 v[20:23], v[112:115], v[186:189], v[20:23]
	v_mfma_f32_16x16x32_bf16 v[76:79], v[104:107], v[200:203], v[76:79]
	v_mfma_f32_16x16x32_bf16 v[12:15], v[112:115], v[200:203], v[12:15]
	v_mfma_f32_16x16x32_bf16 v[68:71], v[104:107], v[208:211], v[68:71]
	v_mfma_f32_16x16x32_bf16 v[4:7], v[112:115], v[208:211], v[4:7]
	v_mfma_f32_16x16x32_bf16 v[92:95], v[108:111], v[178:181], v[92:95]
	v_mfma_f32_16x16x32_bf16 v[28:31], v[154:157], v[178:181], v[28:31]
	v_mfma_f32_16x16x32_bf16 v[84:87], v[108:111], v[196:199], v[84:87]
	v_mfma_f32_16x16x32_bf16 v[20:23], v[154:157], v[196:199], v[20:23]
	v_mfma_f32_16x16x32_bf16 v[76:79], v[108:111], v[204:207], v[76:79]
	v_mfma_f32_16x16x32_bf16 v[12:15], v[154:157], v[204:207], v[12:15]
	v_mfma_f32_16x16x32_bf16 v[68:71], v[108:111], v[212:215], v[68:71]
	v_mfma_f32_16x16x32_bf16 v[4:7], v[154:157], v[212:215], v[4:7]
	v_mfma_f32_16x16x32_bf16 v[88:91], v[158:161], v[174:177], v[88:91]
	v_mfma_f32_16x16x32_bf16 v[24:27], v[166:169], v[174:177], v[24:27]
	v_mfma_f32_16x16x32_bf16 v[80:83], v[158:161], v[186:189], v[80:83]
	v_mfma_f32_16x16x32_bf16 v[16:19], v[166:169], v[186:189], v[16:19]
	v_mfma_f32_16x16x32_bf16 v[72:75], v[158:161], v[200:203], v[72:75]
	v_mfma_f32_16x16x32_bf16 v[8:11], v[166:169], v[200:203], v[8:11]
	v_mfma_f32_16x16x32_bf16 v[64:67], v[158:161], v[208:211], v[64:67]
	v_mfma_f32_16x16x32_bf16 v[0:3], v[166:169], v[208:211], v[0:3]
	v_mfma_f32_16x16x32_bf16 v[88:91], v[162:165], v[178:181], v[88:91]
	v_mfma_f32_16x16x32_bf16 v[24:27], v[170:173], v[178:181], v[24:27]
	v_mfma_f32_16x16x32_bf16 v[80:83], v[162:165], v[196:199], v[80:83]
	v_mfma_f32_16x16x32_bf16 v[16:19], v[170:173], v[196:199], v[16:19]
	v_mfma_f32_16x16x32_bf16 v[72:75], v[162:165], v[204:207], v[72:75]
	v_mfma_f32_16x16x32_bf16 v[8:11], v[170:173], v[204:207], v[8:11]
	v_mfma_f32_16x16x32_bf16 v[64:67], v[162:165], v[212:215], v[64:67]
	v_mfma_f32_16x16x32_bf16 v[0:3], v[170:173], v[212:215], v[0:3]
	s_setprio 0
	s_barrier
	s_andn2_b64 vcc, exec, s[6:7]
	s_mov_b64 s[42:43], -1
	s_mov_b64 s[6:7], 0
	s_mov_b64 s[44:45], 0x100
	s_cbranch_vccz .LBB0_315
	s_and_b64 vcc, exec, s[20:21]
	s_cbranch_vccz .LBB0_318
	s_barrier

.LBB0_516:
	ds_read_b128 v[120:123], v215
	ds_read_b128 v[132:135], v215 offset:1024
	ds_read_b128 v[136:139], v215 offset:2048
	ds_read_b128 v[140:143], v215 offset:3072
	ds_read_b128 v[144:147], v216
	ds_read_b128 v[148:151], v216 offset:1024
	ds_read_b128 v[152:155], v216 offset:2048
	ds_read_b128 v[156:159], v216 offset:3072
	s_add_u32 s34, s8, 0xfff80080
	s_addc_u32 s35, s9, -1
	s_cmp_eq_u32 s54, 28
	s_cselect_b32 s37, s7, s35
	s_cselect_b32 s36, s23, s34
	s_cselect_b32 s35, s21, s53
	s_cselect_b32 s34, s31, s52
	v_lshl_add_u64 v[220:221], s[8:9], 0, v[196:197]
	s_add_i32 m0, s33, 0xc000
	ds_read_b128 v[160:163], v217
	ds_read_b128 v[164:167], v217 offset:1024
	ds_read_b128 v[168:171], v217 offset:2048
	ds_read_b128 v[172:175], v217 offset:3072
	ds_read_b128 v[176:179], v217 offset:4096
	ds_read_b128 v[180:183], v217 offset:5120
	ds_read_b128 v[204:207], v217 offset:6144
	ds_read_b128 v[208:211], v217 offset:7168
	global_load_lds_dwordx4 v[220:221], off
	v_lshl_add_u64 v[220:221], s[8:9], 0, v[198:199]
	s_add_i32 m0, s33, 0xe000
	s_nop 0
	global_load_lds_dwordx4 v[220:221], off
	s_waitcnt vmcnt(8)
	s_waitcnt lgkmcnt(0)
	s_barrier
	s_setprio 1
	s_waitcnt lgkmcnt(0)
	v_mfma_f32_16x16x32_bf16 v[128:131], v[120:123], v[160:163], v[128:131]
	v_mfma_f32_16x16x32_bf16 v[124:127], v[136:139], v[160:163], v[124:127]
	v_mfma_f32_16x16x32_bf16 v[108:111], v[120:123], v[168:171], v[108:111]
	v_mfma_f32_16x16x32_bf16 v[104:107], v[136:139], v[168:171], v[104:107]
	v_mfma_f32_16x16x32_bf16 v[92:95], v[120:123], v[176:179], v[92:95]
	v_mfma_f32_16x16x32_bf16 v[88:91], v[136:139], v[176:179], v[88:91]
	v_mfma_f32_16x16x32_bf16 v[76:79], v[120:123], v[204:207], v[76:79]
	v_mfma_f32_16x16x32_bf16 v[72:75], v[136:139], v[204:207], v[72:75]
	v_mfma_f32_16x16x32_bf16 v[128:131], v[132:135], v[164:167], v[128:131]
	v_mfma_f32_16x16x32_bf16 v[124:127], v[140:143], v[164:167], v[124:127]
	v_mfma_f32_16x16x32_bf16 v[108:111], v[132:135], v[172:175], v[108:111]
	v_mfma_f32_16x16x32_bf16 v[104:107], v[140:143], v[172:175], v[104:107]
	v_mfma_f32_16x16x32_bf16 v[92:95], v[132:135], v[180:183], v[92:95]
	v_mfma_f32_16x16x32_bf16 v[88:91], v[140:143], v[180:183], v[88:91]
	v_mfma_f32_16x16x32_bf16 v[76:79], v[132:135], v[208:211], v[76:79]
	v_mfma_f32_16x16x32_bf16 v[72:75], v[140:143], v[208:211], v[72:75]
	v_mfma_f32_16x16x32_bf16 v[116:119], v[144:147], v[160:163], v[116:119]
	v_mfma_f32_16x16x32_bf16 v[112:115], v[152:155], v[160:163], v[112:115]
	v_mfma_f32_16x16x32_bf16 v[100:103], v[144:147], v[168:171], v[100:103]
	v_mfma_f32_16x16x32_bf16 v[96:99], v[152:155], v[168:171], v[96:99]
	v_mfma_f32_16x16x32_bf16 v[84:87], v[144:147], v[176:179], v[84:87]
	v_mfma_f32_16x16x32_bf16 v[80:83], v[152:155], v[176:179], v[80:83]
	v_mfma_f32_16x16x32_bf16 v[68:71], v[144:147], v[204:207], v[68:71]
	v_mfma_f32_16x16x32_bf16 v[64:67], v[152:155], v[204:207], v[64:67]
	v_mfma_f32_16x16x32_bf16 v[116:119], v[148:151], v[164:167], v[116:119]
	v_mfma_f32_16x16x32_bf16 v[112:115], v[156:159], v[164:167], v[112:115]
	v_mfma_f32_16x16x32_bf16 v[100:103], v[148:151], v[172:175], v[100:103]
	v_mfma_f32_16x16x32_bf16 v[96:99], v[156:159], v[172:175], v[96:99]
	v_mfma_f32_16x16x32_bf16 v[84:87], v[148:151], v[180:183], v[84:87]
	v_mfma_f32_16x16x32_bf16 v[80:83], v[156:159], v[180:183], v[80:83]
	v_mfma_f32_16x16x32_bf16 v[68:71], v[148:151], v[208:211], v[68:71]
	v_mfma_f32_16x16x32_bf16 v[64:67], v[156:159], v[208:211], v[64:67]
	s_setprio 0
	s_barrier
	s_add_i32 s55, s50, s25
	v_lshl_add_u64 v[220:221], s[34:35], 0, v[188:189]
	s_mov_b32 m0, s55
	ds_read_b128 v[160:163], v217 offset:16384
	ds_read_b128 v[164:167], v217 offset:17408
	ds_read_b128 v[168:171], v217 offset:18432
	ds_read_b128 v[172:175], v217 offset:19456
	ds_read_b128 v[176:179], v217 offset:20480
	ds_read_b128 v[180:183], v217 offset:21504
	ds_read_b128 v[204:207], v217 offset:22528
	ds_read_b128 v[208:211], v217 offset:23552
	global_load_lds_dwordx4 v[220:221], off
	s_add_i32 m0, s55, 0x2000
	s_add_u32 s56, s34, 0x80000
	v_lshl_add_u64 v[222:223], s[34:35], 0, v[192:193]
	s_addc_u32 s57, s35, 0
	s_add_i32 s55, s51, s25
	global_load_lds_dwordx4 v[222:223], off
	v_lshl_add_u64 v[224:225], s[56:57], 0, v[188:189]
	s_mov_b32 m0, s55
	v_lshl_add_u64 v[226:227], s[36:37], 0, v[190:191]
	global_load_lds_dwordx4 v[224:225], off
	v_lshl_add_u64 v[224:225], s[56:57], 0, v[192:193]
	s_add_i32 m0, s55, 0x2000
	s_nop 0
	global_load_lds_dwordx4 v[224:225], off
	v_lshl_add_u64 v[224:225], s[36:37], 0, v[186:187]
	s_mov_b32 m0, s33
	s_nop 0
	global_load_lds_dwordx4 v[224:225], off
	s_mov_b32 m0, s38
	s_nop 0
	global_load_lds_dwordx4 v[226:227], off
	s_waitcnt vmcnt(8)
	s_waitcnt lgkmcnt(0)
	s_barrier
	s_setprio 1
	s_waitcnt lgkmcnt(0)
	v_mfma_f32_16x16x32_bf16 v[60:63], v[120:123], v[160:163], v[60:63]
	v_mfma_f32_16x16x32_bf16 v[56:59], v[136:139], v[160:163], v[56:59]
	v_mfma_f32_16x16x32_bf16 v[44:47], v[120:123], v[168:171], v[44:47]
	v_mfma_f32_16x16x32_bf16 v[40:43], v[136:139], v[168:171], v[40:43]
	v_mfma_f32_16x16x32_bf16 v[28:31], v[120:123], v[176:179], v[28:31]
	v_mfma_f32_16x16x32_bf16 v[24:27], v[136:139], v[176:179], v[24:27]
	v_mfma_f32_16x16x32_bf16 v[12:15], v[120:123], v[204:207], v[12:15]
	v_mfma_f32_16x16x32_bf16 v[8:11], v[136:139], v[204:207], v[8:11]
	v_mfma_f32_16x16x32_bf16 v[60:63], v[132:135], v[164:167], v[60:63]
	v_mfma_f32_16x16x32_bf16 v[56:59], v[140:143], v[164:167], v[56:59]
	v_mfma_f32_16x16x32_bf16 v[44:47], v[132:135], v[172:175], v[44:47]
	v_mfma_f32_16x16x32_bf16 v[40:43], v[140:143], v[172:175], v[40:43]
	v_mfma_f32_16x16x32_bf16 v[28:31], v[132:135], v[180:183], v[28:31]
	v_mfma_f32_16x16x32_bf16 v[24:27], v[140:143], v[180:183], v[24:27]
	v_mfma_f32_16x16x32_bf16 v[12:15], v[132:135], v[208:211], v[12:15]
	v_mfma_f32_16x16x32_bf16 v[8:11], v[140:143], v[208:211], v[8:11]
	v_mfma_f32_16x16x32_bf16 v[52:55], v[144:147], v[160:163], v[52:55]
	v_mfma_f32_16x16x32_bf16 v[48:51], v[152:155], v[160:163], v[48:51]
	v_mfma_f32_16x16x32_bf16 v[36:39], v[144:147], v[168:171], v[36:39]
	v_mfma_f32_16x16x32_bf16 v[32:35], v[152:155], v[168:171], v[32:35]
	v_mfma_f32_16x16x32_bf16 v[20:23], v[144:147], v[176:179], v[20:23]
	v_mfma_f32_16x16x32_bf16 v[16:19], v[152:155], v[176:179], v[16:19]
	v_mfma_f32_16x16x32_bf16 v[4:7], v[144:147], v[204:207], v[4:7]
	v_mfma_f32_16x16x32_bf16 v[0:3], v[152:155], v[204:207], v[0:3]
	v_mfma_f32_16x16x32_bf16 v[52:55], v[148:151], v[164:167], v[52:55]
	v_mfma_f32_16x16x32_bf16 v[48:51], v[156:159], v[164:167], v[48:51]
	v_mfma_f32_16x16x32_bf16 v[36:39], v[148:151], v[172:175], v[36:39]
	v_mfma_f32_16x16x32_bf16 v[32:35], v[156:159], v[172:175], v[32:35]
	v_mfma_f32_16x16x32_bf16 v[20:23], v[148:151], v[180:183], v[20:23]
	v_mfma_f32_16x16x32_bf16 v[16:19], v[156:159], v[180:183], v[16:19]
	v_mfma_f32_16x16x32_bf16 v[4:7], v[148:151], v[208:211], v[4:7]
	v_mfma_f32_16x16x32_bf16 v[0:3], v[156:159], v[208:211], v[0:3]
	s_setprio 0
	s_barrier
	s_add_i32 s55, 0, 0x18000
	s_add_i32 s56, 0, 0x1c000
	v_add_u32_e32 v140, s55, v214
	v_add_u32_e32 v156, s56, v214
	ds_read_b128 v[120:123], v140
	ds_read_b128 v[132:135], v140 offset:1024
	ds_read_b128 v[136:139], v140 offset:2048
	ds_read_b128 v[140:143], v140 offset:3072
	ds_read_b128 v[144:147], v156
	ds_read_b128 v[148:151], v156 offset:1024
	ds_read_b128 v[152:155], v156 offset:2048
	ds_read_b128 v[156:159], v156 offset:3072
	s_add_u32 s36, s36, 0x80000
	s_addc_u32 s37, s37, 0
	s_mov_b32 m0, s39
	v_lshl_add_u64 v[228:229], s[36:37], 0, v[186:187]
	ds_read_b128 v[160:163], v217 offset:32768
	ds_read_b128 v[164:167], v217 offset:33792
	ds_read_b128 v[168:171], v217 offset:34816
	ds_read_b128 v[172:175], v217 offset:35840
	ds_read_b128 v[176:179], v217 offset:36864
	ds_read_b128 v[180:183], v217 offset:37888
	ds_read_b128 v[204:207], v217 offset:38912
	ds_read_b128 v[208:211], v217 offset:39936
	global_load_lds_dwordx4 v[228:229], off
	v_lshl_add_u64 v[228:229], s[36:37], 0, v[190:191]
	s_mov_b32 m0, s40
	s_nop 0
	global_load_lds_dwordx4 v[228:229], off
	s_waitcnt vmcnt(8)
	s_waitcnt lgkmcnt(0)
	s_barrier
	s_setprio 1
	s_waitcnt lgkmcnt(0)
	v_mfma_f32_16x16x32_bf16 v[128:131], v[120:123], v[160:163], v[128:131]
	v_mfma_f32_16x16x32_bf16 v[124:127], v[136:139], v[160:163], v[124:127]
	v_mfma_f32_16x16x32_bf16 v[108:111], v[120:123], v[168:171], v[108:111]
	v_mfma_f32_16x16x32_bf16 v[104:107], v[136:139], v[168:171], v[104:107]
	v_mfma_f32_16x16x32_bf16 v[92:95], v[120:123], v[176:179], v[92:95]
	v_mfma_f32_16x16x32_bf16 v[88:91], v[136:139], v[176:179], v[88:91]
	v_mfma_f32_16x16x32_bf16 v[76:79], v[120:123], v[204:207], v[76:79]
	v_mfma_f32_16x16x32_bf16 v[72:75], v[136:139], v[204:207], v[72:75]
	v_mfma_f32_16x16x32_bf16 v[128:131], v[132:135], v[164:167], v[128:131]
	v_mfma_f32_16x16x32_bf16 v[124:127], v[140:143], v[164:167], v[124:127]
	v_mfma_f32_16x16x32_bf16 v[108:111], v[132:135], v[172:175], v[108:111]
	v_mfma_f32_16x16x32_bf16 v[104:107], v[140:143], v[172:175], v[104:107]
	v_mfma_f32_16x16x32_bf16 v[92:95], v[132:135], v[180:183], v[92:95]
	v_mfma_f32_16x16x32_bf16 v[88:91], v[140:143], v[180:183], v[88:91]
	v_mfma_f32_16x16x32_bf16 v[76:79], v[132:135], v[208:211], v[76:79]
	v_mfma_f32_16x16x32_bf16 v[72:75], v[140:143], v[208:211], v[72:75]
	v_mfma_f32_16x16x32_bf16 v[116:119], v[144:147], v[160:163], v[116:119]
	v_mfma_f32_16x16x32_bf16 v[112:115], v[152:155], v[160:163], v[112:115]
	v_mfma_f32_16x16x32_bf16 v[100:103], v[144:147], v[168:171], v[100:103]
	v_mfma_f32_16x16x32_bf16 v[96:99], v[152:155], v[168:171], v[96:99]
	v_mfma_f32_16x16x32_bf16 v[84:87], v[144:147], v[176:179], v[84:87]
	v_mfma_f32_16x16x32_bf16 v[80:83], v[152:155], v[176:179], v[80:83]
	v_mfma_f32_16x16x32_bf16 v[68:71], v[144:147], v[204:207], v[68:71]
	v_mfma_f32_16x16x32_bf16 v[64:67], v[152:155], v[204:207], v[64:67]
	v_mfma_f32_16x16x32_bf16 v[116:119], v[148:151], v[164:167], v[116:119]
	v_mfma_f32_16x16x32_bf16 v[112:115], v[156:159], v[164:167], v[112:115]
	v_mfma_f32_16x16x32_bf16 v[100:103], v[148:151], v[172:175], v[100:103]
	v_mfma_f32_16x16x32_bf16 v[96:99], v[156:159], v[172:175], v[96:99]
	v_mfma_f32_16x16x32_bf16 v[84:87], v[148:151], v[180:183], v[84:87]
	v_mfma_f32_16x16x32_bf16 v[80:83], v[156:159], v[180:183], v[80:83]
	v_mfma_f32_16x16x32_bf16 v[68:71], v[148:151], v[208:211], v[68:71]
	v_mfma_f32_16x16x32_bf16 v[64:67], v[156:159], v[208:211], v[64:67]
	s_setprio 0
	s_barrier
	s_add_i32 s36, s55, s25
	v_lshl_add_u64 v[220:221], v[220:221], 0, s[12:13]
	s_mov_b32 m0, s36
	ds_read_b128 v[160:163], v217 offset:49152
	ds_read_b128 v[164:167], v217 offset:50176
	ds_read_b128 v[168:171], v217 offset:51200
	ds_read_b128 v[172:175], v217 offset:52224
	ds_read_b128 v[176:179], v217 offset:53248
	ds_read_b128 v[180:183], v217 offset:54272
	ds_read_b128 v[204:207], v217 offset:55296
	ds_read_b128 v[208:211], v217 offset:56320
	global_load_lds_dwordx4 v[220:221], off
	s_add_i32 m0, s36, 0x2000
	s_add_u32 s34, s34, 0x80080
	v_lshl_add_u64 v[220:221], v[222:223], 0, s[12:13]
	s_addc_u32 s35, s35, 0
	s_add_i32 s36, s56, s25
	global_load_lds_dwordx4 v[220:221], off
	v_lshl_add_u64 v[220:221], s[34:35], 0, v[188:189]
	s_mov_b32 m0, s36
	s_nop 0
	global_load_lds_dwordx4 v[220:221], off
	v_lshl_add_u64 v[220:221], s[34:35], 0, v[192:193]
	s_add_i32 m0, s36, 0x2000
	s_nop 0
	global_load_lds_dwordx4 v[220:221], off
	v_lshl_add_u64 v[220:221], v[224:225], 0, s[12:13]
	s_mov_b32 m0, s45
	s_nop 0
	global_load_lds_dwordx4 v[220:221], off
	v_lshl_add_u64 v[220:221], v[226:227], 0, s[12:13]
	s_mov_b32 m0, s46
	s_nop 0
	global_load_lds_dwordx4 v[220:221], off
	s_waitcnt vmcnt(8)
	s_waitcnt lgkmcnt(0)
	s_barrier
	s_setprio 1
	s_waitcnt lgkmcnt(0)
	v_mfma_f32_16x16x32_bf16 v[60:63], v[120:123], v[160:163], v[60:63]
	v_mfma_f32_16x16x32_bf16 v[56:59], v[136:139], v[160:163], v[56:59]
	v_mfma_f32_16x16x32_bf16 v[44:47], v[120:123], v[168:171], v[44:47]
	v_mfma_f32_16x16x32_bf16 v[40:43], v[136:139], v[168:171], v[40:43]
	v_mfma_f32_16x16x32_bf16 v[28:31], v[120:123], v[176:179], v[28:31]
	v_mfma_f32_16x16x32_bf16 v[24:27], v[136:139], v[176:179], v[24:27]
	v_mfma_f32_16x16x32_bf16 v[12:15], v[120:123], v[204:207], v[12:15]
	v_mfma_f32_16x16x32_bf16 v[8:11], v[136:139], v[204:207], v[8:11]
	v_mfma_f32_16x16x32_bf16 v[60:63], v[132:135], v[164:167], v[60:63]
	v_mfma_f32_16x16x32_bf16 v[56:59], v[140:143], v[164:167], v[56:59]
	v_mfma_f32_16x16x32_bf16 v[44:47], v[132:135], v[172:175], v[44:47]
	v_mfma_f32_16x16x32_bf16 v[40:43], v[140:143], v[172:175], v[40:43]
	v_mfma_f32_16x16x32_bf16 v[28:31], v[132:135], v[180:183], v[28:31]
	v_mfma_f32_16x16x32_bf16 v[24:27], v[140:143], v[180:183], v[24:27]
	v_mfma_f32_16x16x32_bf16 v[12:15], v[132:135], v[208:211], v[12:15]
	v_mfma_f32_16x16x32_bf16 v[8:11], v[140:143], v[208:211], v[8:11]
	v_mfma_f32_16x16x32_bf16 v[52:55], v[144:147], v[160:163], v[52:55]
	v_mfma_f32_16x16x32_bf16 v[48:51], v[152:155], v[160:163], v[48:51]
	v_mfma_f32_16x16x32_bf16 v[36:39], v[144:147], v[168:171], v[36:39]
	v_mfma_f32_16x16x32_bf16 v[32:35], v[152:155], v[168:171], v[32:35]
	v_mfma_f32_16x16x32_bf16 v[20:23], v[144:147], v[176:179], v[20:23]
	v_mfma_f32_16x16x32_bf16 v[16:19], v[152:155], v[176:179], v[16:19]
	v_mfma_f32_16x16x32_bf16 v[4:7], v[144:147], v[204:207], v[4:7]
	v_mfma_f32_16x16x32_bf16 v[0:3], v[152:155], v[204:207], v[0:3]
	v_mfma_f32_16x16x32_bf16 v[52:55], v[148:151], v[164:167], v[52:55]
	v_mfma_f32_16x16x32_bf16 v[48:51], v[156:159], v[164:167], v[48:51]
	v_mfma_f32_16x16x32_bf16 v[36:39], v[148:151], v[172:175], v[36:39]
	v_mfma_f32_16x16x32_bf16 v[32:35], v[156:159], v[172:175], v[32:35]
	v_mfma_f32_16x16x32_bf16 v[20:23], v[148:151], v[180:183], v[20:23]
	v_mfma_f32_16x16x32_bf16 v[16:19], v[156:159], v[180:183], v[16:19]
	v_mfma_f32_16x16x32_bf16 v[4:7], v[148:151], v[208:211], v[4:7]
	v_mfma_f32_16x16x32_bf16 v[0:3], v[156:159], v[208:211], v[0:3]
	s_setprio 0
	s_barrier
	s_add_i32 s54, s54, 2
	s_add_u32 s8, s8, 0x100
	s_addc_u32 s9, s9, 0
	s_add_u32 s52, s52, 0x100
	s_addc_u32 s53, s53, 0
	s_cmp_gt_u32 s54, 29
	s_cbranch_scc0 .LBB0_516
	s_and_b64 vcc, exec, s[14:15]
	s_cbranch_vccz .LBB0_519
	s_barrier

.LBB0_632:
	ds_read_b128 v[128:131], v175
	ds_read_b128 v[132:135], v175 offset:1024
	ds_read_b128 v[136:139], v175 offset:2048
	ds_read_b128 v[140:143], v175 offset:3072
	ds_read_b128 v[144:147], v176
	ds_read_b128 v[148:151], v176 offset:1024
	ds_read_b128 v[186:189], v176 offset:2048
	ds_read_b128 v[190:193], v176 offset:3072
	s_add_u32 s22, s6, 0xfff80080
	s_addc_u32 s23, s7, -1
	s_cmp_eq_u32 s50, 28
	s_cselect_b32 s27, s17, s23
	s_cselect_b32 s26, s46, s22
	s_cselect_b32 s23, s15, s49
	s_cselect_b32 s22, s47, s48
	v_lshl_add_u64 v[170:171], s[6:7], 0, v[162:163]
	s_add_i32 m0, s30, 0xc000
	ds_read_b128 v[194:197], v177
	ds_read_b128 v[198:201], v177 offset:1024
	ds_read_b128 v[202:205], v177 offset:2048
	ds_read_b128 v[206:209], v177 offset:3072
	ds_read_b128 v[210:213], v177 offset:4096
	ds_read_b128 v[214:217], v177 offset:5120
	ds_read_b128 v[218:221], v177 offset:6144
	ds_read_b128 v[222:225], v177 offset:7168
	global_load_lds_dwordx4 v[170:171], off
	v_lshl_add_u64 v[170:171], s[6:7], 0, v[164:165]
	s_add_i32 m0, s30, 0xe000
	s_nop 0
	global_load_lds_dwordx4 v[170:171], off
	s_waitcnt vmcnt(8)
	s_waitcnt lgkmcnt(0)
	s_barrier
	s_setprio 1
	s_waitcnt lgkmcnt(0)
	v_mfma_f32_16x16x32_bf16 v[124:127], v[128:131], v[194:197], v[124:127]
	v_mfma_f32_16x16x32_bf16 v[116:119], v[136:139], v[194:197], v[116:119]
	v_mfma_f32_16x16x32_bf16 v[108:111], v[128:131], v[202:205], v[108:111]
	v_mfma_f32_16x16x32_bf16 v[100:103], v[136:139], v[202:205], v[100:103]
	v_mfma_f32_16x16x32_bf16 v[92:95], v[128:131], v[210:213], v[92:95]
	v_mfma_f32_16x16x32_bf16 v[84:87], v[136:139], v[210:213], v[84:87]
	v_mfma_f32_16x16x32_bf16 v[76:79], v[128:131], v[218:221], v[76:79]
	v_mfma_f32_16x16x32_bf16 v[68:71], v[136:139], v[218:221], v[68:71]
	v_mfma_f32_16x16x32_bf16 v[124:127], v[132:135], v[198:201], v[124:127]
	v_mfma_f32_16x16x32_bf16 v[116:119], v[140:143], v[198:201], v[116:119]
	v_mfma_f32_16x16x32_bf16 v[108:111], v[132:135], v[206:209], v[108:111]
	v_mfma_f32_16x16x32_bf16 v[100:103], v[140:143], v[206:209], v[100:103]
	v_mfma_f32_16x16x32_bf16 v[92:95], v[132:135], v[214:217], v[92:95]
	v_mfma_f32_16x16x32_bf16 v[84:87], v[140:143], v[214:217], v[84:87]
	v_mfma_f32_16x16x32_bf16 v[76:79], v[132:135], v[222:225], v[76:79]
	v_mfma_f32_16x16x32_bf16 v[68:71], v[140:143], v[222:225], v[68:71]
	v_mfma_f32_16x16x32_bf16 v[120:123], v[144:147], v[194:197], v[120:123]
	v_mfma_f32_16x16x32_bf16 v[112:115], v[186:189], v[194:197], v[112:115]
	v_mfma_f32_16x16x32_bf16 v[104:107], v[144:147], v[202:205], v[104:107]
	v_mfma_f32_16x16x32_bf16 v[96:99], v[186:189], v[202:205], v[96:99]
	v_mfma_f32_16x16x32_bf16 v[88:91], v[144:147], v[210:213], v[88:91]
	v_mfma_f32_16x16x32_bf16 v[80:83], v[186:189], v[210:213], v[80:83]
	v_mfma_f32_16x16x32_bf16 v[72:75], v[144:147], v[218:221], v[72:75]
	v_mfma_f32_16x16x32_bf16 v[64:67], v[186:189], v[218:221], v[64:67]
	v_mfma_f32_16x16x32_bf16 v[120:123], v[148:151], v[198:201], v[120:123]
	v_mfma_f32_16x16x32_bf16 v[112:115], v[190:193], v[198:201], v[112:115]
	v_mfma_f32_16x16x32_bf16 v[104:107], v[148:151], v[206:209], v[104:107]
	v_mfma_f32_16x16x32_bf16 v[96:99], v[190:193], v[206:209], v[96:99]
	v_mfma_f32_16x16x32_bf16 v[88:91], v[148:151], v[214:217], v[88:91]
	v_mfma_f32_16x16x32_bf16 v[80:83], v[190:193], v[214:217], v[80:83]
	v_mfma_f32_16x16x32_bf16 v[72:75], v[148:151], v[222:225], v[72:75]
	v_mfma_f32_16x16x32_bf16 v[64:67], v[190:193], v[222:225], v[64:67]
	s_setprio 0
	s_barrier
	s_add_i32 s51, s42, s25
	v_lshl_add_u64 v[170:171], s[22:23], 0, v[156:157]
	s_mov_b32 m0, s51
	ds_read_b128 v[194:197], v177 offset:16384
	ds_read_b128 v[198:201], v177 offset:17408
	ds_read_b128 v[202:205], v177 offset:18432
	ds_read_b128 v[206:209], v177 offset:19456
	ds_read_b128 v[210:213], v177 offset:20480
	ds_read_b128 v[214:217], v177 offset:21504
	ds_read_b128 v[218:221], v177 offset:22528
	ds_read_b128 v[222:225], v177 offset:23552
	global_load_lds_dwordx4 v[170:171], off
	s_add_i32 m0, s51, 0x2000
	s_add_u32 s52, s22, 0x80000
	v_lshl_add_u64 v[182:183], s[22:23], 0, v[152:153]
	s_addc_u32 s53, s23, 0
	s_add_i32 s51, s43, s25
	global_load_lds_dwordx4 v[182:183], off
	v_lshl_add_u64 v[226:227], s[52:53], 0, v[156:157]
	s_mov_b32 m0, s51
	v_lshl_add_u64 v[228:229], s[26:27], 0, v[154:155]
	global_load_lds_dwordx4 v[226:227], off
	v_lshl_add_u64 v[226:227], s[52:53], 0, v[152:153]
	s_add_i32 m0, s51, 0x2000
	s_nop 0
	global_load_lds_dwordx4 v[226:227], off
	v_lshl_add_u64 v[226:227], s[26:27], 0, v[158:159]
	s_mov_b32 m0, s30
	s_nop 0
	global_load_lds_dwordx4 v[226:227], off
	s_mov_b32 m0, s31
	s_nop 0
	global_load_lds_dwordx4 v[228:229], off
	s_waitcnt vmcnt(8)
	s_waitcnt lgkmcnt(0)
	s_barrier
	s_setprio 1
	s_waitcnt lgkmcnt(0)
	v_mfma_f32_16x16x32_bf16 v[60:63], v[128:131], v[194:197], v[60:63]
	v_mfma_f32_16x16x32_bf16 v[52:55], v[136:139], v[194:197], v[52:55]
	v_mfma_f32_16x16x32_bf16 v[44:47], v[128:131], v[202:205], v[44:47]
	v_mfma_f32_16x16x32_bf16 v[36:39], v[136:139], v[202:205], v[36:39]
	v_mfma_f32_16x16x32_bf16 v[28:31], v[128:131], v[210:213], v[28:31]
	v_mfma_f32_16x16x32_bf16 v[20:23], v[136:139], v[210:213], v[20:23]
	v_mfma_f32_16x16x32_bf16 v[12:15], v[128:131], v[218:221], v[12:15]
	v_mfma_f32_16x16x32_bf16 v[4:7], v[136:139], v[218:221], v[4:7]
	v_mfma_f32_16x16x32_bf16 v[60:63], v[132:135], v[198:201], v[60:63]
	v_mfma_f32_16x16x32_bf16 v[52:55], v[140:143], v[198:201], v[52:55]
	v_mfma_f32_16x16x32_bf16 v[44:47], v[132:135], v[206:209], v[44:47]
	v_mfma_f32_16x16x32_bf16 v[36:39], v[140:143], v[206:209], v[36:39]
	v_mfma_f32_16x16x32_bf16 v[28:31], v[132:135], v[214:217], v[28:31]
	v_mfma_f32_16x16x32_bf16 v[20:23], v[140:143], v[214:217], v[20:23]
	v_mfma_f32_16x16x32_bf16 v[12:15], v[132:135], v[222:225], v[12:15]
	v_mfma_f32_16x16x32_bf16 v[4:7], v[140:143], v[222:225], v[4:7]
	v_mfma_f32_16x16x32_bf16 v[56:59], v[144:147], v[194:197], v[56:59]
	v_mfma_f32_16x16x32_bf16 v[48:51], v[186:189], v[194:197], v[48:51]
	v_mfma_f32_16x16x32_bf16 v[40:43], v[144:147], v[202:205], v[40:43]
	v_mfma_f32_16x16x32_bf16 v[32:35], v[186:189], v[202:205], v[32:35]
	v_mfma_f32_16x16x32_bf16 v[24:27], v[144:147], v[210:213], v[24:27]
	v_mfma_f32_16x16x32_bf16 v[16:19], v[186:189], v[210:213], v[16:19]
	v_mfma_f32_16x16x32_bf16 v[8:11], v[144:147], v[218:221], v[8:11]
	v_mfma_f32_16x16x32_bf16 v[0:3], v[186:189], v[218:221], v[0:3]
	v_mfma_f32_16x16x32_bf16 v[56:59], v[148:151], v[198:201], v[56:59]
	v_mfma_f32_16x16x32_bf16 v[48:51], v[190:193], v[198:201], v[48:51]
	v_mfma_f32_16x16x32_bf16 v[40:43], v[148:151], v[206:209], v[40:43]
	v_mfma_f32_16x16x32_bf16 v[32:35], v[190:193], v[206:209], v[32:35]
	v_mfma_f32_16x16x32_bf16 v[24:27], v[148:151], v[214:217], v[24:27]
	v_mfma_f32_16x16x32_bf16 v[16:19], v[190:193], v[214:217], v[16:19]
	v_mfma_f32_16x16x32_bf16 v[8:11], v[148:151], v[222:225], v[8:11]
	v_mfma_f32_16x16x32_bf16 v[0:3], v[190:193], v[222:225], v[0:3]
	s_setprio 0
	s_barrier
	s_add_i32 s51, 0, 0x18000
	s_add_i32 s52, 0, 0x1c000
	v_add_u32_e32 v140, s51, v174
	v_add_u32_e32 v160, s52, v174
	ds_read_b128 v[128:131], v140
	ds_read_b128 v[132:135], v140 offset:1024
	ds_read_b128 v[136:139], v140 offset:2048
	ds_read_b128 v[140:143], v140 offset:3072
	ds_read_b128 v[144:147], v160
	ds_read_b128 v[148:151], v160 offset:1024
	ds_read_b128 v[186:189], v160 offset:2048
	ds_read_b128 v[190:193], v160 offset:3072
	s_add_u32 s26, s26, 0x80000
	s_addc_u32 s27, s27, 0
	s_mov_b32 m0, s33
	v_lshl_add_u64 v[230:231], s[26:27], 0, v[158:159]
	ds_read_b128 v[194:197], v177 offset:32768
	ds_read_b128 v[198:201], v177 offset:33792
	ds_read_b128 v[202:205], v177 offset:34816
	ds_read_b128 v[206:209], v177 offset:35840
	ds_read_b128 v[210:213], v177 offset:36864
	ds_read_b128 v[214:217], v177 offset:37888
	ds_read_b128 v[218:221], v177 offset:38912
	ds_read_b128 v[222:225], v177 offset:39936
	global_load_lds_dwordx4 v[230:231], off
	v_lshl_add_u64 v[230:231], s[26:27], 0, v[154:155]
	s_mov_b32 m0, s34
	s_nop 0
	global_load_lds_dwordx4 v[230:231], off
	s_waitcnt vmcnt(8)
	s_waitcnt lgkmcnt(0)
	s_barrier
	s_setprio 1
	s_waitcnt lgkmcnt(0)
	v_mfma_f32_16x16x32_bf16 v[124:127], v[128:131], v[194:197], v[124:127]
	v_mfma_f32_16x16x32_bf16 v[116:119], v[136:139], v[194:197], v[116:119]
	v_mfma_f32_16x16x32_bf16 v[108:111], v[128:131], v[202:205], v[108:111]
	v_mfma_f32_16x16x32_bf16 v[100:103], v[136:139], v[202:205], v[100:103]
	v_mfma_f32_16x16x32_bf16 v[92:95], v[128:131], v[210:213], v[92:95]
	v_mfma_f32_16x16x32_bf16 v[84:87], v[136:139], v[210:213], v[84:87]
	v_mfma_f32_16x16x32_bf16 v[76:79], v[128:131], v[218:221], v[76:79]
	v_mfma_f32_16x16x32_bf16 v[68:71], v[136:139], v[218:221], v[68:71]
	v_mfma_f32_16x16x32_bf16 v[124:127], v[132:135], v[198:201], v[124:127]
	v_mfma_f32_16x16x32_bf16 v[116:119], v[140:143], v[198:201], v[116:119]
	v_mfma_f32_16x16x32_bf16 v[108:111], v[132:135], v[206:209], v[108:111]
	v_mfma_f32_16x16x32_bf16 v[100:103], v[140:143], v[206:209], v[100:103]
	v_mfma_f32_16x16x32_bf16 v[92:95], v[132:135], v[214:217], v[92:95]
	v_mfma_f32_16x16x32_bf16 v[84:87], v[140:143], v[214:217], v[84:87]
	v_mfma_f32_16x16x32_bf16 v[76:79], v[132:135], v[222:225], v[76:79]
	v_mfma_f32_16x16x32_bf16 v[68:71], v[140:143], v[222:225], v[68:71]
	v_mfma_f32_16x16x32_bf16 v[120:123], v[144:147], v[194:197], v[120:123]
	v_mfma_f32_16x16x32_bf16 v[112:115], v[186:189], v[194:197], v[112:115]
	v_mfma_f32_16x16x32_bf16 v[104:107], v[144:147], v[202:205], v[104:107]
	v_mfma_f32_16x16x32_bf16 v[96:99], v[186:189], v[202:205], v[96:99]
	v_mfma_f32_16x16x32_bf16 v[88:91], v[144:147], v[210:213], v[88:91]
	v_mfma_f32_16x16x32_bf16 v[80:83], v[186:189], v[210:213], v[80:83]
	v_mfma_f32_16x16x32_bf16 v[72:75], v[144:147], v[218:221], v[72:75]
	v_mfma_f32_16x16x32_bf16 v[64:67], v[186:189], v[218:221], v[64:67]
	v_mfma_f32_16x16x32_bf16 v[120:123], v[148:151], v[198:201], v[120:123]
	v_mfma_f32_16x16x32_bf16 v[112:115], v[190:193], v[198:201], v[112:115]
	v_mfma_f32_16x16x32_bf16 v[104:107], v[148:151], v[206:209], v[104:107]
	v_mfma_f32_16x16x32_bf16 v[96:99], v[190:193], v[206:209], v[96:99]
	v_mfma_f32_16x16x32_bf16 v[88:91], v[148:151], v[214:217], v[88:91]
	v_mfma_f32_16x16x32_bf16 v[80:83], v[190:193], v[214:217], v[80:83]
	v_mfma_f32_16x16x32_bf16 v[72:75], v[148:151], v[222:225], v[72:75]
	v_mfma_f32_16x16x32_bf16 v[64:67], v[190:193], v[222:225], v[64:67]
	s_setprio 0
	s_barrier
	s_add_i32 s26, s51, s25
	v_lshl_add_u64 v[170:171], v[170:171], 0, s[10:11]
	s_mov_b32 m0, s26
	ds_read_b128 v[194:197], v177 offset:49152
	ds_read_b128 v[198:201], v177 offset:50176
	ds_read_b128 v[202:205], v177 offset:51200
	ds_read_b128 v[206:209], v177 offset:52224
	ds_read_b128 v[210:213], v177 offset:53248
	ds_read_b128 v[214:217], v177 offset:54272
	ds_read_b128 v[218:221], v177 offset:55296
	ds_read_b128 v[222:225], v177 offset:56320
	global_load_lds_dwordx4 v[170:171], off
	s_add_i32 m0, s26, 0x2000
	s_add_u32 s22, s22, 0x80080
	v_lshl_add_u64 v[170:171], v[182:183], 0, s[10:11]
	s_addc_u32 s23, s23, 0
	s_add_i32 s26, s52, s25
	global_load_lds_dwordx4 v[170:171], off
	v_lshl_add_u64 v[170:171], s[22:23], 0, v[156:157]
	s_mov_b32 m0, s26
	s_nop 0
	global_load_lds_dwordx4 v[170:171], off
	v_lshl_add_u64 v[170:171], s[22:23], 0, v[152:153]
	s_add_i32 m0, s26, 0x2000
	s_nop 0
	global_load_lds_dwordx4 v[170:171], off
	v_lshl_add_u64 v[170:171], v[226:227], 0, s[10:11]
	s_mov_b32 m0, s38
	s_nop 0
	global_load_lds_dwordx4 v[170:171], off
	v_lshl_add_u64 v[170:171], v[228:229], 0, s[10:11]
	s_mov_b32 m0, s39
	s_nop 0
	global_load_lds_dwordx4 v[170:171], off
	s_waitcnt vmcnt(8)
	s_waitcnt lgkmcnt(0)
	s_barrier
	s_setprio 1
	s_waitcnt lgkmcnt(0)
	v_mfma_f32_16x16x32_bf16 v[60:63], v[128:131], v[194:197], v[60:63]
	v_mfma_f32_16x16x32_bf16 v[52:55], v[136:139], v[194:197], v[52:55]
	v_mfma_f32_16x16x32_bf16 v[44:47], v[128:131], v[202:205], v[44:47]
	v_mfma_f32_16x16x32_bf16 v[36:39], v[136:139], v[202:205], v[36:39]
	v_mfma_f32_16x16x32_bf16 v[28:31], v[128:131], v[210:213], v[28:31]
	v_mfma_f32_16x16x32_bf16 v[20:23], v[136:139], v[210:213], v[20:23]
	v_mfma_f32_16x16x32_bf16 v[12:15], v[128:131], v[218:221], v[12:15]
	v_mfma_f32_16x16x32_bf16 v[4:7], v[136:139], v[218:221], v[4:7]
	v_mfma_f32_16x16x32_bf16 v[60:63], v[132:135], v[198:201], v[60:63]
	v_mfma_f32_16x16x32_bf16 v[52:55], v[140:143], v[198:201], v[52:55]
	v_mfma_f32_16x16x32_bf16 v[44:47], v[132:135], v[206:209], v[44:47]
	v_mfma_f32_16x16x32_bf16 v[36:39], v[140:143], v[206:209], v[36:39]
	v_mfma_f32_16x16x32_bf16 v[28:31], v[132:135], v[214:217], v[28:31]
	v_mfma_f32_16x16x32_bf16 v[20:23], v[140:143], v[214:217], v[20:23]
	v_mfma_f32_16x16x32_bf16 v[12:15], v[132:135], v[222:225], v[12:15]
	v_mfma_f32_16x16x32_bf16 v[4:7], v[140:143], v[222:225], v[4:7]
	v_mfma_f32_16x16x32_bf16 v[56:59], v[144:147], v[194:197], v[56:59]
	v_mfma_f32_16x16x32_bf16 v[48:51], v[186:189], v[194:197], v[48:51]
	v_mfma_f32_16x16x32_bf16 v[40:43], v[144:147], v[202:205], v[40:43]
	v_mfma_f32_16x16x32_bf16 v[32:35], v[186:189], v[202:205], v[32:35]
	v_mfma_f32_16x16x32_bf16 v[24:27], v[144:147], v[210:213], v[24:27]
	v_mfma_f32_16x16x32_bf16 v[16:19], v[186:189], v[210:213], v[16:19]
	v_mfma_f32_16x16x32_bf16 v[8:11], v[144:147], v[218:221], v[8:11]
	v_mfma_f32_16x16x32_bf16 v[0:3], v[186:189], v[218:221], v[0:3]
	v_mfma_f32_16x16x32_bf16 v[56:59], v[148:151], v[198:201], v[56:59]
	v_mfma_f32_16x16x32_bf16 v[48:51], v[190:193], v[198:201], v[48:51]
	v_mfma_f32_16x16x32_bf16 v[40:43], v[148:151], v[206:209], v[40:43]
	v_mfma_f32_16x16x32_bf16 v[32:35], v[190:193], v[206:209], v[32:35]
	v_mfma_f32_16x16x32_bf16 v[24:27], v[148:151], v[214:217], v[24:27]
	v_mfma_f32_16x16x32_bf16 v[16:19], v[190:193], v[214:217], v[16:19]
	v_mfma_f32_16x16x32_bf16 v[8:11], v[148:151], v[222:225], v[8:11]
	v_mfma_f32_16x16x32_bf16 v[0:3], v[190:193], v[222:225], v[0:3]
	s_setprio 0
	s_barrier
	s_add_i32 s50, s50, 2
	s_add_u32 s6, s6, 0x100
	s_addc_u32 s7, s7, 0
	s_add_u32 s48, s48, 0x100
	s_addc_u32 s49, s49, 0
	s_cmp_gt_u32 s50, 29
	s_cbranch_scc0 .LBB0_632
	s_and_b64 vcc, exec, s[12:13]
	s_cbranch_vccz .LBB0_635
	s_barrier

.LBB0_714:
	ds_read_b128 v[128:131], v177
	ds_read_b128 v[132:135], v177 offset:1024
	ds_read_b128 v[136:139], v177 offset:2048
	ds_read_b128 v[140:143], v177 offset:3072
	ds_read_b128 v[144:147], v178
	ds_read_b128 v[148:151], v178 offset:1024
	ds_read_b128 v[170:173], v178 offset:2048
	ds_read_b128 v[186:189], v178 offset:3072
	s_add_u32 s0, s16, 0x100
	s_addc_u32 s1, s17, 0
	s_cmpk_eq_i32 s46, 0x54
	s_cselect_b32 s21, s13, s1
	s_cselect_b32 s20, s12, s0
	s_cselect_b32 s19, s15, s45
	s_cselect_b32 s18, s14, s44
	v_lshl_add_u64 v[182:183], s[16:17], 0, v[162:163]
	s_add_i32 m0, s23, 0xc000
	ds_read_b128 v[190:193], v179
	ds_read_b128 v[194:197], v179 offset:1024
	ds_read_b128 v[198:201], v179 offset:2048
	ds_read_b128 v[202:205], v179 offset:3072
	ds_read_b128 v[206:209], v179 offset:4096
	ds_read_b128 v[210:213], v179 offset:5120
	ds_read_b128 v[214:217], v179 offset:6144
	ds_read_b128 v[218:221], v179 offset:7168
	global_load_lds_dwordx4 v[182:183], off
	v_lshl_add_u64 v[182:183], s[16:17], 0, v[164:165]
	s_add_i32 m0, s23, 0xe000
	s_nop 0
	global_load_lds_dwordx4 v[182:183], off
	s_waitcnt vmcnt(8)
	s_waitcnt lgkmcnt(0)
	s_barrier
	s_setprio 1
	s_waitcnt lgkmcnt(0)
	v_mfma_f32_16x16x32_bf16 v[124:127], v[128:131], v[190:193], v[124:127]
	v_mfma_f32_16x16x32_bf16 v[120:123], v[136:139], v[190:193], v[120:123]
	v_mfma_f32_16x16x32_bf16 v[108:111], v[128:131], v[198:201], v[108:111]
	v_mfma_f32_16x16x32_bf16 v[104:107], v[136:139], v[198:201], v[104:107]
	v_mfma_f32_16x16x32_bf16 v[92:95], v[128:131], v[206:209], v[92:95]
	v_mfma_f32_16x16x32_bf16 v[88:91], v[136:139], v[206:209], v[88:91]
	v_mfma_f32_16x16x32_bf16 v[76:79], v[128:131], v[214:217], v[76:79]
	v_mfma_f32_16x16x32_bf16 v[72:75], v[136:139], v[214:217], v[72:75]
	v_mfma_f32_16x16x32_bf16 v[124:127], v[132:135], v[194:197], v[124:127]
	v_mfma_f32_16x16x32_bf16 v[120:123], v[140:143], v[194:197], v[120:123]
	v_mfma_f32_16x16x32_bf16 v[108:111], v[132:135], v[202:205], v[108:111]
	v_mfma_f32_16x16x32_bf16 v[104:107], v[140:143], v[202:205], v[104:107]
	v_mfma_f32_16x16x32_bf16 v[92:95], v[132:135], v[210:213], v[92:95]
	v_mfma_f32_16x16x32_bf16 v[88:91], v[140:143], v[210:213], v[88:91]
	v_mfma_f32_16x16x32_bf16 v[76:79], v[132:135], v[218:221], v[76:79]
	v_mfma_f32_16x16x32_bf16 v[72:75], v[140:143], v[218:221], v[72:75]
	v_mfma_f32_16x16x32_bf16 v[116:119], v[144:147], v[190:193], v[116:119]
	v_mfma_f32_16x16x32_bf16 v[112:115], v[170:173], v[190:193], v[112:115]
	v_mfma_f32_16x16x32_bf16 v[100:103], v[144:147], v[198:201], v[100:103]
	v_mfma_f32_16x16x32_bf16 v[96:99], v[170:173], v[198:201], v[96:99]
	v_mfma_f32_16x16x32_bf16 v[84:87], v[144:147], v[206:209], v[84:87]
	v_mfma_f32_16x16x32_bf16 v[80:83], v[170:173], v[206:209], v[80:83]
	v_mfma_f32_16x16x32_bf16 v[68:71], v[144:147], v[214:217], v[68:71]
	v_mfma_f32_16x16x32_bf16 v[64:67], v[170:173], v[214:217], v[64:67]
	v_mfma_f32_16x16x32_bf16 v[116:119], v[148:151], v[194:197], v[116:119]
	v_mfma_f32_16x16x32_bf16 v[112:115], v[186:189], v[194:197], v[112:115]
	v_mfma_f32_16x16x32_bf16 v[100:103], v[148:151], v[202:205], v[100:103]
	v_mfma_f32_16x16x32_bf16 v[96:99], v[186:189], v[202:205], v[96:99]
	v_mfma_f32_16x16x32_bf16 v[84:87], v[148:151], v[210:213], v[84:87]
	v_mfma_f32_16x16x32_bf16 v[80:83], v[186:189], v[210:213], v[80:83]
	v_mfma_f32_16x16x32_bf16 v[68:71], v[148:151], v[218:221], v[68:71]
	v_mfma_f32_16x16x32_bf16 v[64:67], v[186:189], v[218:221], v[64:67]
	s_setprio 0
	s_barrier
	s_add_i32 s16, s38, s22
	v_lshl_add_u64 v[182:183], s[18:19], 0, v[154:155]
	s_mov_b32 m0, s16
	ds_read_b128 v[190:193], v179 offset:16384
	ds_read_b128 v[194:197], v179 offset:17408
	ds_read_b128 v[198:201], v179 offset:18432
	ds_read_b128 v[202:205], v179 offset:19456
	ds_read_b128 v[206:209], v179 offset:20480
	ds_read_b128 v[210:213], v179 offset:21504
	ds_read_b128 v[214:217], v179 offset:22528
	ds_read_b128 v[218:221], v179 offset:23552
	global_load_lds_dwordx4 v[182:183], off
	s_add_i32 m0, s16, 0x2000
	s_add_u32 s16, s18, 0x160000
	v_lshl_add_u64 v[222:223], s[18:19], 0, v[158:159]
	s_addc_u32 s17, s19, 0
	s_add_i32 s47, s39, s22
	global_load_lds_dwordx4 v[222:223], off
	v_lshl_add_u64 v[224:225], s[16:17], 0, v[154:155]
	s_mov_b32 m0, s47
	v_lshl_add_u64 v[226:227], s[20:21], 0, v[156:157]
	global_load_lds_dwordx4 v[224:225], off
	v_lshl_add_u64 v[224:225], s[16:17], 0, v[158:159]
	s_add_i32 m0, s47, 0x2000
	s_nop 0
	global_load_lds_dwordx4 v[224:225], off
	v_lshl_add_u64 v[224:225], s[20:21], 0, v[152:153]
	s_mov_b32 m0, s23
	s_nop 0
	global_load_lds_dwordx4 v[224:225], off
	s_mov_b32 m0, s25
	s_nop 0
	global_load_lds_dwordx4 v[226:227], off
	s_waitcnt vmcnt(8)
	s_waitcnt lgkmcnt(0)
	s_barrier
	s_setprio 1
	s_waitcnt lgkmcnt(0)
	v_mfma_f32_16x16x32_bf16 v[60:63], v[128:131], v[190:193], v[60:63]
	v_mfma_f32_16x16x32_bf16 v[56:59], v[136:139], v[190:193], v[56:59]
	v_mfma_f32_16x16x32_bf16 v[44:47], v[128:131], v[198:201], v[44:47]
	v_mfma_f32_16x16x32_bf16 v[40:43], v[136:139], v[198:201], v[40:43]
	v_mfma_f32_16x16x32_bf16 v[28:31], v[128:131], v[206:209], v[28:31]
	v_mfma_f32_16x16x32_bf16 v[24:27], v[136:139], v[206:209], v[24:27]
	v_mfma_f32_16x16x32_bf16 v[12:15], v[128:131], v[214:217], v[12:15]
	v_mfma_f32_16x16x32_bf16 v[8:11], v[136:139], v[214:217], v[8:11]
	v_mfma_f32_16x16x32_bf16 v[60:63], v[132:135], v[194:197], v[60:63]
	v_mfma_f32_16x16x32_bf16 v[56:59], v[140:143], v[194:197], v[56:59]
	v_mfma_f32_16x16x32_bf16 v[44:47], v[132:135], v[202:205], v[44:47]
	v_mfma_f32_16x16x32_bf16 v[40:43], v[140:143], v[202:205], v[40:43]
	v_mfma_f32_16x16x32_bf16 v[28:31], v[132:135], v[210:213], v[28:31]
	v_mfma_f32_16x16x32_bf16 v[24:27], v[140:143], v[210:213], v[24:27]
	v_mfma_f32_16x16x32_bf16 v[12:15], v[132:135], v[218:221], v[12:15]
	v_mfma_f32_16x16x32_bf16 v[8:11], v[140:143], v[218:221], v[8:11]
	v_mfma_f32_16x16x32_bf16 v[52:55], v[144:147], v[190:193], v[52:55]
	v_mfma_f32_16x16x32_bf16 v[48:51], v[170:173], v[190:193], v[48:51]
	v_mfma_f32_16x16x32_bf16 v[36:39], v[144:147], v[198:201], v[36:39]
	v_mfma_f32_16x16x32_bf16 v[32:35], v[170:173], v[198:201], v[32:35]
	v_mfma_f32_16x16x32_bf16 v[20:23], v[144:147], v[206:209], v[20:23]
	v_mfma_f32_16x16x32_bf16 v[16:19], v[170:173], v[206:209], v[16:19]
	v_mfma_f32_16x16x32_bf16 v[4:7], v[144:147], v[214:217], v[4:7]
	v_mfma_f32_16x16x32_bf16 v[0:3], v[170:173], v[214:217], v[0:3]
	v_mfma_f32_16x16x32_bf16 v[52:55], v[148:151], v[194:197], v[52:55]
	v_mfma_f32_16x16x32_bf16 v[48:51], v[186:189], v[194:197], v[48:51]
	v_mfma_f32_16x16x32_bf16 v[36:39], v[148:151], v[202:205], v[36:39]
	v_mfma_f32_16x16x32_bf16 v[32:35], v[186:189], v[202:205], v[32:35]
	v_mfma_f32_16x16x32_bf16 v[20:23], v[148:151], v[210:213], v[20:23]
	v_mfma_f32_16x16x32_bf16 v[16:19], v[186:189], v[210:213], v[16:19]
	v_mfma_f32_16x16x32_bf16 v[4:7], v[148:151], v[218:221], v[4:7]
	v_mfma_f32_16x16x32_bf16 v[0:3], v[186:189], v[218:221], v[0:3]
	s_setprio 0
	s_barrier
	s_add_i32 s47, 0, 0x18000
	s_add_i32 s48, 0, 0x1c000
	v_add_u32_e32 v140, s47, v176
	v_add_u32_e32 v160, s48, v176
	ds_read_b128 v[128:131], v140
	ds_read_b128 v[132:135], v140 offset:1024
	ds_read_b128 v[136:139], v140 offset:2048
	ds_read_b128 v[140:143], v140 offset:3072
	ds_read_b128 v[144:147], v160
	ds_read_b128 v[148:151], v160 offset:1024
	ds_read_b128 v[170:173], v160 offset:2048
	ds_read_b128 v[186:189], v160 offset:3072
	s_add_u32 s16, s20, 0x160000
	s_addc_u32 s17, s21, 0
	s_mov_b32 m0, s26
	v_lshl_add_u64 v[228:229], s[16:17], 0, v[152:153]
	ds_read_b128 v[190:193], v179 offset:32768
	ds_read_b128 v[194:197], v179 offset:33792
	ds_read_b128 v[198:201], v179 offset:34816
	ds_read_b128 v[202:205], v179 offset:35840
	ds_read_b128 v[206:209], v179 offset:36864
	ds_read_b128 v[210:213], v179 offset:37888
	ds_read_b128 v[214:217], v179 offset:38912
	ds_read_b128 v[218:221], v179 offset:39936
	global_load_lds_dwordx4 v[228:229], off
	v_lshl_add_u64 v[228:229], s[16:17], 0, v[156:157]
	s_mov_b32 m0, s27
	s_nop 0
	global_load_lds_dwordx4 v[228:229], off
	s_waitcnt vmcnt(8)
	s_waitcnt lgkmcnt(0)
	s_barrier
	s_setprio 1
	s_waitcnt lgkmcnt(0)
	v_mfma_f32_16x16x32_bf16 v[124:127], v[128:131], v[190:193], v[124:127]
	v_mfma_f32_16x16x32_bf16 v[120:123], v[136:139], v[190:193], v[120:123]
	v_mfma_f32_16x16x32_bf16 v[108:111], v[128:131], v[198:201], v[108:111]
	v_mfma_f32_16x16x32_bf16 v[104:107], v[136:139], v[198:201], v[104:107]
	v_mfma_f32_16x16x32_bf16 v[92:95], v[128:131], v[206:209], v[92:95]
	v_mfma_f32_16x16x32_bf16 v[88:91], v[136:139], v[206:209], v[88:91]
	v_mfma_f32_16x16x32_bf16 v[76:79], v[128:131], v[214:217], v[76:79]
	v_mfma_f32_16x16x32_bf16 v[72:75], v[136:139], v[214:217], v[72:75]
	v_mfma_f32_16x16x32_bf16 v[124:127], v[132:135], v[194:197], v[124:127]
	v_mfma_f32_16x16x32_bf16 v[120:123], v[140:143], v[194:197], v[120:123]
	v_mfma_f32_16x16x32_bf16 v[108:111], v[132:135], v[202:205], v[108:111]
	v_mfma_f32_16x16x32_bf16 v[104:107], v[140:143], v[202:205], v[104:107]
	v_mfma_f32_16x16x32_bf16 v[92:95], v[132:135], v[210:213], v[92:95]
	v_mfma_f32_16x16x32_bf16 v[88:91], v[140:143], v[210:213], v[88:91]
	v_mfma_f32_16x16x32_bf16 v[76:79], v[132:135], v[218:221], v[76:79]
	v_mfma_f32_16x16x32_bf16 v[72:75], v[140:143], v[218:221], v[72:75]
	v_mfma_f32_16x16x32_bf16 v[116:119], v[144:147], v[190:193], v[116:119]
	v_mfma_f32_16x16x32_bf16 v[112:115], v[170:173], v[190:193], v[112:115]
	v_mfma_f32_16x16x32_bf16 v[100:103], v[144:147], v[198:201], v[100:103]
	v_mfma_f32_16x16x32_bf16 v[96:99], v[170:173], v[198:201], v[96:99]
	v_mfma_f32_16x16x32_bf16 v[84:87], v[144:147], v[206:209], v[84:87]
	v_mfma_f32_16x16x32_bf16 v[80:83], v[170:173], v[206:209], v[80:83]
	v_mfma_f32_16x16x32_bf16 v[68:71], v[144:147], v[214:217], v[68:71]
	v_mfma_f32_16x16x32_bf16 v[64:67], v[170:173], v[214:217], v[64:67]
	v_mfma_f32_16x16x32_bf16 v[116:119], v[148:151], v[194:197], v[116:119]
	v_mfma_f32_16x16x32_bf16 v[112:115], v[186:189], v[194:197], v[112:115]
	v_mfma_f32_16x16x32_bf16 v[100:103], v[148:151], v[202:205], v[100:103]
	v_mfma_f32_16x16x32_bf16 v[96:99], v[186:189], v[202:205], v[96:99]
	v_mfma_f32_16x16x32_bf16 v[84:87], v[148:151], v[210:213], v[84:87]
	v_mfma_f32_16x16x32_bf16 v[80:83], v[186:189], v[210:213], v[80:83]
	v_mfma_f32_16x16x32_bf16 v[68:71], v[148:151], v[218:221], v[68:71]
	v_mfma_f32_16x16x32_bf16 v[64:67], v[186:189], v[218:221], v[64:67]
	s_setprio 0
	s_barrier
	s_add_i32 s16, s47, s22
	v_lshl_add_u64 v[182:183], v[182:183], 0, s[8:9]
	s_mov_b32 m0, s16
	ds_read_b128 v[190:193], v179 offset:49152
	ds_read_b128 v[194:197], v179 offset:50176
	ds_read_b128 v[198:201], v179 offset:51200
	ds_read_b128 v[202:205], v179 offset:52224
	ds_read_b128 v[206:209], v179 offset:53248
	ds_read_b128 v[210:213], v179 offset:54272
	ds_read_b128 v[214:217], v179 offset:55296
	ds_read_b128 v[218:221], v179 offset:56320
	global_load_lds_dwordx4 v[182:183], off
	s_add_i32 m0, s16, 0x2000
	s_add_u32 s16, s18, 0x160080
	v_lshl_add_u64 v[182:183], v[222:223], 0, s[8:9]
	s_addc_u32 s17, s19, 0
	s_add_i32 s18, s48, s22
	global_load_lds_dwordx4 v[182:183], off
	v_lshl_add_u64 v[182:183], s[16:17], 0, v[154:155]
	s_mov_b32 m0, s18
	s_nop 0
	global_load_lds_dwordx4 v[182:183], off
	v_lshl_add_u64 v[182:183], s[16:17], 0, v[158:159]
	s_add_i32 m0, s18, 0x2000
	s_nop 0
	global_load_lds_dwordx4 v[182:183], off
	v_lshl_add_u64 v[182:183], v[224:225], 0, s[8:9]
	s_mov_b32 m0, s33
	s_nop 0
	global_load_lds_dwordx4 v[182:183], off
	v_lshl_add_u64 v[182:183], v[226:227], 0, s[8:9]
	s_mov_b32 m0, s34
	s_nop 0
	global_load_lds_dwordx4 v[182:183], off
	s_waitcnt vmcnt(8)
	s_waitcnt lgkmcnt(0)
	s_barrier
	s_setprio 1
	s_waitcnt lgkmcnt(0)
	v_mfma_f32_16x16x32_bf16 v[60:63], v[128:131], v[190:193], v[60:63]
	v_mfma_f32_16x16x32_bf16 v[56:59], v[136:139], v[190:193], v[56:59]
	v_mfma_f32_16x16x32_bf16 v[44:47], v[128:131], v[198:201], v[44:47]
	v_mfma_f32_16x16x32_bf16 v[40:43], v[136:139], v[198:201], v[40:43]
	v_mfma_f32_16x16x32_bf16 v[28:31], v[128:131], v[206:209], v[28:31]
	v_mfma_f32_16x16x32_bf16 v[24:27], v[136:139], v[206:209], v[24:27]
	v_mfma_f32_16x16x32_bf16 v[12:15], v[128:131], v[214:217], v[12:15]
	v_mfma_f32_16x16x32_bf16 v[8:11], v[136:139], v[214:217], v[8:11]
	v_mfma_f32_16x16x32_bf16 v[60:63], v[132:135], v[194:197], v[60:63]
	v_mfma_f32_16x16x32_bf16 v[56:59], v[140:143], v[194:197], v[56:59]
	v_mfma_f32_16x16x32_bf16 v[44:47], v[132:135], v[202:205], v[44:47]
	v_mfma_f32_16x16x32_bf16 v[40:43], v[140:143], v[202:205], v[40:43]
	v_mfma_f32_16x16x32_bf16 v[28:31], v[132:135], v[210:213], v[28:31]
	v_mfma_f32_16x16x32_bf16 v[24:27], v[140:143], v[210:213], v[24:27]
	v_mfma_f32_16x16x32_bf16 v[12:15], v[132:135], v[218:221], v[12:15]
	v_mfma_f32_16x16x32_bf16 v[8:11], v[140:143], v[218:221], v[8:11]
	v_mfma_f32_16x16x32_bf16 v[52:55], v[144:147], v[190:193], v[52:55]
	v_mfma_f32_16x16x32_bf16 v[48:51], v[170:173], v[190:193], v[48:51]
	v_mfma_f32_16x16x32_bf16 v[36:39], v[144:147], v[198:201], v[36:39]
	v_mfma_f32_16x16x32_bf16 v[32:35], v[170:173], v[198:201], v[32:35]
	v_mfma_f32_16x16x32_bf16 v[20:23], v[144:147], v[206:209], v[20:23]
	v_mfma_f32_16x16x32_bf16 v[16:19], v[170:173], v[206:209], v[16:19]
	v_mfma_f32_16x16x32_bf16 v[4:7], v[144:147], v[214:217], v[4:7]
	v_mfma_f32_16x16x32_bf16 v[0:3], v[170:173], v[214:217], v[0:3]
	v_mfma_f32_16x16x32_bf16 v[52:55], v[148:151], v[194:197], v[52:55]
	v_mfma_f32_16x16x32_bf16 v[48:51], v[186:189], v[194:197], v[48:51]
	v_mfma_f32_16x16x32_bf16 v[36:39], v[148:151], v[202:205], v[36:39]
	v_mfma_f32_16x16x32_bf16 v[32:35], v[186:189], v[202:205], v[32:35]
	v_mfma_f32_16x16x32_bf16 v[20:23], v[148:151], v[210:213], v[20:23]
	v_mfma_f32_16x16x32_bf16 v[16:19], v[186:189], v[210:213], v[16:19]
	v_mfma_f32_16x16x32_bf16 v[4:7], v[148:151], v[218:221], v[4:7]
	v_mfma_f32_16x16x32_bf16 v[0:3], v[186:189], v[218:221], v[0:3]
	s_setprio 0
	s_barrier
	s_add_i32 s46, s46, 2
	s_add_u32 s44, s44, 0x100
	s_addc_u32 s45, s45, 0
	s_cmpk_gt_u32 s46, 0x55
	s_mov_b64 s[16:17], s[0:1]
	s_cbranch_scc0 .LBB0_714
	s_and_b64 vcc, exec, s[10:11]
	s_cbranch_vccz .LBB0_717
	s_barrier

.LBB0_800:
	ds_read_b128 v[158:161], v152
	ds_read_b128 v[162:165], v152 offset:1024
	ds_read_b128 v[166:169], v152 offset:2048
	ds_read_b128 v[170:173], v152 offset:3072
	ds_read_b128 v[174:177], v153
	ds_read_b128 v[178:181], v153 offset:1024
	ds_read_b128 v[186:189], v153 offset:2048
	ds_read_b128 v[190:193], v153 offset:3072
	s_add_u32 s28, s26, 0xfff80080
	s_addc_u32 s29, s27, -1
	s_cmp_eq_u32 s53, 28
	s_cselect_b32 s31, s1, s29
	s_cselect_b32 s30, s17, s28
	s_cselect_b32 s29, s15, s52
	s_cselect_b32 s28, s50, s51
	v_lshl_add_u64 v[146:147], s[26:27], 0, v[138:139]
	s_add_i32 m0, s23, 0xc000
	ds_read_b128 v[194:197], v154
	ds_read_b128 v[198:201], v154 offset:1024
	ds_read_b128 v[202:205], v154 offset:2048
	ds_read_b128 v[206:209], v154 offset:3072
	ds_read_b128 v[210:213], v154 offset:4096
	ds_read_b128 v[214:217], v154 offset:5120
	ds_read_b128 v[218:221], v154 offset:6144
	ds_read_b128 v[222:225], v154 offset:7168
	global_load_lds_dwordx4 v[146:147], off
	v_lshl_add_u64 v[146:147], s[26:27], 0, v[140:141]
	s_add_i32 m0, s23, 0xe000
	s_nop 0
	global_load_lds_dwordx4 v[146:147], off
	s_waitcnt vmcnt(8)
	s_waitcnt lgkmcnt(0)
	s_barrier
	s_setprio 1
	s_waitcnt lgkmcnt(0)
	v_mfma_f32_16x16x32_bf16 v[124:127], v[158:161], v[194:197], v[124:127]
	v_mfma_f32_16x16x32_bf16 v[120:123], v[166:169], v[194:197], v[120:123]
	v_mfma_f32_16x16x32_bf16 v[108:111], v[158:161], v[202:205], v[108:111]
	v_mfma_f32_16x16x32_bf16 v[104:107], v[166:169], v[202:205], v[104:107]
	v_mfma_f32_16x16x32_bf16 v[92:95], v[158:161], v[210:213], v[92:95]
	v_mfma_f32_16x16x32_bf16 v[88:91], v[166:169], v[210:213], v[88:91]
	v_mfma_f32_16x16x32_bf16 v[76:79], v[158:161], v[218:221], v[76:79]
	v_mfma_f32_16x16x32_bf16 v[72:75], v[166:169], v[218:221], v[72:75]
	v_mfma_f32_16x16x32_bf16 v[124:127], v[162:165], v[198:201], v[124:127]
	v_mfma_f32_16x16x32_bf16 v[120:123], v[170:173], v[198:201], v[120:123]
	v_mfma_f32_16x16x32_bf16 v[108:111], v[162:165], v[206:209], v[108:111]
	v_mfma_f32_16x16x32_bf16 v[104:107], v[170:173], v[206:209], v[104:107]
	v_mfma_f32_16x16x32_bf16 v[92:95], v[162:165], v[214:217], v[92:95]
	v_mfma_f32_16x16x32_bf16 v[88:91], v[170:173], v[214:217], v[88:91]
	v_mfma_f32_16x16x32_bf16 v[76:79], v[162:165], v[222:225], v[76:79]
	v_mfma_f32_16x16x32_bf16 v[72:75], v[170:173], v[222:225], v[72:75]
	v_mfma_f32_16x16x32_bf16 v[116:119], v[174:177], v[194:197], v[116:119]
	v_mfma_f32_16x16x32_bf16 v[112:115], v[186:189], v[194:197], v[112:115]
	v_mfma_f32_16x16x32_bf16 v[100:103], v[174:177], v[202:205], v[100:103]
	v_mfma_f32_16x16x32_bf16 v[96:99], v[186:189], v[202:205], v[96:99]
	v_mfma_f32_16x16x32_bf16 v[84:87], v[174:177], v[210:213], v[84:87]
	v_mfma_f32_16x16x32_bf16 v[80:83], v[186:189], v[210:213], v[80:83]
	v_mfma_f32_16x16x32_bf16 v[68:71], v[174:177], v[218:221], v[68:71]
	v_mfma_f32_16x16x32_bf16 v[64:67], v[186:189], v[218:221], v[64:67]
	v_mfma_f32_16x16x32_bf16 v[116:119], v[178:181], v[198:201], v[116:119]
	v_mfma_f32_16x16x32_bf16 v[112:115], v[190:193], v[198:201], v[112:115]
	v_mfma_f32_16x16x32_bf16 v[100:103], v[178:181], v[206:209], v[100:103]
	v_mfma_f32_16x16x32_bf16 v[96:99], v[190:193], v[206:209], v[96:99]
	v_mfma_f32_16x16x32_bf16 v[84:87], v[178:181], v[214:217], v[84:87]
	v_mfma_f32_16x16x32_bf16 v[80:83], v[190:193], v[214:217], v[80:83]
	v_mfma_f32_16x16x32_bf16 v[68:71], v[178:181], v[222:225], v[68:71]
	v_mfma_f32_16x16x32_bf16 v[64:67], v[190:193], v[222:225], v[64:67]
	s_setprio 0
	s_barrier
	s_add_i32 s54, s46, s33
	v_lshl_add_u64 v[146:147], s[28:29], 0, v[130:131]
	s_mov_b32 m0, s54
	ds_read_b128 v[194:197], v154 offset:16384
	ds_read_b128 v[198:201], v154 offset:17408
	ds_read_b128 v[202:205], v154 offset:18432
	ds_read_b128 v[206:209], v154 offset:19456
	ds_read_b128 v[210:213], v154 offset:20480
	ds_read_b128 v[214:217], v154 offset:21504
	ds_read_b128 v[218:221], v154 offset:22528
	ds_read_b128 v[222:225], v154 offset:23552
	global_load_lds_dwordx4 v[146:147], off
	s_add_i32 m0, s54, 0x2000
	s_add_u32 s54, s28, 0x80000
	v_lshl_add_u64 v[182:183], s[28:29], 0, v[134:135]
	s_addc_u32 s55, s29, 0
	s_add_i32 s56, s47, s33
	global_load_lds_dwordx4 v[182:183], off
	v_lshl_add_u64 v[226:227], s[54:55], 0, v[130:131]
	s_mov_b32 m0, s56
	v_lshl_add_u64 v[228:229], s[30:31], 0, v[132:133]
	global_load_lds_dwordx4 v[226:227], off
	v_lshl_add_u64 v[226:227], s[54:55], 0, v[134:135]
	s_add_i32 m0, s56, 0x2000
	s_nop 0
	global_load_lds_dwordx4 v[226:227], off
	v_lshl_add_u64 v[226:227], s[30:31], 0, v[128:129]
	s_mov_b32 m0, s23
	s_nop 0
	global_load_lds_dwordx4 v[226:227], off
	s_mov_b32 m0, s34
	s_nop 0
	global_load_lds_dwordx4 v[228:229], off
	s_waitcnt vmcnt(8)
	s_waitcnt lgkmcnt(0)
	s_barrier
	s_setprio 1
	s_waitcnt lgkmcnt(0)
	v_mfma_f32_16x16x32_bf16 v[60:63], v[158:161], v[194:197], v[60:63]
	v_mfma_f32_16x16x32_bf16 v[56:59], v[166:169], v[194:197], v[56:59]
	v_mfma_f32_16x16x32_bf16 v[44:47], v[158:161], v[202:205], v[44:47]
	v_mfma_f32_16x16x32_bf16 v[40:43], v[166:169], v[202:205], v[40:43]
	v_mfma_f32_16x16x32_bf16 v[28:31], v[158:161], v[210:213], v[28:31]
	v_mfma_f32_16x16x32_bf16 v[24:27], v[166:169], v[210:213], v[24:27]
	v_mfma_f32_16x16x32_bf16 v[12:15], v[158:161], v[218:221], v[12:15]
	v_mfma_f32_16x16x32_bf16 v[8:11], v[166:169], v[218:221], v[8:11]
	v_mfma_f32_16x16x32_bf16 v[60:63], v[162:165], v[198:201], v[60:63]
	v_mfma_f32_16x16x32_bf16 v[56:59], v[170:173], v[198:201], v[56:59]
	v_mfma_f32_16x16x32_bf16 v[44:47], v[162:165], v[206:209], v[44:47]
	v_mfma_f32_16x16x32_bf16 v[40:43], v[170:173], v[206:209], v[40:43]
	v_mfma_f32_16x16x32_bf16 v[28:31], v[162:165], v[214:217], v[28:31]
	v_mfma_f32_16x16x32_bf16 v[24:27], v[170:173], v[214:217], v[24:27]
	v_mfma_f32_16x16x32_bf16 v[12:15], v[162:165], v[222:225], v[12:15]
	v_mfma_f32_16x16x32_bf16 v[8:11], v[170:173], v[222:225], v[8:11]
	v_mfma_f32_16x16x32_bf16 v[52:55], v[174:177], v[194:197], v[52:55]
	v_mfma_f32_16x16x32_bf16 v[48:51], v[186:189], v[194:197], v[48:51]
	v_mfma_f32_16x16x32_bf16 v[36:39], v[174:177], v[202:205], v[36:39]
	v_mfma_f32_16x16x32_bf16 v[32:35], v[186:189], v[202:205], v[32:35]
	v_mfma_f32_16x16x32_bf16 v[20:23], v[174:177], v[210:213], v[20:23]
	v_mfma_f32_16x16x32_bf16 v[16:19], v[186:189], v[210:213], v[16:19]
	v_mfma_f32_16x16x32_bf16 v[4:7], v[174:177], v[218:221], v[4:7]
	v_mfma_f32_16x16x32_bf16 v[0:3], v[186:189], v[218:221], v[0:3]
	v_mfma_f32_16x16x32_bf16 v[52:55], v[178:181], v[198:201], v[52:55]
	v_mfma_f32_16x16x32_bf16 v[48:51], v[190:193], v[198:201], v[48:51]
	v_mfma_f32_16x16x32_bf16 v[36:39], v[178:181], v[206:209], v[36:39]
	v_mfma_f32_16x16x32_bf16 v[32:35], v[190:193], v[206:209], v[32:35]
	v_mfma_f32_16x16x32_bf16 v[20:23], v[178:181], v[214:217], v[20:23]
	v_mfma_f32_16x16x32_bf16 v[16:19], v[190:193], v[214:217], v[16:19]
	v_mfma_f32_16x16x32_bf16 v[4:7], v[178:181], v[222:225], v[4:7]
	v_mfma_f32_16x16x32_bf16 v[0:3], v[190:193], v[222:225], v[0:3]
	s_setprio 0
	s_barrier
	s_add_i32 s54, 0, 0x18000
	v_add_u32_e32 v136, s54, v151
	s_add_i32 s55, 0, 0x1c000
	ds_read_b128 v[158:161], v136
	ds_read_b128 v[162:165], v136 offset:1024
	ds_read_b128 v[166:169], v136 offset:2048
	ds_read_b128 v[170:173], v136 offset:3072
	v_add_u32_e32 v136, s55, v151
	ds_read_b128 v[174:177], v136
	ds_read_b128 v[178:181], v136 offset:1024
	ds_read_b128 v[186:189], v136 offset:2048
	ds_read_b128 v[190:193], v136 offset:3072
	s_add_u32 s30, s30, 0x80000
	s_addc_u32 s31, s31, 0
	s_mov_b32 m0, s35
	v_lshl_add_u64 v[230:231], s[30:31], 0, v[128:129]
	ds_read_b128 v[194:197], v154 offset:32768
	ds_read_b128 v[198:201], v154 offset:33792
	ds_read_b128 v[202:205], v154 offset:34816
	ds_read_b128 v[206:209], v154 offset:35840
	ds_read_b128 v[210:213], v154 offset:36864
	ds_read_b128 v[214:217], v154 offset:37888
	ds_read_b128 v[218:221], v154 offset:38912
	ds_read_b128 v[222:225], v154 offset:39936
	global_load_lds_dwordx4 v[230:231], off
	v_lshl_add_u64 v[230:231], s[30:31], 0, v[132:133]
	s_mov_b32 m0, s36
	s_nop 0
	global_load_lds_dwordx4 v[230:231], off
	s_waitcnt vmcnt(8)
	s_waitcnt lgkmcnt(0)
	s_barrier
	s_setprio 1
	s_waitcnt lgkmcnt(0)
	v_mfma_f32_16x16x32_bf16 v[124:127], v[158:161], v[194:197], v[124:127]
	v_mfma_f32_16x16x32_bf16 v[120:123], v[166:169], v[194:197], v[120:123]
	v_mfma_f32_16x16x32_bf16 v[108:111], v[158:161], v[202:205], v[108:111]
	v_mfma_f32_16x16x32_bf16 v[104:107], v[166:169], v[202:205], v[104:107]
	v_mfma_f32_16x16x32_bf16 v[92:95], v[158:161], v[210:213], v[92:95]
	v_mfma_f32_16x16x32_bf16 v[88:91], v[166:169], v[210:213], v[88:91]
	v_mfma_f32_16x16x32_bf16 v[76:79], v[158:161], v[218:221], v[76:79]
	v_mfma_f32_16x16x32_bf16 v[72:75], v[166:169], v[218:221], v[72:75]
	v_mfma_f32_16x16x32_bf16 v[124:127], v[162:165], v[198:201], v[124:127]
	v_mfma_f32_16x16x32_bf16 v[120:123], v[170:173], v[198:201], v[120:123]
	v_mfma_f32_16x16x32_bf16 v[108:111], v[162:165], v[206:209], v[108:111]
	v_mfma_f32_16x16x32_bf16 v[104:107], v[170:173], v[206:209], v[104:107]
	v_mfma_f32_16x16x32_bf16 v[92:95], v[162:165], v[214:217], v[92:95]
	v_mfma_f32_16x16x32_bf16 v[88:91], v[170:173], v[214:217], v[88:91]
	v_mfma_f32_16x16x32_bf16 v[76:79], v[162:165], v[222:225], v[76:79]
	v_mfma_f32_16x16x32_bf16 v[72:75], v[170:173], v[222:225], v[72:75]
	v_mfma_f32_16x16x32_bf16 v[116:119], v[174:177], v[194:197], v[116:119]
	v_mfma_f32_16x16x32_bf16 v[112:115], v[186:189], v[194:197], v[112:115]
	v_mfma_f32_16x16x32_bf16 v[100:103], v[174:177], v[202:205], v[100:103]
	v_mfma_f32_16x16x32_bf16 v[96:99], v[186:189], v[202:205], v[96:99]
	v_mfma_f32_16x16x32_bf16 v[84:87], v[174:177], v[210:213], v[84:87]
	v_mfma_f32_16x16x32_bf16 v[80:83], v[186:189], v[210:213], v[80:83]
	v_mfma_f32_16x16x32_bf16 v[68:71], v[174:177], v[218:221], v[68:71]
	v_mfma_f32_16x16x32_bf16 v[64:67], v[186:189], v[218:221], v[64:67]
	v_mfma_f32_16x16x32_bf16 v[116:119], v[178:181], v[198:201], v[116:119]
	v_mfma_f32_16x16x32_bf16 v[112:115], v[190:193], v[198:201], v[112:115]
	v_mfma_f32_16x16x32_bf16 v[100:103], v[178:181], v[206:209], v[100:103]
	v_mfma_f32_16x16x32_bf16 v[96:99], v[190:193], v[206:209], v[96:99]
	v_mfma_f32_16x16x32_bf16 v[84:87], v[178:181], v[214:217], v[84:87]
	v_mfma_f32_16x16x32_bf16 v[80:83], v[190:193], v[214:217], v[80:83]
	v_mfma_f32_16x16x32_bf16 v[68:71], v[178:181], v[222:225], v[68:71]
	v_mfma_f32_16x16x32_bf16 v[64:67], v[190:193], v[222:225], v[64:67]
	s_setprio 0
	s_barrier
	s_add_i32 s30, s54, s33
	v_lshl_add_u64 v[146:147], v[146:147], 0, s[10:11]
	s_mov_b32 m0, s30
	ds_read_b128 v[194:197], v154 offset:49152
	ds_read_b128 v[198:201], v154 offset:50176
	ds_read_b128 v[202:205], v154 offset:51200
	ds_read_b128 v[206:209], v154 offset:52224
	ds_read_b128 v[210:213], v154 offset:53248
	ds_read_b128 v[214:217], v154 offset:54272
	ds_read_b128 v[218:221], v154 offset:55296
	ds_read_b128 v[222:225], v154 offset:56320
	global_load_lds_dwordx4 v[146:147], off
	s_add_i32 m0, s30, 0x2000
	s_add_u32 s28, s28, 0x80080
	v_lshl_add_u64 v[146:147], v[182:183], 0, s[10:11]
	s_addc_u32 s29, s29, 0
	s_add_i32 s30, s55, s33
	global_load_lds_dwordx4 v[146:147], off
	v_lshl_add_u64 v[146:147], s[28:29], 0, v[130:131]
	s_mov_b32 m0, s30
	s_nop 0
	global_load_lds_dwordx4 v[146:147], off
	v_lshl_add_u64 v[146:147], s[28:29], 0, v[134:135]
	s_add_i32 m0, s30, 0x2000
	s_nop 0
	global_load_lds_dwordx4 v[146:147], off
	v_lshl_add_u64 v[146:147], v[226:227], 0, s[10:11]
	s_mov_b32 m0, s41
	s_nop 0
	global_load_lds_dwordx4 v[146:147], off
	v_lshl_add_u64 v[146:147], v[228:229], 0, s[10:11]
	s_mov_b32 m0, s42
	s_nop 0
	global_load_lds_dwordx4 v[146:147], off
	s_waitcnt vmcnt(8)
	s_waitcnt lgkmcnt(0)
	s_barrier
	s_setprio 1
	s_waitcnt lgkmcnt(0)
	v_mfma_f32_16x16x32_bf16 v[60:63], v[158:161], v[194:197], v[60:63]
	v_mfma_f32_16x16x32_bf16 v[56:59], v[166:169], v[194:197], v[56:59]
	v_mfma_f32_16x16x32_bf16 v[44:47], v[158:161], v[202:205], v[44:47]
	v_mfma_f32_16x16x32_bf16 v[40:43], v[166:169], v[202:205], v[40:43]
	v_mfma_f32_16x16x32_bf16 v[28:31], v[158:161], v[210:213], v[28:31]
	v_mfma_f32_16x16x32_bf16 v[24:27], v[166:169], v[210:213], v[24:27]
	v_mfma_f32_16x16x32_bf16 v[12:15], v[158:161], v[218:221], v[12:15]
	v_mfma_f32_16x16x32_bf16 v[8:11], v[166:169], v[218:221], v[8:11]
	v_mfma_f32_16x16x32_bf16 v[60:63], v[162:165], v[198:201], v[60:63]
	v_mfma_f32_16x16x32_bf16 v[56:59], v[170:173], v[198:201], v[56:59]
	v_mfma_f32_16x16x32_bf16 v[44:47], v[162:165], v[206:209], v[44:47]
	v_mfma_f32_16x16x32_bf16 v[40:43], v[170:173], v[206:209], v[40:43]
	v_mfma_f32_16x16x32_bf16 v[28:31], v[162:165], v[214:217], v[28:31]
	v_mfma_f32_16x16x32_bf16 v[24:27], v[170:173], v[214:217], v[24:27]
	v_mfma_f32_16x16x32_bf16 v[12:15], v[162:165], v[222:225], v[12:15]
	v_mfma_f32_16x16x32_bf16 v[8:11], v[170:173], v[222:225], v[8:11]
	v_mfma_f32_16x16x32_bf16 v[52:55], v[174:177], v[194:197], v[52:55]
	v_mfma_f32_16x16x32_bf16 v[48:51], v[186:189], v[194:197], v[48:51]
	v_mfma_f32_16x16x32_bf16 v[36:39], v[174:177], v[202:205], v[36:39]
	v_mfma_f32_16x16x32_bf16 v[32:35], v[186:189], v[202:205], v[32:35]
	v_mfma_f32_16x16x32_bf16 v[20:23], v[174:177], v[210:213], v[20:23]
	v_mfma_f32_16x16x32_bf16 v[16:19], v[186:189], v[210:213], v[16:19]
	v_mfma_f32_16x16x32_bf16 v[4:7], v[174:177], v[218:221], v[4:7]
	v_mfma_f32_16x16x32_bf16 v[0:3], v[186:189], v[218:221], v[0:3]
	v_mfma_f32_16x16x32_bf16 v[52:55], v[178:181], v[198:201], v[52:55]
	v_mfma_f32_16x16x32_bf16 v[48:51], v[190:193], v[198:201], v[48:51]
	v_mfma_f32_16x16x32_bf16 v[36:39], v[178:181], v[206:209], v[36:39]
	v_mfma_f32_16x16x32_bf16 v[32:35], v[190:193], v[206:209], v[32:35]
	v_mfma_f32_16x16x32_bf16 v[20:23], v[178:181], v[214:217], v[20:23]
	v_mfma_f32_16x16x32_bf16 v[16:19], v[190:193], v[214:217], v[16:19]
	v_mfma_f32_16x16x32_bf16 v[4:7], v[178:181], v[222:225], v[4:7]
	v_mfma_f32_16x16x32_bf16 v[0:3], v[190:193], v[222:225], v[0:3]
	s_setprio 0
	s_barrier
	s_add_i32 s53, s53, 2
	s_add_u32 s26, s26, 0x100
	s_addc_u32 s27, s27, 0
	s_add_u32 s51, s51, 0x100
	s_addc_u32 s52, s52, 0
	s_cmp_gt_u32 s53, 29
	s_cbranch_scc0 .LBB0_800
	s_and_b64 vcc, exec, s[12:13]
	s_cbranch_vccz .LBB0_803
	s_barrier

.LBB0_896:
	ds_read_b128 v[104:107], v215
	ds_read_b128 v[108:111], v215 offset:1024
	ds_read_b128 v[124:127], v215 offset:2048
	ds_read_b128 v[132:135], v215 offset:3072
	ds_read_b128 v[144:147], v216
	ds_read_b128 v[148:151], v216 offset:1024
	ds_read_b128 v[152:155], v216 offset:2048
	ds_read_b128 v[156:159], v216 offset:3072
	s_add_u32 s0, s6, 0x100
	s_addc_u32 s1, s7, 0
	s_cmp_eq_u32 s37, 4
	s_cselect_b32 s31, s21, s1
	s_cselect_b32 s30, s20, s0
	s_cselect_b32 s29, s19, s36
	s_cselect_b32 s28, s27, s35
	v_lshl_add_u64 v[220:221], s[6:7], 0, v[196:197]
	s_add_i32 m0, s33, 0xc000
	ds_read_b128 v[160:163], v217
	ds_read_b128 v[164:167], v217 offset:1024
	ds_read_b128 v[168:171], v217 offset:2048
	ds_read_b128 v[172:175], v217 offset:3072
	ds_read_b128 v[176:179], v217 offset:4096
	ds_read_b128 v[180:183], v217 offset:5120
	ds_read_b128 v[204:207], v217 offset:6144
	ds_read_b128 v[208:211], v217 offset:7168
	global_load_lds_dwordx4 v[220:221], off
	v_lshl_add_u64 v[220:221], s[6:7], 0, v[198:199]
	s_add_i32 m0, s33, 0xe000
	s_nop 0
	global_load_lds_dwordx4 v[220:221], off
	s_waitcnt vmcnt(8)
	s_waitcnt lgkmcnt(0)
	s_barrier
	s_setprio 1
	s_waitcnt lgkmcnt(0)
	v_mfma_f32_16x16x32_bf16 v[140:143], v[104:107], v[160:163], v[140:143]
	v_mfma_f32_16x16x32_bf16 v[136:139], v[124:127], v[160:163], v[136:139]
	v_mfma_f32_16x16x32_bf16 v[116:119], v[104:107], v[168:171], v[116:119]
	v_mfma_f32_16x16x32_bf16 v[112:115], v[124:127], v[168:171], v[112:115]
	v_mfma_f32_16x16x32_bf16 v[92:95], v[104:107], v[176:179], v[92:95]
	v_mfma_f32_16x16x32_bf16 v[88:91], v[124:127], v[176:179], v[88:91]
	v_mfma_f32_16x16x32_bf16 v[76:79], v[104:107], v[204:207], v[76:79]
	v_mfma_f32_16x16x32_bf16 v[72:75], v[124:127], v[204:207], v[72:75]
	v_mfma_f32_16x16x32_bf16 v[140:143], v[108:111], v[164:167], v[140:143]
	v_mfma_f32_16x16x32_bf16 v[136:139], v[132:135], v[164:167], v[136:139]
	v_mfma_f32_16x16x32_bf16 v[116:119], v[108:111], v[172:175], v[116:119]
	v_mfma_f32_16x16x32_bf16 v[112:115], v[132:135], v[172:175], v[112:115]
	v_mfma_f32_16x16x32_bf16 v[92:95], v[108:111], v[180:183], v[92:95]
	v_mfma_f32_16x16x32_bf16 v[88:91], v[132:135], v[180:183], v[88:91]
	v_mfma_f32_16x16x32_bf16 v[76:79], v[108:111], v[208:211], v[76:79]
	v_mfma_f32_16x16x32_bf16 v[72:75], v[132:135], v[208:211], v[72:75]
	v_mfma_f32_16x16x32_bf16 v[128:131], v[144:147], v[160:163], v[128:131]
	v_mfma_f32_16x16x32_bf16 v[120:123], v[152:155], v[160:163], v[120:123]
	v_mfma_f32_16x16x32_bf16 v[100:103], v[144:147], v[168:171], v[100:103]
	v_mfma_f32_16x16x32_bf16 v[96:99], v[152:155], v[168:171], v[96:99]
	v_mfma_f32_16x16x32_bf16 v[84:87], v[144:147], v[176:179], v[84:87]
	v_mfma_f32_16x16x32_bf16 v[80:83], v[152:155], v[176:179], v[80:83]
	v_mfma_f32_16x16x32_bf16 v[68:71], v[144:147], v[204:207], v[68:71]
	v_mfma_f32_16x16x32_bf16 v[64:67], v[152:155], v[204:207], v[64:67]
	v_mfma_f32_16x16x32_bf16 v[128:131], v[148:151], v[164:167], v[128:131]
	v_mfma_f32_16x16x32_bf16 v[120:123], v[156:159], v[164:167], v[120:123]
	v_mfma_f32_16x16x32_bf16 v[100:103], v[148:151], v[172:175], v[100:103]
	v_mfma_f32_16x16x32_bf16 v[96:99], v[156:159], v[172:175], v[96:99]
	v_mfma_f32_16x16x32_bf16 v[84:87], v[148:151], v[180:183], v[84:87]
	v_mfma_f32_16x16x32_bf16 v[80:83], v[156:159], v[180:183], v[80:83]
	v_mfma_f32_16x16x32_bf16 v[68:71], v[148:151], v[208:211], v[68:71]
	v_mfma_f32_16x16x32_bf16 v[64:67], v[156:159], v[208:211], v[64:67]
	s_setprio 0
	s_barrier
	s_add_i32 s6, s52, s25
	v_lshl_add_u64 v[220:221], s[28:29], 0, v[188:189]
	s_mov_b32 m0, s6
	ds_read_b128 v[160:163], v217 offset:16384
	ds_read_b128 v[164:167], v217 offset:17408
	ds_read_b128 v[168:171], v217 offset:18432
	ds_read_b128 v[172:175], v217 offset:19456
	ds_read_b128 v[176:179], v217 offset:20480
	ds_read_b128 v[180:183], v217 offset:21504
	ds_read_b128 v[204:207], v217 offset:22528
	ds_read_b128 v[208:211], v217 offset:23552
	global_load_lds_dwordx4 v[220:221], off
	s_add_i32 m0, s6, 0x2000
	s_add_u32 s6, s28, 0x20000
	v_lshl_add_u64 v[222:223], s[28:29], 0, v[192:193]
	s_addc_u32 s7, s29, 0
	s_add_i32 s38, s53, s25
	global_load_lds_dwordx4 v[222:223], off
	v_lshl_add_u64 v[224:225], s[6:7], 0, v[188:189]
	s_mov_b32 m0, s38
	v_lshl_add_u64 v[226:227], s[30:31], 0, v[190:191]
	global_load_lds_dwordx4 v[224:225], off
	v_lshl_add_u64 v[224:225], s[6:7], 0, v[192:193]
	s_add_i32 m0, s38, 0x2000
	s_nop 0
	global_load_lds_dwordx4 v[224:225], off
	v_lshl_add_u64 v[224:225], s[30:31], 0, v[186:187]
	s_mov_b32 m0, s33
	s_nop 0
	global_load_lds_dwordx4 v[224:225], off
	s_mov_b32 m0, s40
	s_nop 0
	global_load_lds_dwordx4 v[226:227], off
	s_waitcnt vmcnt(8)
	s_waitcnt lgkmcnt(0)
	s_barrier
	s_setprio 1
	s_waitcnt lgkmcnt(0)
	v_mfma_f32_16x16x32_bf16 v[60:63], v[104:107], v[160:163], v[60:63]
	v_mfma_f32_16x16x32_bf16 v[56:59], v[124:127], v[160:163], v[56:59]
	v_mfma_f32_16x16x32_bf16 v[44:47], v[104:107], v[168:171], v[44:47]
	v_mfma_f32_16x16x32_bf16 v[40:43], v[124:127], v[168:171], v[40:43]
	v_mfma_f32_16x16x32_bf16 v[28:31], v[104:107], v[176:179], v[28:31]
	v_mfma_f32_16x16x32_bf16 v[24:27], v[124:127], v[176:179], v[24:27]
	v_mfma_f32_16x16x32_bf16 v[12:15], v[104:107], v[204:207], v[12:15]
	v_mfma_f32_16x16x32_bf16 v[8:11], v[124:127], v[204:207], v[8:11]
	v_mfma_f32_16x16x32_bf16 v[60:63], v[108:111], v[164:167], v[60:63]
	v_mfma_f32_16x16x32_bf16 v[56:59], v[132:135], v[164:167], v[56:59]
	v_mfma_f32_16x16x32_bf16 v[44:47], v[108:111], v[172:175], v[44:47]
	v_mfma_f32_16x16x32_bf16 v[40:43], v[132:135], v[172:175], v[40:43]
	v_mfma_f32_16x16x32_bf16 v[28:31], v[108:111], v[180:183], v[28:31]
	v_mfma_f32_16x16x32_bf16 v[24:27], v[132:135], v[180:183], v[24:27]
	v_mfma_f32_16x16x32_bf16 v[12:15], v[108:111], v[208:211], v[12:15]
	v_mfma_f32_16x16x32_bf16 v[8:11], v[132:135], v[208:211], v[8:11]
	v_mfma_f32_16x16x32_bf16 v[52:55], v[144:147], v[160:163], v[52:55]
	v_mfma_f32_16x16x32_bf16 v[48:51], v[152:155], v[160:163], v[48:51]
	v_mfma_f32_16x16x32_bf16 v[36:39], v[144:147], v[168:171], v[36:39]
	v_mfma_f32_16x16x32_bf16 v[32:35], v[152:155], v[168:171], v[32:35]
	v_mfma_f32_16x16x32_bf16 v[20:23], v[144:147], v[176:179], v[20:23]
	v_mfma_f32_16x16x32_bf16 v[16:19], v[152:155], v[176:179], v[16:19]
	v_mfma_f32_16x16x32_bf16 v[4:7], v[144:147], v[204:207], v[4:7]
	v_mfma_f32_16x16x32_bf16 v[0:3], v[152:155], v[204:207], v[0:3]
	v_mfma_f32_16x16x32_bf16 v[52:55], v[148:151], v[164:167], v[52:55]
	v_mfma_f32_16x16x32_bf16 v[48:51], v[156:159], v[164:167], v[48:51]
	v_mfma_f32_16x16x32_bf16 v[36:39], v[148:151], v[172:175], v[36:39]
	v_mfma_f32_16x16x32_bf16 v[32:35], v[156:159], v[172:175], v[32:35]
	v_mfma_f32_16x16x32_bf16 v[20:23], v[148:151], v[180:183], v[20:23]
	v_mfma_f32_16x16x32_bf16 v[16:19], v[156:159], v[180:183], v[16:19]
	v_mfma_f32_16x16x32_bf16 v[4:7], v[148:151], v[208:211], v[4:7]
	v_mfma_f32_16x16x32_bf16 v[0:3], v[156:159], v[208:211], v[0:3]
	s_setprio 0
	s_barrier
	s_add_i32 s38, 0, 0x18000
	s_add_i32 s39, 0, 0x1c000
	v_add_u32_e32 v132, s38, v214
	v_add_u32_e32 v156, s39, v214
	ds_read_b128 v[104:107], v132
	ds_read_b128 v[108:111], v132 offset:1024
	ds_read_b128 v[124:127], v132 offset:2048
	ds_read_b128 v[132:135], v132 offset:3072
	ds_read_b128 v[144:147], v156
	ds_read_b128 v[148:151], v156 offset:1024
	ds_read_b128 v[152:155], v156 offset:2048
	ds_read_b128 v[156:159], v156 offset:3072
	s_add_u32 s6, s30, 0x50000
	s_addc_u32 s7, s31, 0
	s_mov_b32 m0, s41
	v_lshl_add_u64 v[228:229], s[6:7], 0, v[186:187]
	ds_read_b128 v[160:163], v217 offset:32768
	ds_read_b128 v[164:167], v217 offset:33792
	ds_read_b128 v[168:171], v217 offset:34816
	ds_read_b128 v[172:175], v217 offset:35840
	ds_read_b128 v[176:179], v217 offset:36864
	ds_read_b128 v[180:183], v217 offset:37888
	ds_read_b128 v[204:207], v217 offset:38912
	ds_read_b128 v[208:211], v217 offset:39936
	global_load_lds_dwordx4 v[228:229], off
	v_lshl_add_u64 v[228:229], s[6:7], 0, v[190:191]
	s_mov_b32 m0, s42
	s_nop 0
	global_load_lds_dwordx4 v[228:229], off
	s_waitcnt vmcnt(8)
	s_waitcnt lgkmcnt(0)
	s_barrier
	s_setprio 1
	s_waitcnt lgkmcnt(0)
	v_mfma_f32_16x16x32_bf16 v[140:143], v[104:107], v[160:163], v[140:143]
	v_mfma_f32_16x16x32_bf16 v[136:139], v[124:127], v[160:163], v[136:139]
	v_mfma_f32_16x16x32_bf16 v[116:119], v[104:107], v[168:171], v[116:119]
	v_mfma_f32_16x16x32_bf16 v[112:115], v[124:127], v[168:171], v[112:115]
	v_mfma_f32_16x16x32_bf16 v[92:95], v[104:107], v[176:179], v[92:95]
	v_mfma_f32_16x16x32_bf16 v[88:91], v[124:127], v[176:179], v[88:91]
	v_mfma_f32_16x16x32_bf16 v[76:79], v[104:107], v[204:207], v[76:79]
	v_mfma_f32_16x16x32_bf16 v[72:75], v[124:127], v[204:207], v[72:75]
	v_mfma_f32_16x16x32_bf16 v[140:143], v[108:111], v[164:167], v[140:143]
	v_mfma_f32_16x16x32_bf16 v[136:139], v[132:135], v[164:167], v[136:139]
	v_mfma_f32_16x16x32_bf16 v[116:119], v[108:111], v[172:175], v[116:119]
	v_mfma_f32_16x16x32_bf16 v[112:115], v[132:135], v[172:175], v[112:115]
	v_mfma_f32_16x16x32_bf16 v[92:95], v[108:111], v[180:183], v[92:95]
	v_mfma_f32_16x16x32_bf16 v[88:91], v[132:135], v[180:183], v[88:91]
	v_mfma_f32_16x16x32_bf16 v[76:79], v[108:111], v[208:211], v[76:79]
	v_mfma_f32_16x16x32_bf16 v[72:75], v[132:135], v[208:211], v[72:75]
	v_mfma_f32_16x16x32_bf16 v[128:131], v[144:147], v[160:163], v[128:131]
	v_mfma_f32_16x16x32_bf16 v[120:123], v[152:155], v[160:163], v[120:123]
	v_mfma_f32_16x16x32_bf16 v[100:103], v[144:147], v[168:171], v[100:103]
	v_mfma_f32_16x16x32_bf16 v[96:99], v[152:155], v[168:171], v[96:99]
	v_mfma_f32_16x16x32_bf16 v[84:87], v[144:147], v[176:179], v[84:87]
	v_mfma_f32_16x16x32_bf16 v[80:83], v[152:155], v[176:179], v[80:83]
	v_mfma_f32_16x16x32_bf16 v[68:71], v[144:147], v[204:207], v[68:71]
	v_mfma_f32_16x16x32_bf16 v[64:67], v[152:155], v[204:207], v[64:67]
	v_mfma_f32_16x16x32_bf16 v[128:131], v[148:151], v[164:167], v[128:131]
	v_mfma_f32_16x16x32_bf16 v[120:123], v[156:159], v[164:167], v[120:123]
	v_mfma_f32_16x16x32_bf16 v[100:103], v[148:151], v[172:175], v[100:103]
	v_mfma_f32_16x16x32_bf16 v[96:99], v[156:159], v[172:175], v[96:99]
	v_mfma_f32_16x16x32_bf16 v[84:87], v[148:151], v[180:183], v[84:87]
	v_mfma_f32_16x16x32_bf16 v[80:83], v[156:159], v[180:183], v[80:83]
	v_mfma_f32_16x16x32_bf16 v[68:71], v[148:151], v[208:211], v[68:71]
	v_mfma_f32_16x16x32_bf16 v[64:67], v[156:159], v[208:211], v[64:67]
	s_setprio 0
	s_barrier
	s_add_i32 s6, s38, s25
	v_lshl_add_u64 v[220:221], v[220:221], 0, s[12:13]
	s_mov_b32 m0, s6
	ds_read_b128 v[160:163], v217 offset:49152
	ds_read_b128 v[164:167], v217 offset:50176
	ds_read_b128 v[168:171], v217 offset:51200
	ds_read_b128 v[172:175], v217 offset:52224
	ds_read_b128 v[176:179], v217 offset:53248
	ds_read_b128 v[180:183], v217 offset:54272
	ds_read_b128 v[204:207], v217 offset:55296
	ds_read_b128 v[208:211], v217 offset:56320
	global_load_lds_dwordx4 v[220:221], off
	s_add_i32 m0, s6, 0x2000
	s_add_u32 s6, s28, 0x20080
	v_lshl_add_u64 v[220:221], v[222:223], 0, s[12:13]
	s_addc_u32 s7, s29, 0
	s_add_i32 s28, s39, s25
	global_load_lds_dwordx4 v[220:221], off
	v_lshl_add_u64 v[220:221], s[6:7], 0, v[188:189]
	s_mov_b32 m0, s28
	s_nop 0
	global_load_lds_dwordx4 v[220:221], off
	v_lshl_add_u64 v[220:221], s[6:7], 0, v[192:193]
	s_add_i32 m0, s28, 0x2000
	s_nop 0
	global_load_lds_dwordx4 v[220:221], off
	v_lshl_add_u64 v[220:221], v[224:225], 0, s[12:13]
	s_mov_b32 m0, s46
	s_nop 0
	global_load_lds_dwordx4 v[220:221], off
	v_lshl_add_u64 v[220:221], v[226:227], 0, s[12:13]
	s_mov_b32 m0, s47
	s_nop 0
	global_load_lds_dwordx4 v[220:221], off
	s_waitcnt vmcnt(8)
	s_waitcnt lgkmcnt(0)
	s_barrier
	s_setprio 1
	s_waitcnt lgkmcnt(0)
	v_mfma_f32_16x16x32_bf16 v[60:63], v[104:107], v[160:163], v[60:63]
	v_mfma_f32_16x16x32_bf16 v[56:59], v[124:127], v[160:163], v[56:59]
	v_mfma_f32_16x16x32_bf16 v[44:47], v[104:107], v[168:171], v[44:47]
	v_mfma_f32_16x16x32_bf16 v[40:43], v[124:127], v[168:171], v[40:43]
	v_mfma_f32_16x16x32_bf16 v[28:31], v[104:107], v[176:179], v[28:31]
	v_mfma_f32_16x16x32_bf16 v[24:27], v[124:127], v[176:179], v[24:27]
	v_mfma_f32_16x16x32_bf16 v[12:15], v[104:107], v[204:207], v[12:15]
	v_mfma_f32_16x16x32_bf16 v[8:11], v[124:127], v[204:207], v[8:11]
	v_mfma_f32_16x16x32_bf16 v[60:63], v[108:111], v[164:167], v[60:63]
	v_mfma_f32_16x16x32_bf16 v[56:59], v[132:135], v[164:167], v[56:59]
	v_mfma_f32_16x16x32_bf16 v[44:47], v[108:111], v[172:175], v[44:47]
	v_mfma_f32_16x16x32_bf16 v[40:43], v[132:135], v[172:175], v[40:43]
	v_mfma_f32_16x16x32_bf16 v[28:31], v[108:111], v[180:183], v[28:31]
	v_mfma_f32_16x16x32_bf16 v[24:27], v[132:135], v[180:183], v[24:27]
	v_mfma_f32_16x16x32_bf16 v[12:15], v[108:111], v[208:211], v[12:15]
	v_mfma_f32_16x16x32_bf16 v[8:11], v[132:135], v[208:211], v[8:11]
	v_mfma_f32_16x16x32_bf16 v[52:55], v[144:147], v[160:163], v[52:55]
	v_mfma_f32_16x16x32_bf16 v[48:51], v[152:155], v[160:163], v[48:51]
	v_mfma_f32_16x16x32_bf16 v[36:39], v[144:147], v[168:171], v[36:39]
	v_mfma_f32_16x16x32_bf16 v[32:35], v[152:155], v[168:171], v[32:35]
	v_mfma_f32_16x16x32_bf16 v[20:23], v[144:147], v[176:179], v[20:23]
	v_mfma_f32_16x16x32_bf16 v[16:19], v[152:155], v[176:179], v[16:19]
	v_mfma_f32_16x16x32_bf16 v[4:7], v[144:147], v[204:207], v[4:7]
	v_mfma_f32_16x16x32_bf16 v[0:3], v[152:155], v[204:207], v[0:3]
	v_mfma_f32_16x16x32_bf16 v[52:55], v[148:151], v[164:167], v[52:55]
	v_mfma_f32_16x16x32_bf16 v[48:51], v[156:159], v[164:167], v[48:51]
	v_mfma_f32_16x16x32_bf16 v[36:39], v[148:151], v[172:175], v[36:39]
	v_mfma_f32_16x16x32_bf16 v[32:35], v[156:159], v[172:175], v[32:35]
	v_mfma_f32_16x16x32_bf16 v[20:23], v[148:151], v[180:183], v[20:23]
	v_mfma_f32_16x16x32_bf16 v[16:19], v[156:159], v[180:183], v[16:19]
	v_mfma_f32_16x16x32_bf16 v[4:7], v[148:151], v[208:211], v[4:7]
	v_mfma_f32_16x16x32_bf16 v[0:3], v[156:159], v[208:211], v[0:3]
	s_setprio 0
	s_barrier
	s_add_i32 s37, s37, 2
	s_add_u32 s35, s35, 0x100
	s_addc_u32 s36, s36, 0
	s_cmp_gt_u32 s37, 5
	s_mov_b64 s[6:7], s[0:1]
	s_cbranch_scc0 .LBB0_896
	s_and_b64 vcc, exec, s[14:15]
	s_cbranch_vccz .LBB0_899
	s_barrier

.LBB0_1280:
	ds_read_b128 v[128:131], v177
	ds_read_b128 v[132:135], v177 offset:1024
	ds_read_b128 v[136:139], v177 offset:2048
	ds_read_b128 v[140:143], v177 offset:3072
	ds_read_b128 v[144:147], v178
	ds_read_b128 v[148:151], v178 offset:1024
	ds_read_b128 v[170:173], v178 offset:2048
	ds_read_b128 v[186:189], v178 offset:3072
	s_add_u32 s24, s22, 0xfff80080
	s_addc_u32 s25, s23, -1
	s_cmp_eq_u32 s47, 28
	s_cselect_b32 s27, s1, s25
	s_cselect_b32 s26, s15, s24
	s_cselect_b32 s25, s13, s46
	s_cselect_b32 s24, s44, s45
	v_lshl_add_u64 v[182:183], s[22:23], 0, v[162:163]
	s_add_i32 m0, s21, 0xc000
	ds_read_b128 v[190:193], v179
	ds_read_b128 v[194:197], v179 offset:1024
	ds_read_b128 v[198:201], v179 offset:2048
	ds_read_b128 v[202:205], v179 offset:3072
	ds_read_b128 v[206:209], v179 offset:4096
	ds_read_b128 v[210:213], v179 offset:5120
	ds_read_b128 v[214:217], v179 offset:6144
	ds_read_b128 v[218:221], v179 offset:7168
	global_load_lds_dwordx4 v[182:183], off
	v_lshl_add_u64 v[182:183], s[22:23], 0, v[164:165]
	s_add_i32 m0, s21, 0xe000
	s_nop 0
	global_load_lds_dwordx4 v[182:183], off
	s_waitcnt vmcnt(8)
	s_waitcnt lgkmcnt(0)
	s_barrier
	s_setprio 1
	s_waitcnt lgkmcnt(0)
	v_mfma_f32_16x16x32_bf16 v[124:127], v[128:131], v[190:193], v[124:127]
	v_mfma_f32_16x16x32_bf16 v[120:123], v[136:139], v[190:193], v[120:123]
	v_mfma_f32_16x16x32_bf16 v[108:111], v[128:131], v[198:201], v[108:111]
	v_mfma_f32_16x16x32_bf16 v[104:107], v[136:139], v[198:201], v[104:107]
	v_mfma_f32_16x16x32_bf16 v[92:95], v[128:131], v[206:209], v[92:95]
	v_mfma_f32_16x16x32_bf16 v[88:91], v[136:139], v[206:209], v[88:91]
	v_mfma_f32_16x16x32_bf16 v[76:79], v[128:131], v[214:217], v[76:79]
	v_mfma_f32_16x16x32_bf16 v[72:75], v[136:139], v[214:217], v[72:75]
	v_mfma_f32_16x16x32_bf16 v[124:127], v[132:135], v[194:197], v[124:127]
	v_mfma_f32_16x16x32_bf16 v[120:123], v[140:143], v[194:197], v[120:123]
	v_mfma_f32_16x16x32_bf16 v[108:111], v[132:135], v[202:205], v[108:111]
	v_mfma_f32_16x16x32_bf16 v[104:107], v[140:143], v[202:205], v[104:107]
	v_mfma_f32_16x16x32_bf16 v[92:95], v[132:135], v[210:213], v[92:95]
	v_mfma_f32_16x16x32_bf16 v[88:91], v[140:143], v[210:213], v[88:91]
	v_mfma_f32_16x16x32_bf16 v[76:79], v[132:135], v[218:221], v[76:79]
	v_mfma_f32_16x16x32_bf16 v[72:75], v[140:143], v[218:221], v[72:75]
	v_mfma_f32_16x16x32_bf16 v[116:119], v[144:147], v[190:193], v[116:119]
	v_mfma_f32_16x16x32_bf16 v[112:115], v[170:173], v[190:193], v[112:115]
	v_mfma_f32_16x16x32_bf16 v[100:103], v[144:147], v[198:201], v[100:103]
	v_mfma_f32_16x16x32_bf16 v[96:99], v[170:173], v[198:201], v[96:99]
	v_mfma_f32_16x16x32_bf16 v[84:87], v[144:147], v[206:209], v[84:87]
	v_mfma_f32_16x16x32_bf16 v[80:83], v[170:173], v[206:209], v[80:83]
	v_mfma_f32_16x16x32_bf16 v[68:71], v[144:147], v[214:217], v[68:71]
	v_mfma_f32_16x16x32_bf16 v[64:67], v[170:173], v[214:217], v[64:67]
	v_mfma_f32_16x16x32_bf16 v[116:119], v[148:151], v[194:197], v[116:119]
	v_mfma_f32_16x16x32_bf16 v[112:115], v[186:189], v[194:197], v[112:115]
	v_mfma_f32_16x16x32_bf16 v[100:103], v[148:151], v[202:205], v[100:103]
	v_mfma_f32_16x16x32_bf16 v[96:99], v[186:189], v[202:205], v[96:99]
	v_mfma_f32_16x16x32_bf16 v[84:87], v[148:151], v[210:213], v[84:87]
	v_mfma_f32_16x16x32_bf16 v[80:83], v[186:189], v[210:213], v[80:83]
	v_mfma_f32_16x16x32_bf16 v[68:71], v[148:151], v[218:221], v[68:71]
	v_mfma_f32_16x16x32_bf16 v[64:67], v[186:189], v[218:221], v[64:67]
	s_setprio 0
	s_barrier
	s_add_i32 s48, s42, s28
	v_lshl_add_u64 v[182:183], s[24:25], 0, v[154:155]
	s_mov_b32 m0, s48
	ds_read_b128 v[190:193], v179 offset:16384
	ds_read_b128 v[194:197], v179 offset:17408
	ds_read_b128 v[198:201], v179 offset:18432
	ds_read_b128 v[202:205], v179 offset:19456
	ds_read_b128 v[206:209], v179 offset:20480
	ds_read_b128 v[210:213], v179 offset:21504
	ds_read_b128 v[214:217], v179 offset:22528
	ds_read_b128 v[218:221], v179 offset:23552
	global_load_lds_dwordx4 v[182:183], off
	s_add_i32 m0, s48, 0x2000
	s_add_u32 s48, s24, 0x80000
	v_lshl_add_u64 v[222:223], s[24:25], 0, v[158:159]
	s_addc_u32 s49, s25, 0
	s_add_i32 s50, s43, s28
	global_load_lds_dwordx4 v[222:223], off
	v_lshl_add_u64 v[224:225], s[48:49], 0, v[154:155]
	s_mov_b32 m0, s50
	v_lshl_add_u64 v[226:227], s[26:27], 0, v[156:157]
	global_load_lds_dwordx4 v[224:225], off
	v_lshl_add_u64 v[224:225], s[48:49], 0, v[158:159]
	s_add_i32 m0, s50, 0x2000
	s_nop 0
	global_load_lds_dwordx4 v[224:225], off
	v_lshl_add_u64 v[224:225], s[26:27], 0, v[152:153]
	s_mov_b32 m0, s21
	s_nop 0
	global_load_lds_dwordx4 v[224:225], off
	s_mov_b32 m0, s29
	s_nop 0
	global_load_lds_dwordx4 v[226:227], off
	s_waitcnt vmcnt(8)
	s_waitcnt lgkmcnt(0)
	s_barrier
	s_setprio 1
	s_waitcnt lgkmcnt(0)
	v_mfma_f32_16x16x32_bf16 v[60:63], v[128:131], v[190:193], v[60:63]
	v_mfma_f32_16x16x32_bf16 v[56:59], v[136:139], v[190:193], v[56:59]
	v_mfma_f32_16x16x32_bf16 v[44:47], v[128:131], v[198:201], v[44:47]
	v_mfma_f32_16x16x32_bf16 v[40:43], v[136:139], v[198:201], v[40:43]
	v_mfma_f32_16x16x32_bf16 v[28:31], v[128:131], v[206:209], v[28:31]
	v_mfma_f32_16x16x32_bf16 v[24:27], v[136:139], v[206:209], v[24:27]
	v_mfma_f32_16x16x32_bf16 v[12:15], v[128:131], v[214:217], v[12:15]
	v_mfma_f32_16x16x32_bf16 v[8:11], v[136:139], v[214:217], v[8:11]
	v_mfma_f32_16x16x32_bf16 v[60:63], v[132:135], v[194:197], v[60:63]
	v_mfma_f32_16x16x32_bf16 v[56:59], v[140:143], v[194:197], v[56:59]
	v_mfma_f32_16x16x32_bf16 v[44:47], v[132:135], v[202:205], v[44:47]
	v_mfma_f32_16x16x32_bf16 v[40:43], v[140:143], v[202:205], v[40:43]
	v_mfma_f32_16x16x32_bf16 v[28:31], v[132:135], v[210:213], v[28:31]
	v_mfma_f32_16x16x32_bf16 v[24:27], v[140:143], v[210:213], v[24:27]
	v_mfma_f32_16x16x32_bf16 v[12:15], v[132:135], v[218:221], v[12:15]
	v_mfma_f32_16x16x32_bf16 v[8:11], v[140:143], v[218:221], v[8:11]
	v_mfma_f32_16x16x32_bf16 v[52:55], v[144:147], v[190:193], v[52:55]
	v_mfma_f32_16x16x32_bf16 v[48:51], v[170:173], v[190:193], v[48:51]
	v_mfma_f32_16x16x32_bf16 v[36:39], v[144:147], v[198:201], v[36:39]
	v_mfma_f32_16x16x32_bf16 v[32:35], v[170:173], v[198:201], v[32:35]
	v_mfma_f32_16x16x32_bf16 v[20:23], v[144:147], v[206:209], v[20:23]
	v_mfma_f32_16x16x32_bf16 v[16:19], v[170:173], v[206:209], v[16:19]
	v_mfma_f32_16x16x32_bf16 v[4:7], v[144:147], v[214:217], v[4:7]
	v_mfma_f32_16x16x32_bf16 v[0:3], v[170:173], v[214:217], v[0:3]
	v_mfma_f32_16x16x32_bf16 v[52:55], v[148:151], v[194:197], v[52:55]
	v_mfma_f32_16x16x32_bf16 v[48:51], v[186:189], v[194:197], v[48:51]
	v_mfma_f32_16x16x32_bf16 v[36:39], v[148:151], v[202:205], v[36:39]
	v_mfma_f32_16x16x32_bf16 v[32:35], v[186:189], v[202:205], v[32:35]
	v_mfma_f32_16x16x32_bf16 v[20:23], v[148:151], v[210:213], v[20:23]
	v_mfma_f32_16x16x32_bf16 v[16:19], v[186:189], v[210:213], v[16:19]
	v_mfma_f32_16x16x32_bf16 v[4:7], v[148:151], v[218:221], v[4:7]
	v_mfma_f32_16x16x32_bf16 v[0:3], v[186:189], v[218:221], v[0:3]
	s_setprio 0
	s_barrier
	s_add_i32 s48, 0, 0x18000
	s_add_i32 s49, 0, 0x1c000
	v_add_u32_e32 v140, s48, v176
	v_add_u32_e32 v160, s49, v176
	ds_read_b128 v[128:131], v140
	ds_read_b128 v[132:135], v140 offset:1024
	ds_read_b128 v[136:139], v140 offset:2048
	ds_read_b128 v[140:143], v140 offset:3072
	ds_read_b128 v[144:147], v160
	ds_read_b128 v[148:151], v160 offset:1024
	ds_read_b128 v[170:173], v160 offset:2048
	ds_read_b128 v[186:189], v160 offset:3072
	s_add_u32 s26, s26, 0x80000
	s_addc_u32 s27, s27, 0
	s_mov_b32 m0, s30
	v_lshl_add_u64 v[228:229], s[26:27], 0, v[152:153]
	ds_read_b128 v[190:193], v179 offset:32768
	ds_read_b128 v[194:197], v179 offset:33792
	ds_read_b128 v[198:201], v179 offset:34816
	ds_read_b128 v[202:205], v179 offset:35840
	ds_read_b128 v[206:209], v179 offset:36864
	ds_read_b128 v[210:213], v179 offset:37888
	ds_read_b128 v[214:217], v179 offset:38912
	ds_read_b128 v[218:221], v179 offset:39936
	global_load_lds_dwordx4 v[228:229], off
	v_lshl_add_u64 v[228:229], s[26:27], 0, v[156:157]
	s_mov_b32 m0, s31
	s_nop 0
	global_load_lds_dwordx4 v[228:229], off
	s_waitcnt vmcnt(8)
	s_waitcnt lgkmcnt(0)
	s_barrier
	s_setprio 1
	s_waitcnt lgkmcnt(0)
	v_mfma_f32_16x16x32_bf16 v[124:127], v[128:131], v[190:193], v[124:127]
	v_mfma_f32_16x16x32_bf16 v[120:123], v[136:139], v[190:193], v[120:123]
	v_mfma_f32_16x16x32_bf16 v[108:111], v[128:131], v[198:201], v[108:111]
	v_mfma_f32_16x16x32_bf16 v[104:107], v[136:139], v[198:201], v[104:107]
	v_mfma_f32_16x16x32_bf16 v[92:95], v[128:131], v[206:209], v[92:95]
	v_mfma_f32_16x16x32_bf16 v[88:91], v[136:139], v[206:209], v[88:91]
	v_mfma_f32_16x16x32_bf16 v[76:79], v[128:131], v[214:217], v[76:79]
	v_mfma_f32_16x16x32_bf16 v[72:75], v[136:139], v[214:217], v[72:75]
	v_mfma_f32_16x16x32_bf16 v[124:127], v[132:135], v[194:197], v[124:127]
	v_mfma_f32_16x16x32_bf16 v[120:123], v[140:143], v[194:197], v[120:123]
	v_mfma_f32_16x16x32_bf16 v[108:111], v[132:135], v[202:205], v[108:111]
	v_mfma_f32_16x16x32_bf16 v[104:107], v[140:143], v[202:205], v[104:107]
	v_mfma_f32_16x16x32_bf16 v[92:95], v[132:135], v[210:213], v[92:95]
	v_mfma_f32_16x16x32_bf16 v[88:91], v[140:143], v[210:213], v[88:91]
	v_mfma_f32_16x16x32_bf16 v[76:79], v[132:135], v[218:221], v[76:79]
	v_mfma_f32_16x16x32_bf16 v[72:75], v[140:143], v[218:221], v[72:75]
	v_mfma_f32_16x16x32_bf16 v[116:119], v[144:147], v[190:193], v[116:119]
	v_mfma_f32_16x16x32_bf16 v[112:115], v[170:173], v[190:193], v[112:115]
	v_mfma_f32_16x16x32_bf16 v[100:103], v[144:147], v[198:201], v[100:103]
	v_mfma_f32_16x16x32_bf16 v[96:99], v[170:173], v[198:201], v[96:99]
	v_mfma_f32_16x16x32_bf16 v[84:87], v[144:147], v[206:209], v[84:87]
	v_mfma_f32_16x16x32_bf16 v[80:83], v[170:173], v[206:209], v[80:83]
	v_mfma_f32_16x16x32_bf16 v[68:71], v[144:147], v[214:217], v[68:71]
	v_mfma_f32_16x16x32_bf16 v[64:67], v[170:173], v[214:217], v[64:67]
	v_mfma_f32_16x16x32_bf16 v[116:119], v[148:151], v[194:197], v[116:119]
	v_mfma_f32_16x16x32_bf16 v[112:115], v[186:189], v[194:197], v[112:115]
	v_mfma_f32_16x16x32_bf16 v[100:103], v[148:151], v[202:205], v[100:103]
	v_mfma_f32_16x16x32_bf16 v[96:99], v[186:189], v[202:205], v[96:99]
	v_mfma_f32_16x16x32_bf16 v[84:87], v[148:151], v[210:213], v[84:87]
	v_mfma_f32_16x16x32_bf16 v[80:83], v[186:189], v[210:213], v[80:83]
	v_mfma_f32_16x16x32_bf16 v[68:71], v[148:151], v[218:221], v[68:71]
	v_mfma_f32_16x16x32_bf16 v[64:67], v[186:189], v[218:221], v[64:67]
	s_setprio 0
	s_barrier
	s_add_i32 s26, s48, s28
	v_lshl_add_u64 v[182:183], v[182:183], 0, s[8:9]
	s_mov_b32 m0, s26
	ds_read_b128 v[190:193], v179 offset:49152
	ds_read_b128 v[194:197], v179 offset:50176
	ds_read_b128 v[198:201], v179 offset:51200
	ds_read_b128 v[202:205], v179 offset:52224
	ds_read_b128 v[206:209], v179 offset:53248
	ds_read_b128 v[210:213], v179 offset:54272
	ds_read_b128 v[214:217], v179 offset:55296
	ds_read_b128 v[218:221], v179 offset:56320
	global_load_lds_dwordx4 v[182:183], off
	s_add_i32 m0, s26, 0x2000
	s_add_u32 s24, s24, 0x80080
	v_lshl_add_u64 v[182:183], v[222:223], 0, s[8:9]
	s_addc_u32 s25, s25, 0
	s_add_i32 s26, s49, s28
	global_load_lds_dwordx4 v[182:183], off
	v_lshl_add_u64 v[182:183], s[24:25], 0, v[154:155]
	s_mov_b32 m0, s26
	s_nop 0
	global_load_lds_dwordx4 v[182:183], off
	v_lshl_add_u64 v[182:183], s[24:25], 0, v[158:159]
	s_add_i32 m0, s26, 0x2000
	s_nop 0
	global_load_lds_dwordx4 v[182:183], off
	v_lshl_add_u64 v[182:183], v[224:225], 0, s[8:9]
	s_mov_b32 m0, s37
	s_nop 0
	global_load_lds_dwordx4 v[182:183], off
	v_lshl_add_u64 v[182:183], v[226:227], 0, s[8:9]
	s_mov_b32 m0, s38
	s_nop 0
	global_load_lds_dwordx4 v[182:183], off
	s_waitcnt vmcnt(8)
	s_waitcnt lgkmcnt(0)
	s_barrier
	s_setprio 1
	s_waitcnt lgkmcnt(0)
	v_mfma_f32_16x16x32_bf16 v[60:63], v[128:131], v[190:193], v[60:63]
	v_mfma_f32_16x16x32_bf16 v[56:59], v[136:139], v[190:193], v[56:59]
	v_mfma_f32_16x16x32_bf16 v[44:47], v[128:131], v[198:201], v[44:47]
	v_mfma_f32_16x16x32_bf16 v[40:43], v[136:139], v[198:201], v[40:43]
	v_mfma_f32_16x16x32_bf16 v[28:31], v[128:131], v[206:209], v[28:31]
	v_mfma_f32_16x16x32_bf16 v[24:27], v[136:139], v[206:209], v[24:27]
	v_mfma_f32_16x16x32_bf16 v[12:15], v[128:131], v[214:217], v[12:15]
	v_mfma_f32_16x16x32_bf16 v[8:11], v[136:139], v[214:217], v[8:11]
	v_mfma_f32_16x16x32_bf16 v[60:63], v[132:135], v[194:197], v[60:63]
	v_mfma_f32_16x16x32_bf16 v[56:59], v[140:143], v[194:197], v[56:59]
	v_mfma_f32_16x16x32_bf16 v[44:47], v[132:135], v[202:205], v[44:47]
	v_mfma_f32_16x16x32_bf16 v[40:43], v[140:143], v[202:205], v[40:43]
	v_mfma_f32_16x16x32_bf16 v[28:31], v[132:135], v[210:213], v[28:31]
	v_mfma_f32_16x16x32_bf16 v[24:27], v[140:143], v[210:213], v[24:27]
	v_mfma_f32_16x16x32_bf16 v[12:15], v[132:135], v[218:221], v[12:15]
	v_mfma_f32_16x16x32_bf16 v[8:11], v[140:143], v[218:221], v[8:11]
	v_mfma_f32_16x16x32_bf16 v[52:55], v[144:147], v[190:193], v[52:55]
	v_mfma_f32_16x16x32_bf16 v[48:51], v[170:173], v[190:193], v[48:51]
	v_mfma_f32_16x16x32_bf16 v[36:39], v[144:147], v[198:201], v[36:39]
	v_mfma_f32_16x16x32_bf16 v[32:35], v[170:173], v[198:201], v[32:35]
	v_mfma_f32_16x16x32_bf16 v[20:23], v[144:147], v[206:209], v[20:23]
	v_mfma_f32_16x16x32_bf16 v[16:19], v[170:173], v[206:209], v[16:19]
	v_mfma_f32_16x16x32_bf16 v[4:7], v[144:147], v[214:217], v[4:7]
	v_mfma_f32_16x16x32_bf16 v[0:3], v[170:173], v[214:217], v[0:3]
	v_mfma_f32_16x16x32_bf16 v[52:55], v[148:151], v[194:197], v[52:55]
	v_mfma_f32_16x16x32_bf16 v[48:51], v[186:189], v[194:197], v[48:51]
	v_mfma_f32_16x16x32_bf16 v[36:39], v[148:151], v[202:205], v[36:39]
	v_mfma_f32_16x16x32_bf16 v[32:35], v[186:189], v[202:205], v[32:35]
	v_mfma_f32_16x16x32_bf16 v[20:23], v[148:151], v[210:213], v[20:23]
	v_mfma_f32_16x16x32_bf16 v[16:19], v[186:189], v[210:213], v[16:19]
	v_mfma_f32_16x16x32_bf16 v[4:7], v[148:151], v[218:221], v[4:7]
	v_mfma_f32_16x16x32_bf16 v[0:3], v[186:189], v[218:221], v[0:3]
	s_setprio 0
	s_barrier
	s_add_i32 s47, s47, 2
	s_add_u32 s22, s22, 0x100
	s_addc_u32 s23, s23, 0
	s_add_u32 s45, s45, 0x100
	s_addc_u32 s46, s46, 0
	s_cmp_gt_u32 s47, 29
	s_cbranch_scc0 .LBB0_1280
	s_and_b64 vcc, exec, s[10:11]
	s_cbranch_vccz .LBB0_1283
	s_barrier

.LBB0_1364:
	ds_read_b128 v[128:131], v175
	ds_read_b128 v[132:135], v175 offset:1024
	ds_read_b128 v[136:139], v175 offset:2048
	ds_read_b128 v[140:143], v175 offset:3072
	ds_read_b128 v[144:147], v176
	ds_read_b128 v[148:151], v176 offset:1024
	ds_read_b128 v[186:189], v176 offset:2048
	ds_read_b128 v[190:193], v176 offset:3072
	s_add_u32 s22, s6, 0xfff80080
	s_addc_u32 s23, s7, -1
	s_cmp_eq_u32 s49, 28
	s_cselect_b32 s25, s17, s23
	s_cselect_b32 s24, s45, s22
	s_cselect_b32 s23, s15, s48
	s_cselect_b32 s22, s46, s47
	v_lshl_add_u64 v[170:171], s[6:7], 0, v[162:163]
	s_add_i32 m0, s29, 0xc000
	ds_read_b128 v[194:197], v177
	ds_read_b128 v[198:201], v177 offset:1024
	ds_read_b128 v[202:205], v177 offset:2048
	ds_read_b128 v[206:209], v177 offset:3072
	ds_read_b128 v[210:213], v177 offset:4096
	ds_read_b128 v[214:217], v177 offset:5120
	ds_read_b128 v[218:221], v177 offset:6144
	ds_read_b128 v[222:225], v177 offset:7168
	global_load_lds_dwordx4 v[170:171], off
	v_lshl_add_u64 v[170:171], s[6:7], 0, v[164:165]
	s_add_i32 m0, s29, 0xe000
	s_nop 0
	global_load_lds_dwordx4 v[170:171], off
	s_waitcnt vmcnt(8)
	s_waitcnt lgkmcnt(0)
	s_barrier
	s_setprio 1
	s_waitcnt lgkmcnt(0)
	v_mfma_f32_16x16x32_bf16 v[124:127], v[128:131], v[194:197], v[124:127]
	v_mfma_f32_16x16x32_bf16 v[116:119], v[136:139], v[194:197], v[116:119]
	v_mfma_f32_16x16x32_bf16 v[108:111], v[128:131], v[202:205], v[108:111]
	v_mfma_f32_16x16x32_bf16 v[100:103], v[136:139], v[202:205], v[100:103]
	v_mfma_f32_16x16x32_bf16 v[92:95], v[128:131], v[210:213], v[92:95]
	v_mfma_f32_16x16x32_bf16 v[84:87], v[136:139], v[210:213], v[84:87]
	v_mfma_f32_16x16x32_bf16 v[76:79], v[128:131], v[218:221], v[76:79]
	v_mfma_f32_16x16x32_bf16 v[68:71], v[136:139], v[218:221], v[68:71]
	v_mfma_f32_16x16x32_bf16 v[124:127], v[132:135], v[198:201], v[124:127]
	v_mfma_f32_16x16x32_bf16 v[116:119], v[140:143], v[198:201], v[116:119]
	v_mfma_f32_16x16x32_bf16 v[108:111], v[132:135], v[206:209], v[108:111]
	v_mfma_f32_16x16x32_bf16 v[100:103], v[140:143], v[206:209], v[100:103]
	v_mfma_f32_16x16x32_bf16 v[92:95], v[132:135], v[214:217], v[92:95]
	v_mfma_f32_16x16x32_bf16 v[84:87], v[140:143], v[214:217], v[84:87]
	v_mfma_f32_16x16x32_bf16 v[76:79], v[132:135], v[222:225], v[76:79]
	v_mfma_f32_16x16x32_bf16 v[68:71], v[140:143], v[222:225], v[68:71]
	v_mfma_f32_16x16x32_bf16 v[120:123], v[144:147], v[194:197], v[120:123]
	v_mfma_f32_16x16x32_bf16 v[112:115], v[186:189], v[194:197], v[112:115]
	v_mfma_f32_16x16x32_bf16 v[104:107], v[144:147], v[202:205], v[104:107]
	v_mfma_f32_16x16x32_bf16 v[96:99], v[186:189], v[202:205], v[96:99]
	v_mfma_f32_16x16x32_bf16 v[88:91], v[144:147], v[210:213], v[88:91]
	v_mfma_f32_16x16x32_bf16 v[80:83], v[186:189], v[210:213], v[80:83]
	v_mfma_f32_16x16x32_bf16 v[72:75], v[144:147], v[218:221], v[72:75]
	v_mfma_f32_16x16x32_bf16 v[64:67], v[186:189], v[218:221], v[64:67]
	v_mfma_f32_16x16x32_bf16 v[120:123], v[148:151], v[198:201], v[120:123]
	v_mfma_f32_16x16x32_bf16 v[112:115], v[190:193], v[198:201], v[112:115]
	v_mfma_f32_16x16x32_bf16 v[104:107], v[148:151], v[206:209], v[104:107]
	v_mfma_f32_16x16x32_bf16 v[96:99], v[190:193], v[206:209], v[96:99]
	v_mfma_f32_16x16x32_bf16 v[88:91], v[148:151], v[214:217], v[88:91]
	v_mfma_f32_16x16x32_bf16 v[80:83], v[190:193], v[214:217], v[80:83]
	v_mfma_f32_16x16x32_bf16 v[72:75], v[148:151], v[222:225], v[72:75]
	v_mfma_f32_16x16x32_bf16 v[64:67], v[190:193], v[222:225], v[64:67]
	s_setprio 0
	s_barrier
	s_add_i32 s50, s41, s26
	v_lshl_add_u64 v[170:171], s[22:23], 0, v[156:157]
	s_mov_b32 m0, s50
	ds_read_b128 v[194:197], v177 offset:16384
	ds_read_b128 v[198:201], v177 offset:17408
	ds_read_b128 v[202:205], v177 offset:18432
	ds_read_b128 v[206:209], v177 offset:19456
	ds_read_b128 v[210:213], v177 offset:20480
	ds_read_b128 v[214:217], v177 offset:21504
	ds_read_b128 v[218:221], v177 offset:22528
	ds_read_b128 v[222:225], v177 offset:23552
	global_load_lds_dwordx4 v[170:171], off
	s_add_i32 m0, s50, 0x2000
	s_add_u32 s50, s22, 0x80000
	v_lshl_add_u64 v[182:183], s[22:23], 0, v[152:153]
	s_addc_u32 s51, s23, 0
	s_add_i32 s52, s42, s26
	global_load_lds_dwordx4 v[182:183], off
	v_lshl_add_u64 v[226:227], s[50:51], 0, v[156:157]
	s_mov_b32 m0, s52
	v_lshl_add_u64 v[228:229], s[24:25], 0, v[154:155]
	global_load_lds_dwordx4 v[226:227], off
	v_lshl_add_u64 v[226:227], s[50:51], 0, v[152:153]
	s_add_i32 m0, s52, 0x2000
	s_nop 0
	global_load_lds_dwordx4 v[226:227], off
	v_lshl_add_u64 v[226:227], s[24:25], 0, v[158:159]
	s_mov_b32 m0, s29
	s_nop 0
	global_load_lds_dwordx4 v[226:227], off
	s_mov_b32 m0, s30
	s_nop 0
	global_load_lds_dwordx4 v[228:229], off
	s_waitcnt vmcnt(8)
	s_waitcnt lgkmcnt(0)
	s_barrier
	s_setprio 1
	s_waitcnt lgkmcnt(0)
	v_mfma_f32_16x16x32_bf16 v[60:63], v[128:131], v[194:197], v[60:63]
	v_mfma_f32_16x16x32_bf16 v[52:55], v[136:139], v[194:197], v[52:55]
	v_mfma_f32_16x16x32_bf16 v[44:47], v[128:131], v[202:205], v[44:47]
	v_mfma_f32_16x16x32_bf16 v[36:39], v[136:139], v[202:205], v[36:39]
	v_mfma_f32_16x16x32_bf16 v[28:31], v[128:131], v[210:213], v[28:31]
	v_mfma_f32_16x16x32_bf16 v[20:23], v[136:139], v[210:213], v[20:23]
	v_mfma_f32_16x16x32_bf16 v[12:15], v[128:131], v[218:221], v[12:15]
	v_mfma_f32_16x16x32_bf16 v[4:7], v[136:139], v[218:221], v[4:7]
	v_mfma_f32_16x16x32_bf16 v[60:63], v[132:135], v[198:201], v[60:63]
	v_mfma_f32_16x16x32_bf16 v[52:55], v[140:143], v[198:201], v[52:55]
	v_mfma_f32_16x16x32_bf16 v[44:47], v[132:135], v[206:209], v[44:47]
	v_mfma_f32_16x16x32_bf16 v[36:39], v[140:143], v[206:209], v[36:39]
	v_mfma_f32_16x16x32_bf16 v[28:31], v[132:135], v[214:217], v[28:31]
	v_mfma_f32_16x16x32_bf16 v[20:23], v[140:143], v[214:217], v[20:23]
	v_mfma_f32_16x16x32_bf16 v[12:15], v[132:135], v[222:225], v[12:15]
	v_mfma_f32_16x16x32_bf16 v[4:7], v[140:143], v[222:225], v[4:7]
	v_mfma_f32_16x16x32_bf16 v[56:59], v[144:147], v[194:197], v[56:59]
	v_mfma_f32_16x16x32_bf16 v[48:51], v[186:189], v[194:197], v[48:51]
	v_mfma_f32_16x16x32_bf16 v[40:43], v[144:147], v[202:205], v[40:43]
	v_mfma_f32_16x16x32_bf16 v[32:35], v[186:189], v[202:205], v[32:35]
	v_mfma_f32_16x16x32_bf16 v[24:27], v[144:147], v[210:213], v[24:27]
	v_mfma_f32_16x16x32_bf16 v[16:19], v[186:189], v[210:213], v[16:19]
	v_mfma_f32_16x16x32_bf16 v[8:11], v[144:147], v[218:221], v[8:11]
	v_mfma_f32_16x16x32_bf16 v[0:3], v[186:189], v[218:221], v[0:3]
	v_mfma_f32_16x16x32_bf16 v[56:59], v[148:151], v[198:201], v[56:59]
	v_mfma_f32_16x16x32_bf16 v[48:51], v[190:193], v[198:201], v[48:51]
	v_mfma_f32_16x16x32_bf16 v[40:43], v[148:151], v[206:209], v[40:43]
	v_mfma_f32_16x16x32_bf16 v[32:35], v[190:193], v[206:209], v[32:35]
	v_mfma_f32_16x16x32_bf16 v[24:27], v[148:151], v[214:217], v[24:27]
	v_mfma_f32_16x16x32_bf16 v[16:19], v[190:193], v[214:217], v[16:19]
	v_mfma_f32_16x16x32_bf16 v[8:11], v[148:151], v[222:225], v[8:11]
	v_mfma_f32_16x16x32_bf16 v[0:3], v[190:193], v[222:225], v[0:3]
	s_setprio 0
	s_barrier
	s_add_i32 s50, 0, 0x18000
	s_add_i32 s51, 0, 0x1c000
	v_add_u32_e32 v140, s50, v174
	v_add_u32_e32 v160, s51, v174
	ds_read_b128 v[128:131], v140
	ds_read_b128 v[132:135], v140 offset:1024
	ds_read_b128 v[136:139], v140 offset:2048
	ds_read_b128 v[140:143], v140 offset:3072
	ds_read_b128 v[144:147], v160
	ds_read_b128 v[148:151], v160 offset:1024
	ds_read_b128 v[186:189], v160 offset:2048
	ds_read_b128 v[190:193], v160 offset:3072
	s_add_u32 s24, s24, 0x80000
	s_addc_u32 s25, s25, 0
	s_mov_b32 m0, s31
	v_lshl_add_u64 v[230:231], s[24:25], 0, v[158:159]
	ds_read_b128 v[194:197], v177 offset:32768
	ds_read_b128 v[198:201], v177 offset:33792
	ds_read_b128 v[202:205], v177 offset:34816
	ds_read_b128 v[206:209], v177 offset:35840
	ds_read_b128 v[210:213], v177 offset:36864
	ds_read_b128 v[214:217], v177 offset:37888
	ds_read_b128 v[218:221], v177 offset:38912
	ds_read_b128 v[222:225], v177 offset:39936
	global_load_lds_dwordx4 v[230:231], off
	v_lshl_add_u64 v[230:231], s[24:25], 0, v[154:155]
	s_mov_b32 m0, s33
	s_nop 0
	global_load_lds_dwordx4 v[230:231], off
	s_waitcnt vmcnt(8)
	s_waitcnt lgkmcnt(0)
	s_barrier
	s_setprio 1
	s_waitcnt lgkmcnt(0)
	v_mfma_f32_16x16x32_bf16 v[124:127], v[128:131], v[194:197], v[124:127]
	v_mfma_f32_16x16x32_bf16 v[116:119], v[136:139], v[194:197], v[116:119]
	v_mfma_f32_16x16x32_bf16 v[108:111], v[128:131], v[202:205], v[108:111]
	v_mfma_f32_16x16x32_bf16 v[100:103], v[136:139], v[202:205], v[100:103]
	v_mfma_f32_16x16x32_bf16 v[92:95], v[128:131], v[210:213], v[92:95]
	v_mfma_f32_16x16x32_bf16 v[84:87], v[136:139], v[210:213], v[84:87]
	v_mfma_f32_16x16x32_bf16 v[76:79], v[128:131], v[218:221], v[76:79]
	v_mfma_f32_16x16x32_bf16 v[68:71], v[136:139], v[218:221], v[68:71]
	v_mfma_f32_16x16x32_bf16 v[124:127], v[132:135], v[198:201], v[124:127]
	v_mfma_f32_16x16x32_bf16 v[116:119], v[140:143], v[198:201], v[116:119]
	v_mfma_f32_16x16x32_bf16 v[108:111], v[132:135], v[206:209], v[108:111]
	v_mfma_f32_16x16x32_bf16 v[100:103], v[140:143], v[206:209], v[100:103]
	v_mfma_f32_16x16x32_bf16 v[92:95], v[132:135], v[214:217], v[92:95]
	v_mfma_f32_16x16x32_bf16 v[84:87], v[140:143], v[214:217], v[84:87]
	v_mfma_f32_16x16x32_bf16 v[76:79], v[132:135], v[222:225], v[76:79]
	v_mfma_f32_16x16x32_bf16 v[68:71], v[140:143], v[222:225], v[68:71]
	v_mfma_f32_16x16x32_bf16 v[120:123], v[144:147], v[194:197], v[120:123]
	v_mfma_f32_16x16x32_bf16 v[112:115], v[186:189], v[194:197], v[112:115]
	v_mfma_f32_16x16x32_bf16 v[104:107], v[144:147], v[202:205], v[104:107]
	v_mfma_f32_16x16x32_bf16 v[96:99], v[186:189], v[202:205], v[96:99]
	v_mfma_f32_16x16x32_bf16 v[88:91], v[144:147], v[210:213], v[88:91]
	v_mfma_f32_16x16x32_bf16 v[80:83], v[186:189], v[210:213], v[80:83]
	v_mfma_f32_16x16x32_bf16 v[72:75], v[144:147], v[218:221], v[72:75]
	v_mfma_f32_16x16x32_bf16 v[64:67], v[186:189], v[218:221], v[64:67]
	v_mfma_f32_16x16x32_bf16 v[120:123], v[148:151], v[198:201], v[120:123]
	v_mfma_f32_16x16x32_bf16 v[112:115], v[190:193], v[198:201], v[112:115]
	v_mfma_f32_16x16x32_bf16 v[104:107], v[148:151], v[206:209], v[104:107]
	v_mfma_f32_16x16x32_bf16 v[96:99], v[190:193], v[206:209], v[96:99]
	v_mfma_f32_16x16x32_bf16 v[88:91], v[148:151], v[214:217], v[88:91]
	v_mfma_f32_16x16x32_bf16 v[80:83], v[190:193], v[214:217], v[80:83]
	v_mfma_f32_16x16x32_bf16 v[72:75], v[148:151], v[222:225], v[72:75]
	v_mfma_f32_16x16x32_bf16 v[64:67], v[190:193], v[222:225], v[64:67]
	s_setprio 0
	s_barrier
	s_add_i32 s24, s50, s26
	v_lshl_add_u64 v[170:171], v[170:171], 0, s[10:11]
	s_mov_b32 m0, s24
	ds_read_b128 v[194:197], v177 offset:49152
	ds_read_b128 v[198:201], v177 offset:50176
	ds_read_b128 v[202:205], v177 offset:51200
	ds_read_b128 v[206:209], v177 offset:52224
	ds_read_b128 v[210:213], v177 offset:53248
	ds_read_b128 v[214:217], v177 offset:54272
	ds_read_b128 v[218:221], v177 offset:55296
	ds_read_b128 v[222:225], v177 offset:56320
	global_load_lds_dwordx4 v[170:171], off
	s_add_i32 m0, s24, 0x2000
	s_add_u32 s22, s22, 0x80080
	v_lshl_add_u64 v[170:171], v[182:183], 0, s[10:11]
	s_addc_u32 s23, s23, 0
	s_add_i32 s24, s51, s26
	global_load_lds_dwordx4 v[170:171], off
	v_lshl_add_u64 v[170:171], s[22:23], 0, v[156:157]
	s_mov_b32 m0, s24
	s_nop 0
	global_load_lds_dwordx4 v[170:171], off
	v_lshl_add_u64 v[170:171], s[22:23], 0, v[152:153]
	s_add_i32 m0, s24, 0x2000
	s_nop 0
	global_load_lds_dwordx4 v[170:171], off
	v_lshl_add_u64 v[170:171], v[226:227], 0, s[10:11]
	s_mov_b32 m0, s37
	s_nop 0
	global_load_lds_dwordx4 v[170:171], off
	v_lshl_add_u64 v[170:171], v[228:229], 0, s[10:11]
	s_mov_b32 m0, s38
	s_nop 0
	global_load_lds_dwordx4 v[170:171], off
	s_waitcnt vmcnt(8)
	s_waitcnt lgkmcnt(0)
	s_barrier
	s_setprio 1
	s_waitcnt lgkmcnt(0)
	v_mfma_f32_16x16x32_bf16 v[60:63], v[128:131], v[194:197], v[60:63]
	v_mfma_f32_16x16x32_bf16 v[52:55], v[136:139], v[194:197], v[52:55]
	v_mfma_f32_16x16x32_bf16 v[44:47], v[128:131], v[202:205], v[44:47]
	v_mfma_f32_16x16x32_bf16 v[36:39], v[136:139], v[202:205], v[36:39]
	v_mfma_f32_16x16x32_bf16 v[28:31], v[128:131], v[210:213], v[28:31]
	v_mfma_f32_16x16x32_bf16 v[20:23], v[136:139], v[210:213], v[20:23]
	v_mfma_f32_16x16x32_bf16 v[12:15], v[128:131], v[218:221], v[12:15]
	v_mfma_f32_16x16x32_bf16 v[4:7], v[136:139], v[218:221], v[4:7]
	v_mfma_f32_16x16x32_bf16 v[60:63], v[132:135], v[198:201], v[60:63]
	v_mfma_f32_16x16x32_bf16 v[52:55], v[140:143], v[198:201], v[52:55]
	v_mfma_f32_16x16x32_bf16 v[44:47], v[132:135], v[206:209], v[44:47]
	v_mfma_f32_16x16x32_bf16 v[36:39], v[140:143], v[206:209], v[36:39]
	v_mfma_f32_16x16x32_bf16 v[28:31], v[132:135], v[214:217], v[28:31]
	v_mfma_f32_16x16x32_bf16 v[20:23], v[140:143], v[214:217], v[20:23]
	v_mfma_f32_16x16x32_bf16 v[12:15], v[132:135], v[222:225], v[12:15]
	v_mfma_f32_16x16x32_bf16 v[4:7], v[140:143], v[222:225], v[4:7]
	v_mfma_f32_16x16x32_bf16 v[56:59], v[144:147], v[194:197], v[56:59]
	v_mfma_f32_16x16x32_bf16 v[48:51], v[186:189], v[194:197], v[48:51]
	v_mfma_f32_16x16x32_bf16 v[40:43], v[144:147], v[202:205], v[40:43]
	v_mfma_f32_16x16x32_bf16 v[32:35], v[186:189], v[202:205], v[32:35]
	v_mfma_f32_16x16x32_bf16 v[24:27], v[144:147], v[210:213], v[24:27]
	v_mfma_f32_16x16x32_bf16 v[16:19], v[186:189], v[210:213], v[16:19]
	v_mfma_f32_16x16x32_bf16 v[8:11], v[144:147], v[218:221], v[8:11]
	v_mfma_f32_16x16x32_bf16 v[0:3], v[186:189], v[218:221], v[0:3]
	v_mfma_f32_16x16x32_bf16 v[56:59], v[148:151], v[198:201], v[56:59]
	v_mfma_f32_16x16x32_bf16 v[48:51], v[190:193], v[198:201], v[48:51]
	v_mfma_f32_16x16x32_bf16 v[40:43], v[148:151], v[206:209], v[40:43]
	v_mfma_f32_16x16x32_bf16 v[32:35], v[190:193], v[206:209], v[32:35]
	v_mfma_f32_16x16x32_bf16 v[24:27], v[148:151], v[214:217], v[24:27]
	v_mfma_f32_16x16x32_bf16 v[16:19], v[190:193], v[214:217], v[16:19]
	v_mfma_f32_16x16x32_bf16 v[8:11], v[148:151], v[222:225], v[8:11]
	v_mfma_f32_16x16x32_bf16 v[0:3], v[190:193], v[222:225], v[0:3]
	s_setprio 0
	s_barrier
	s_add_i32 s49, s49, 2
	s_add_u32 s6, s6, 0x100
	s_addc_u32 s7, s7, 0
	s_add_u32 s47, s47, 0x100
	s_addc_u32 s48, s48, 0
	s_cmp_gt_u32 s49, 29
	s_cbranch_scc0 .LBB0_1364
	s_and_b64 vcc, exec, s[12:13]
	s_cbranch_vccz .LBB0_1367
	s_barrier

.LBB0_1444:
	ds_read_b128 v[128:131], v159
	ds_read_b128 v[150:153], v159 offset:1024
	ds_read_b128 v[162:165], v159 offset:2048
	ds_read_b128 v[166:169], v159 offset:3072
	ds_read_b128 v[170:173], v160
	ds_read_b128 v[174:177], v160 offset:1024
	ds_read_b128 v[178:181], v160 offset:2048
	ds_read_b128 v[182:185], v160 offset:3072
	s_add_u32 s4, s18, 0x100
	s_addc_u32 s5, s19, 0
	s_cmpk_eq_i32 s45, 0x54
	s_cselect_b32 s23, s15, s5
	s_cselect_b32 s22, s14, s4
	s_cselect_b32 s21, s17, s44
	s_cselect_b32 s20, s16, s43
	v_lshl_add_u64 v[154:155], s[18:19], 0, v[142:143]
	s_add_i32 m0, s26, 0xc000
	ds_read_b128 v[186:189], v161
	ds_read_b128 v[190:193], v161 offset:1024
	ds_read_b128 v[194:197], v161 offset:2048
	ds_read_b128 v[198:201], v161 offset:3072
	ds_read_b128 v[202:205], v161 offset:4096
	ds_read_b128 v[206:209], v161 offset:5120
	ds_read_b128 v[210:213], v161 offset:6144
	ds_read_b128 v[214:217], v161 offset:7168
	global_load_lds_dwordx4 v[154:155], off
	v_lshl_add_u64 v[154:155], s[18:19], 0, v[144:145]
	s_add_i32 m0, s26, 0xe000
	s_nop 0
	global_load_lds_dwordx4 v[154:155], off
	s_waitcnt vmcnt(8)
	s_waitcnt lgkmcnt(0)
	s_barrier
	s_setprio 1
	s_waitcnt lgkmcnt(0)
	v_mfma_f32_16x16x32_bf16 v[124:127], v[128:131], v[186:189], v[124:127]
	v_mfma_f32_16x16x32_bf16 v[120:123], v[162:165], v[186:189], v[120:123]
	v_mfma_f32_16x16x32_bf16 v[116:119], v[128:131], v[194:197], v[116:119]
	v_mfma_f32_16x16x32_bf16 v[112:115], v[162:165], v[194:197], v[112:115]
	v_mfma_f32_16x16x32_bf16 v[88:91], v[128:131], v[202:205], v[88:91]
	v_mfma_f32_16x16x32_bf16 v[92:95], v[162:165], v[202:205], v[92:95]
	v_mfma_f32_16x16x32_bf16 v[72:75], v[128:131], v[210:213], v[72:75]
	v_mfma_f32_16x16x32_bf16 v[76:79], v[162:165], v[210:213], v[76:79]
	v_mfma_f32_16x16x32_bf16 v[124:127], v[150:153], v[190:193], v[124:127]
	v_mfma_f32_16x16x32_bf16 v[120:123], v[166:169], v[190:193], v[120:123]
	v_mfma_f32_16x16x32_bf16 v[116:119], v[150:153], v[198:201], v[116:119]
	v_mfma_f32_16x16x32_bf16 v[112:115], v[166:169], v[198:201], v[112:115]
	v_mfma_f32_16x16x32_bf16 v[88:91], v[150:153], v[206:209], v[88:91]
	v_mfma_f32_16x16x32_bf16 v[92:95], v[166:169], v[206:209], v[92:95]
	v_mfma_f32_16x16x32_bf16 v[72:75], v[150:153], v[214:217], v[72:75]
	v_mfma_f32_16x16x32_bf16 v[76:79], v[166:169], v[214:217], v[76:79]
	v_mfma_f32_16x16x32_bf16 v[108:111], v[170:173], v[186:189], v[108:111]
	v_mfma_f32_16x16x32_bf16 v[104:107], v[178:181], v[186:189], v[104:107]
	v_mfma_f32_16x16x32_bf16 v[96:99], v[170:173], v[194:197], v[96:99]
	v_mfma_f32_16x16x32_bf16 v[100:103], v[178:181], v[194:197], v[100:103]
	v_mfma_f32_16x16x32_bf16 v[80:83], v[170:173], v[202:205], v[80:83]
	v_mfma_f32_16x16x32_bf16 v[84:87], v[178:181], v[202:205], v[84:87]
	v_mfma_f32_16x16x32_bf16 v[64:67], v[170:173], v[210:213], v[64:67]
	v_mfma_f32_16x16x32_bf16 v[68:71], v[178:181], v[210:213], v[68:71]
	v_mfma_f32_16x16x32_bf16 v[108:111], v[174:177], v[190:193], v[108:111]
	v_mfma_f32_16x16x32_bf16 v[104:107], v[182:185], v[190:193], v[104:107]
	v_mfma_f32_16x16x32_bf16 v[96:99], v[174:177], v[198:201], v[96:99]
	v_mfma_f32_16x16x32_bf16 v[100:103], v[182:185], v[198:201], v[100:103]
	v_mfma_f32_16x16x32_bf16 v[80:83], v[174:177], v[206:209], v[80:83]
	v_mfma_f32_16x16x32_bf16 v[84:87], v[182:185], v[206:209], v[84:87]
	v_mfma_f32_16x16x32_bf16 v[64:67], v[174:177], v[214:217], v[64:67]
	v_mfma_f32_16x16x32_bf16 v[68:71], v[182:185], v[214:217], v[68:71]
	s_setprio 0
	s_barrier
	s_add_i32 s18, s37, s25
	v_lshl_add_u64 v[154:155], s[20:21], 0, v[134:135]
	s_mov_b32 m0, s18
	ds_read_b128 v[186:189], v161 offset:16384
	ds_read_b128 v[190:193], v161 offset:17408
	ds_read_b128 v[194:197], v161 offset:18432
	ds_read_b128 v[198:201], v161 offset:19456
	ds_read_b128 v[202:205], v161 offset:20480
	ds_read_b128 v[206:209], v161 offset:21504
	ds_read_b128 v[210:213], v161 offset:22528
	ds_read_b128 v[214:217], v161 offset:23552
	global_load_lds_dwordx4 v[154:155], off
	s_add_i32 m0, s18, 0x2000
	s_add_u32 s18, s20, 0x160000
	v_lshl_add_u64 v[218:219], s[20:21], 0, v[138:139]
	s_addc_u32 s19, s21, 0
	s_add_i32 s46, s38, s25
	global_load_lds_dwordx4 v[218:219], off
	v_lshl_add_u64 v[220:221], s[18:19], 0, v[134:135]
	s_mov_b32 m0, s46
	v_lshl_add_u64 v[222:223], s[22:23], 0, v[136:137]
	global_load_lds_dwordx4 v[220:221], off
	v_lshl_add_u64 v[220:221], s[18:19], 0, v[138:139]
	s_add_i32 m0, s46, 0x2000
	s_nop 0
	global_load_lds_dwordx4 v[220:221], off
	v_lshl_add_u64 v[220:221], s[22:23], 0, v[132:133]
	s_mov_b32 m0, s26
	s_nop 0
	global_load_lds_dwordx4 v[220:221], off
	s_mov_b32 m0, s27
	s_nop 0
	global_load_lds_dwordx4 v[222:223], off
	s_waitcnt vmcnt(8)
	s_waitcnt lgkmcnt(0)
	s_barrier
	s_setprio 1
	s_waitcnt lgkmcnt(0)
	v_mfma_f32_16x16x32_bf16 v[60:63], v[128:131], v[186:189], v[60:63]
	v_mfma_f32_16x16x32_bf16 v[56:59], v[162:165], v[186:189], v[56:59]
	v_mfma_f32_16x16x32_bf16 v[52:55], v[128:131], v[194:197], v[52:55]
	v_mfma_f32_16x16x32_bf16 v[48:51], v[162:165], v[194:197], v[48:51]
	v_mfma_f32_16x16x32_bf16 v[24:27], v[128:131], v[202:205], v[24:27]
	v_mfma_f32_16x16x32_bf16 v[28:31], v[162:165], v[202:205], v[28:31]
	v_mfma_f32_16x16x32_bf16 v[8:11], v[128:131], v[210:213], v[8:11]
	v_mfma_f32_16x16x32_bf16 v[12:15], v[162:165], v[210:213], v[12:15]
	v_mfma_f32_16x16x32_bf16 v[60:63], v[150:153], v[190:193], v[60:63]
	v_mfma_f32_16x16x32_bf16 v[56:59], v[166:169], v[190:193], v[56:59]
	v_mfma_f32_16x16x32_bf16 v[52:55], v[150:153], v[198:201], v[52:55]
	v_mfma_f32_16x16x32_bf16 v[48:51], v[166:169], v[198:201], v[48:51]
	v_mfma_f32_16x16x32_bf16 v[24:27], v[150:153], v[206:209], v[24:27]
	v_mfma_f32_16x16x32_bf16 v[28:31], v[166:169], v[206:209], v[28:31]
	v_mfma_f32_16x16x32_bf16 v[8:11], v[150:153], v[214:217], v[8:11]
	v_mfma_f32_16x16x32_bf16 v[12:15], v[166:169], v[214:217], v[12:15]
	v_mfma_f32_16x16x32_bf16 v[44:47], v[170:173], v[186:189], v[44:47]
	v_mfma_f32_16x16x32_bf16 v[40:43], v[178:181], v[186:189], v[40:43]
	v_mfma_f32_16x16x32_bf16 v[32:35], v[170:173], v[194:197], v[32:35]
	v_mfma_f32_16x16x32_bf16 v[36:39], v[178:181], v[194:197], v[36:39]
	v_mfma_f32_16x16x32_bf16 v[16:19], v[170:173], v[202:205], v[16:19]
	v_mfma_f32_16x16x32_bf16 v[20:23], v[178:181], v[202:205], v[20:23]
	v_mfma_f32_16x16x32_bf16 v[0:3], v[170:173], v[210:213], v[0:3]
	v_mfma_f32_16x16x32_bf16 v[4:7], v[178:181], v[210:213], v[4:7]
	v_mfma_f32_16x16x32_bf16 v[44:47], v[174:177], v[190:193], v[44:47]
	v_mfma_f32_16x16x32_bf16 v[40:43], v[182:185], v[190:193], v[40:43]
	v_mfma_f32_16x16x32_bf16 v[32:35], v[174:177], v[198:201], v[32:35]
	v_mfma_f32_16x16x32_bf16 v[36:39], v[182:185], v[198:201], v[36:39]
	v_mfma_f32_16x16x32_bf16 v[16:19], v[174:177], v[206:209], v[16:19]
	v_mfma_f32_16x16x32_bf16 v[20:23], v[182:185], v[206:209], v[20:23]
	v_mfma_f32_16x16x32_bf16 v[0:3], v[174:177], v[214:217], v[0:3]
	v_mfma_f32_16x16x32_bf16 v[4:7], v[182:185], v[214:217], v[4:7]
	s_setprio 0
	s_barrier
	s_add_i32 s46, 0, 0x18000
	v_add_u32_e32 v140, s46, v158
	s_add_i32 s47, 0, 0x1c000
	ds_read_b128 v[128:131], v140
	ds_read_b128 v[150:153], v140 offset:1024
	ds_read_b128 v[162:165], v140 offset:2048
	ds_read_b128 v[166:169], v140 offset:3072
	v_add_u32_e32 v140, s47, v158
	ds_read_b128 v[170:173], v140
	ds_read_b128 v[174:177], v140 offset:1024
	ds_read_b128 v[178:181], v140 offset:2048
	ds_read_b128 v[182:185], v140 offset:3072
	s_add_u32 s18, s22, 0x160000
	s_addc_u32 s19, s23, 0
	s_mov_b32 m0, s28
	v_lshl_add_u64 v[224:225], s[18:19], 0, v[132:133]
	ds_read_b128 v[186:189], v161 offset:32768
	ds_read_b128 v[190:193], v161 offset:33792
	ds_read_b128 v[194:197], v161 offset:34816
	ds_read_b128 v[198:201], v161 offset:35840
	ds_read_b128 v[202:205], v161 offset:36864
	ds_read_b128 v[206:209], v161 offset:37888
	ds_read_b128 v[210:213], v161 offset:38912
	ds_read_b128 v[214:217], v161 offset:39936
	global_load_lds_dwordx4 v[224:225], off
	v_lshl_add_u64 v[224:225], s[18:19], 0, v[136:137]
	s_mov_b32 m0, s29
	s_nop 0
	global_load_lds_dwordx4 v[224:225], off
	s_waitcnt vmcnt(8)
	s_waitcnt lgkmcnt(0)
	s_barrier
	s_setprio 1
	s_waitcnt lgkmcnt(0)
	v_mfma_f32_16x16x32_bf16 v[124:127], v[128:131], v[186:189], v[124:127]
	v_mfma_f32_16x16x32_bf16 v[120:123], v[162:165], v[186:189], v[120:123]
	v_mfma_f32_16x16x32_bf16 v[116:119], v[128:131], v[194:197], v[116:119]
	v_mfma_f32_16x16x32_bf16 v[112:115], v[162:165], v[194:197], v[112:115]
	v_mfma_f32_16x16x32_bf16 v[88:91], v[128:131], v[202:205], v[88:91]
	v_mfma_f32_16x16x32_bf16 v[92:95], v[162:165], v[202:205], v[92:95]
	v_mfma_f32_16x16x32_bf16 v[72:75], v[128:131], v[210:213], v[72:75]
	v_mfma_f32_16x16x32_bf16 v[76:79], v[162:165], v[210:213], v[76:79]
	v_mfma_f32_16x16x32_bf16 v[124:127], v[150:153], v[190:193], v[124:127]
	v_mfma_f32_16x16x32_bf16 v[120:123], v[166:169], v[190:193], v[120:123]
	v_mfma_f32_16x16x32_bf16 v[116:119], v[150:153], v[198:201], v[116:119]
	v_mfma_f32_16x16x32_bf16 v[112:115], v[166:169], v[198:201], v[112:115]
	v_mfma_f32_16x16x32_bf16 v[88:91], v[150:153], v[206:209], v[88:91]
	v_mfma_f32_16x16x32_bf16 v[92:95], v[166:169], v[206:209], v[92:95]
	v_mfma_f32_16x16x32_bf16 v[72:75], v[150:153], v[214:217], v[72:75]
	v_mfma_f32_16x16x32_bf16 v[76:79], v[166:169], v[214:217], v[76:79]
	v_mfma_f32_16x16x32_bf16 v[108:111], v[170:173], v[186:189], v[108:111]
	v_mfma_f32_16x16x32_bf16 v[104:107], v[178:181], v[186:189], v[104:107]
	v_mfma_f32_16x16x32_bf16 v[96:99], v[170:173], v[194:197], v[96:99]
	v_mfma_f32_16x16x32_bf16 v[100:103], v[178:181], v[194:197], v[100:103]
	v_mfma_f32_16x16x32_bf16 v[80:83], v[170:173], v[202:205], v[80:83]
	v_mfma_f32_16x16x32_bf16 v[84:87], v[178:181], v[202:205], v[84:87]
	v_mfma_f32_16x16x32_bf16 v[64:67], v[170:173], v[210:213], v[64:67]
	v_mfma_f32_16x16x32_bf16 v[68:71], v[178:181], v[210:213], v[68:71]
	v_mfma_f32_16x16x32_bf16 v[108:111], v[174:177], v[190:193], v[108:111]
	v_mfma_f32_16x16x32_bf16 v[104:107], v[182:185], v[190:193], v[104:107]
	v_mfma_f32_16x16x32_bf16 v[96:99], v[174:177], v[198:201], v[96:99]
	v_mfma_f32_16x16x32_bf16 v[100:103], v[182:185], v[198:201], v[100:103]
	v_mfma_f32_16x16x32_bf16 v[80:83], v[174:177], v[206:209], v[80:83]
	v_mfma_f32_16x16x32_bf16 v[84:87], v[182:185], v[206:209], v[84:87]
	v_mfma_f32_16x16x32_bf16 v[64:67], v[174:177], v[214:217], v[64:67]
	v_mfma_f32_16x16x32_bf16 v[68:71], v[182:185], v[214:217], v[68:71]
	s_setprio 0
	s_barrier
	s_add_i32 s18, s46, s25
	v_lshl_add_u64 v[154:155], v[154:155], 0, s[8:9]
	s_mov_b32 m0, s18
	ds_read_b128 v[186:189], v161 offset:49152
	ds_read_b128 v[190:193], v161 offset:50176
	ds_read_b128 v[194:197], v161 offset:51200
	ds_read_b128 v[198:201], v161 offset:52224
	ds_read_b128 v[202:205], v161 offset:53248
	ds_read_b128 v[206:209], v161 offset:54272
	ds_read_b128 v[210:213], v161 offset:55296
	ds_read_b128 v[214:217], v161 offset:56320
	global_load_lds_dwordx4 v[154:155], off
	s_add_i32 m0, s18, 0x2000
	s_add_u32 s18, s20, 0x160080
	v_lshl_add_u64 v[154:155], v[218:219], 0, s[8:9]
	s_addc_u32 s19, s21, 0
	s_add_i32 s20, s47, s25
	global_load_lds_dwordx4 v[154:155], off
	v_lshl_add_u64 v[154:155], s[18:19], 0, v[134:135]
	s_mov_b32 m0, s20
	s_nop 0
	global_load_lds_dwordx4 v[154:155], off
	v_lshl_add_u64 v[154:155], s[18:19], 0, v[138:139]
	s_add_i32 m0, s20, 0x2000
	s_nop 0
	global_load_lds_dwordx4 v[154:155], off
	v_lshl_add_u64 v[154:155], v[220:221], 0, s[8:9]
	s_mov_b32 m0, s34
	s_nop 0
	global_load_lds_dwordx4 v[154:155], off
	v_lshl_add_u64 v[154:155], v[222:223], 0, s[8:9]
	s_mov_b32 m0, s35
	s_nop 0
	global_load_lds_dwordx4 v[154:155], off
	s_waitcnt vmcnt(8)
	s_waitcnt lgkmcnt(0)
	s_barrier
	s_setprio 1
	s_waitcnt lgkmcnt(0)
	v_mfma_f32_16x16x32_bf16 v[60:63], v[128:131], v[186:189], v[60:63]
	v_mfma_f32_16x16x32_bf16 v[56:59], v[162:165], v[186:189], v[56:59]
	v_mfma_f32_16x16x32_bf16 v[52:55], v[128:131], v[194:197], v[52:55]
	v_mfma_f32_16x16x32_bf16 v[48:51], v[162:165], v[194:197], v[48:51]
	v_mfma_f32_16x16x32_bf16 v[24:27], v[128:131], v[202:205], v[24:27]
	v_mfma_f32_16x16x32_bf16 v[28:31], v[162:165], v[202:205], v[28:31]
	v_mfma_f32_16x16x32_bf16 v[8:11], v[128:131], v[210:213], v[8:11]
	v_mfma_f32_16x16x32_bf16 v[12:15], v[162:165], v[210:213], v[12:15]
	v_mfma_f32_16x16x32_bf16 v[60:63], v[150:153], v[190:193], v[60:63]
	v_mfma_f32_16x16x32_bf16 v[56:59], v[166:169], v[190:193], v[56:59]
	v_mfma_f32_16x16x32_bf16 v[52:55], v[150:153], v[198:201], v[52:55]
	v_mfma_f32_16x16x32_bf16 v[48:51], v[166:169], v[198:201], v[48:51]
	v_mfma_f32_16x16x32_bf16 v[24:27], v[150:153], v[206:209], v[24:27]
	v_mfma_f32_16x16x32_bf16 v[28:31], v[166:169], v[206:209], v[28:31]
	v_mfma_f32_16x16x32_bf16 v[8:11], v[150:153], v[214:217], v[8:11]
	v_mfma_f32_16x16x32_bf16 v[12:15], v[166:169], v[214:217], v[12:15]
	v_mfma_f32_16x16x32_bf16 v[44:47], v[170:173], v[186:189], v[44:47]
	v_mfma_f32_16x16x32_bf16 v[40:43], v[178:181], v[186:189], v[40:43]
	v_mfma_f32_16x16x32_bf16 v[32:35], v[170:173], v[194:197], v[32:35]
	v_mfma_f32_16x16x32_bf16 v[36:39], v[178:181], v[194:197], v[36:39]
	v_mfma_f32_16x16x32_bf16 v[16:19], v[170:173], v[202:205], v[16:19]
	v_mfma_f32_16x16x32_bf16 v[20:23], v[178:181], v[202:205], v[20:23]
	v_mfma_f32_16x16x32_bf16 v[0:3], v[170:173], v[210:213], v[0:3]
	v_mfma_f32_16x16x32_bf16 v[4:7], v[178:181], v[210:213], v[4:7]
	v_mfma_f32_16x16x32_bf16 v[44:47], v[174:177], v[190:193], v[44:47]
	v_mfma_f32_16x16x32_bf16 v[40:43], v[182:185], v[190:193], v[40:43]
	v_mfma_f32_16x16x32_bf16 v[32:35], v[174:177], v[198:201], v[32:35]
	v_mfma_f32_16x16x32_bf16 v[36:39], v[182:185], v[198:201], v[36:39]
	v_mfma_f32_16x16x32_bf16 v[16:19], v[174:177], v[206:209], v[16:19]
	v_mfma_f32_16x16x32_bf16 v[20:23], v[182:185], v[206:209], v[20:23]
	v_mfma_f32_16x16x32_bf16 v[0:3], v[174:177], v[214:217], v[0:3]
	v_mfma_f32_16x16x32_bf16 v[4:7], v[182:185], v[214:217], v[4:7]
	s_setprio 0
	s_barrier
	s_add_i32 s45, s45, 2
	s_add_u32 s43, s43, 0x100
	s_addc_u32 s44, s44, 0
	s_cmpk_gt_u32 s45, 0x55
	s_mov_b64 s[18:19], s[4:5]
	s_cbranch_scc0 .LBB0_1444
	s_and_b64 vcc, exec, s[10:11]
	s_cbranch_vccz .LBB0_1447
	s_barrier
